# all big-GEMM bf16/f16 epilogue row-store pairs widened to dwordx4 via v_permlane16_swap (RW, NAT q/k, LRU, GATE)
# baseline (speedup 1.0000x reference)
.LBB0_90:
	v_mbcnt_lo_u32_b32 v200, -1, 0
	v_mbcnt_hi_u32_b32 v200, -1, v200
	v_and_b32_e32 v200, 16, v200
	v_lshrrev_b32_e32 v201, 1, v200
	v_add_u32_e32 v200, v200, v201
	v_mov_b32_e32 v201, 0
	v_mov_b32_e32 v136, s88
	ds_read_b32 v136, v136
	v_readlane_b32 s2, v254, 44
	v_mov_b32_e32 v151, v153
	s_mov_b64 s[58:59], -1
	s_mov_b64 s[56:57], 0
	s_waitcnt lgkmcnt(0)
	v_readfirstlane_b32 s48, v136
	v_mov_b32_e32 v136, s89
	ds_read_b32 v136, v136
	s_add_u32 s52, s48, 0x2100000
	s_waitcnt lgkmcnt(0)
	v_readfirstlane_b32 s49, v136
	v_mov_b32_e32 v136, s2
	ds_read_b32 v136, v136
	v_readlane_b32 s2, v254, 45
	s_addc_u32 s53, s49, 0
	s_add_u32 s46, s48, 0x158d0000
	s_addc_u32 s47, s49, 0
	s_waitcnt lgkmcnt(0)
	v_readfirstlane_b32 s42, v136
	v_mov_b32_e32 v136, s2
	ds_read_b32 v136, v136
	v_readlane_b32 s2, v254, 31
	s_add_u32 s40, s48, 0xc600000
	s_addc_u32 s41, s49, 0
	s_add_u32 s36, s48, 0xe700000
	s_waitcnt lgkmcnt(0)
	v_readfirstlane_b32 s43, v136
	v_mov_b32_e32 v136, s2
	ds_read_b32 v136, v136
	v_readlane_b32 s2, v254, 46
	s_addc_u32 s37, s49, 0
	s_add_u32 s34, s48, 0x6300000
	s_addc_u32 s35, s49, 0
	s_waitcnt lgkmcnt(0)
	v_readfirstlane_b32 s65, v136
	v_mov_b32_e32 v136, s2
	ds_read_b32 v136, v136
	v_readlane_b32 s2, v254, 39
	s_add_u32 s38, s48, 0x4200000
	s_addc_u32 s39, s49, 0
	s_add_u32 s50, s48, 0x15af4000
	s_waitcnt lgkmcnt(0)
	v_readfirstlane_b32 s66, v136
	v_mov_b32_e32 v136, s2
	ds_read_b32 v136, v136
	v_readlane_b32 s2, v254, 48
	s_addc_u32 s51, s49, 0
	s_lshl_b32 s62, s10, 8
	s_lshl_b32 s27, s67, 8
	s_waitcnt lgkmcnt(0)
	v_readfirstlane_b32 s44, v136
	v_mov_b32_e32 v136, s2
	v_readlane_b32 s2, v254, 40
	s_add_i32 s62, s62, s2
	s_ashr_i32 s2, s62, 13
	ds_read_b32 v136, v136
	s_mul_i32 s54, s2, 0x1800
	v_readlane_b32 s2, v254, 26
	s_ashr_i32 s55, s54, 31
	s_mul_i32 s2, s2, 0x12000
	s_add_u32 s2, s48, s2
	v_or_b32_e32 v138, s62, v157
	s_addc_u32 s3, s49, 0
	v_ashrrev_i32_e32 v139, 31, v138
	s_add_u32 s30, s2, 0x15ad0000
	s_waitcnt lgkmcnt(0)
	v_readfirstlane_b32 s45, v136
	v_lshlrev_b64 v[136:137], 13, v[138:139]
	v_add_u32_e32 v150, 0xffffc000, v138
	s_addc_u32 s31, s3, 0
	v_lshl_add_u64 v[148:149], s[52:53], 0, v[136:137]
	v_cmp_gt_i32_e64 s[10:11], s92, v138
	v_cmp_lt_i32_e64 s[8:9], s80, v138
	v_lshlrev_b64 v[146:147], 10, v[150:151]
	v_lshlrev_b64 v[142:143], 10, v[138:139]
	v_or_b32_e32 v136, s27, v161
	s_cmp_lg_u32 s79, 26
	s_cbranch_scc1 .Lff1_no
	v_ashrrev_i32_e32 v137, 31, v136
	v_lshl_add_u64 v[244:245], v[136:137], 1, v[148:149]
	v_mbcnt_lo_u32_b32 v246, -1, 0
	v_mbcnt_hi_u32_b32 v246, -1, v246
	v_and_b32_e32 v246, 16, v246
	v_lshrrev_b32_e32 v247, 1, v246
	v_add_u32_e32 v246, v246, v247
	v_mov_b32_e32 v247, 0
	v_lshl_add_u64 v[244:245], v[246:247], 0, v[244:245]
	v_max_f32_e32 v124, v124, v124
	v_max_f32_e32 v124, 0, v124
	v_mul_f32_e32 v124, v124, v124
	v_max_f32_e32 v125, v125, v125
	v_max_f32_e32 v125, 0, v125
	v_mul_f32_e32 v125, v125, v125
	v_max_f32_e32 v126, v126, v126
	v_max_f32_e32 v126, 0, v126
	v_mul_f32_e32 v126, v126, v126
	v_max_f32_e32 v127, v127, v127
	v_max_f32_e32 v127, 0, v127
	v_mul_f32_e32 v127, v127, v127
	v_max_f32_e32 v120, v120, v120
	v_max_f32_e32 v120, 0, v120
	v_mul_f32_e32 v120, v120, v120
	v_max_f32_e32 v121, v121, v121
	v_max_f32_e32 v121, 0, v121
	v_mul_f32_e32 v121, v121, v121
	v_max_f32_e32 v122, v122, v122
	v_max_f32_e32 v122, 0, v122
	v_mul_f32_e32 v122, v122, v122
	v_max_f32_e32 v123, v123, v123
	v_max_f32_e32 v123, 0, v123
	v_mul_f32_e32 v123, v123, v123
	v_cvt_pk_bf16_f32 v230, v124, v125
	v_cvt_pk_bf16_f32 v231, v126, v127
	v_cvt_pk_bf16_f32 v232, v120, v121
	v_cvt_pk_bf16_f32 v233, v122, v123
	s_nop 1
	v_permlane16_swap_b32 v230, v232
	v_permlane16_swap_b32 v231, v233
	global_store_dwordx4 v[244:245], v[230:233], off
	v_max_f32_e32 v116, v116, v116
	v_max_f32_e32 v116, 0, v116
	v_mul_f32_e32 v116, v116, v116
	v_max_f32_e32 v117, v117, v117
	v_max_f32_e32 v117, 0, v117
	v_mul_f32_e32 v117, v117, v117
	v_max_f32_e32 v118, v118, v118
	v_max_f32_e32 v118, 0, v118
	v_mul_f32_e32 v118, v118, v118
	v_max_f32_e32 v119, v119, v119
	v_max_f32_e32 v119, 0, v119
	v_mul_f32_e32 v119, v119, v119
	v_max_f32_e32 v112, v112, v112
	v_max_f32_e32 v112, 0, v112
	v_mul_f32_e32 v112, v112, v112
	v_max_f32_e32 v113, v113, v113
	v_max_f32_e32 v113, 0, v113
	v_mul_f32_e32 v113, v113, v113
	v_max_f32_e32 v114, v114, v114
	v_max_f32_e32 v114, 0, v114
	v_mul_f32_e32 v114, v114, v114
	v_max_f32_e32 v115, v115, v115
	v_max_f32_e32 v115, 0, v115
	v_mul_f32_e32 v115, v115, v115
	v_cvt_pk_bf16_f32 v234, v116, v117
	v_cvt_pk_bf16_f32 v235, v118, v119
	v_cvt_pk_bf16_f32 v236, v112, v113
	v_cvt_pk_bf16_f32 v237, v114, v115
	v_add_co_u32_e32 v246, vcc, 0x100, v244
	v_addc_co_u32_e32 v247, vcc, 0, v245, vcc
	v_permlane16_swap_b32 v234, v236
	v_permlane16_swap_b32 v235, v237
	global_store_dwordx4 v[246:247], v[234:237], off
	v_max_f32_e32 v108, v108, v108
	v_max_f32_e32 v108, 0, v108
	v_mul_f32_e32 v108, v108, v108
	v_max_f32_e32 v109, v109, v109
	v_max_f32_e32 v109, 0, v109
	v_mul_f32_e32 v109, v109, v109
	v_max_f32_e32 v110, v110, v110
	v_max_f32_e32 v110, 0, v110
	v_mul_f32_e32 v110, v110, v110
	v_max_f32_e32 v111, v111, v111
	v_max_f32_e32 v111, 0, v111
	v_mul_f32_e32 v111, v111, v111
	v_max_f32_e32 v104, v104, v104
	v_max_f32_e32 v104, 0, v104
	v_mul_f32_e32 v104, v104, v104
	v_max_f32_e32 v105, v105, v105
	v_max_f32_e32 v105, 0, v105
	v_mul_f32_e32 v105, v105, v105
	v_max_f32_e32 v106, v106, v106
	v_max_f32_e32 v106, 0, v106
	v_mul_f32_e32 v106, v106, v106
	v_max_f32_e32 v107, v107, v107
	v_max_f32_e32 v107, 0, v107
	v_mul_f32_e32 v107, v107, v107
	v_cvt_pk_bf16_f32 v230, v108, v109
	v_cvt_pk_bf16_f32 v231, v110, v111
	v_cvt_pk_bf16_f32 v232, v104, v105
	v_cvt_pk_bf16_f32 v233, v106, v107
	v_add_co_u32_e32 v246, vcc, 0x20000, v244
	v_addc_co_u32_e32 v247, vcc, 0, v245, vcc
	v_permlane16_swap_b32 v230, v232
	v_permlane16_swap_b32 v231, v233
	global_store_dwordx4 v[246:247], v[230:233], off
	v_max_f32_e32 v100, v100, v100
	v_max_f32_e32 v100, 0, v100
	v_mul_f32_e32 v100, v100, v100
	v_max_f32_e32 v101, v101, v101
	v_max_f32_e32 v101, 0, v101
	v_mul_f32_e32 v101, v101, v101
	v_max_f32_e32 v102, v102, v102
	v_max_f32_e32 v102, 0, v102
	v_mul_f32_e32 v102, v102, v102
	v_max_f32_e32 v103, v103, v103
	v_max_f32_e32 v103, 0, v103
	v_mul_f32_e32 v103, v103, v103
	v_max_f32_e32 v96, v96, v96
	v_max_f32_e32 v96, 0, v96
	v_mul_f32_e32 v96, v96, v96
	v_max_f32_e32 v97, v97, v97
	v_max_f32_e32 v97, 0, v97
	v_mul_f32_e32 v97, v97, v97
	v_max_f32_e32 v98, v98, v98
	v_max_f32_e32 v98, 0, v98
	v_mul_f32_e32 v98, v98, v98
	v_max_f32_e32 v99, v99, v99
	v_max_f32_e32 v99, 0, v99
	v_mul_f32_e32 v99, v99, v99
	v_cvt_pk_bf16_f32 v234, v100, v101
	v_cvt_pk_bf16_f32 v235, v102, v103
	v_cvt_pk_bf16_f32 v236, v96, v97
	v_cvt_pk_bf16_f32 v237, v98, v99
	v_add_co_u32_e32 v246, vcc, 0x20100, v244
	v_addc_co_u32_e32 v247, vcc, 0, v245, vcc
	v_permlane16_swap_b32 v234, v236
	v_permlane16_swap_b32 v235, v237
	global_store_dwordx4 v[246:247], v[234:237], off
	v_max_f32_e32 v92, v92, v92
	v_max_f32_e32 v92, 0, v92
	v_mul_f32_e32 v92, v92, v92
	v_max_f32_e32 v93, v93, v93
	v_max_f32_e32 v93, 0, v93
	v_mul_f32_e32 v93, v93, v93
	v_max_f32_e32 v94, v94, v94
	v_max_f32_e32 v94, 0, v94
	v_mul_f32_e32 v94, v94, v94
	v_max_f32_e32 v95, v95, v95
	v_max_f32_e32 v95, 0, v95
	v_mul_f32_e32 v95, v95, v95
	v_max_f32_e32 v88, v88, v88
	v_max_f32_e32 v88, 0, v88
	v_mul_f32_e32 v88, v88, v88
	v_max_f32_e32 v89, v89, v89
	v_max_f32_e32 v89, 0, v89
	v_mul_f32_e32 v89, v89, v89
	v_max_f32_e32 v90, v90, v90
	v_max_f32_e32 v90, 0, v90
	v_mul_f32_e32 v90, v90, v90
	v_max_f32_e32 v91, v91, v91
	v_max_f32_e32 v91, 0, v91
	v_mul_f32_e32 v91, v91, v91
	v_cvt_pk_bf16_f32 v230, v92, v93
	v_cvt_pk_bf16_f32 v231, v94, v95
	v_cvt_pk_bf16_f32 v232, v88, v89
	v_cvt_pk_bf16_f32 v233, v90, v91
	v_add_co_u32_e32 v246, vcc, 0x40000, v244
	v_addc_co_u32_e32 v247, vcc, 0, v245, vcc
	v_permlane16_swap_b32 v230, v232
	v_permlane16_swap_b32 v231, v233
	global_store_dwordx4 v[246:247], v[230:233], off
	v_max_f32_e32 v84, v84, v84
	v_max_f32_e32 v84, 0, v84
	v_mul_f32_e32 v84, v84, v84
	v_max_f32_e32 v85, v85, v85
	v_max_f32_e32 v85, 0, v85
	v_mul_f32_e32 v85, v85, v85
	v_max_f32_e32 v86, v86, v86
	v_max_f32_e32 v86, 0, v86
	v_mul_f32_e32 v86, v86, v86
	v_max_f32_e32 v87, v87, v87
	v_max_f32_e32 v87, 0, v87
	v_mul_f32_e32 v87, v87, v87
	v_max_f32_e32 v80, v80, v80
	v_max_f32_e32 v80, 0, v80
	v_mul_f32_e32 v80, v80, v80
	v_max_f32_e32 v81, v81, v81
	v_max_f32_e32 v81, 0, v81
	v_mul_f32_e32 v81, v81, v81
	v_max_f32_e32 v82, v82, v82
	v_max_f32_e32 v82, 0, v82
	v_mul_f32_e32 v82, v82, v82
	v_max_f32_e32 v83, v83, v83
	v_max_f32_e32 v83, 0, v83
	v_mul_f32_e32 v83, v83, v83
	v_cvt_pk_bf16_f32 v234, v84, v85
	v_cvt_pk_bf16_f32 v235, v86, v87
	v_cvt_pk_bf16_f32 v236, v80, v81
	v_cvt_pk_bf16_f32 v237, v82, v83
	v_add_co_u32_e32 v246, vcc, 0x40100, v244
	v_addc_co_u32_e32 v247, vcc, 0, v245, vcc
	v_permlane16_swap_b32 v234, v236
	v_permlane16_swap_b32 v235, v237
	global_store_dwordx4 v[246:247], v[234:237], off
	v_max_f32_e32 v76, v76, v76
	v_max_f32_e32 v76, 0, v76
	v_mul_f32_e32 v76, v76, v76
	v_max_f32_e32 v77, v77, v77
	v_max_f32_e32 v77, 0, v77
	v_mul_f32_e32 v77, v77, v77
	v_max_f32_e32 v78, v78, v78
	v_max_f32_e32 v78, 0, v78
	v_mul_f32_e32 v78, v78, v78
	v_max_f32_e32 v79, v79, v79
	v_max_f32_e32 v79, 0, v79
	v_mul_f32_e32 v79, v79, v79
	v_max_f32_e32 v72, v72, v72
	v_max_f32_e32 v72, 0, v72
	v_mul_f32_e32 v72, v72, v72
	v_max_f32_e32 v73, v73, v73
	v_max_f32_e32 v73, 0, v73
	v_mul_f32_e32 v73, v73, v73
	v_max_f32_e32 v74, v74, v74
	v_max_f32_e32 v74, 0, v74
	v_mul_f32_e32 v74, v74, v74
	v_max_f32_e32 v75, v75, v75
	v_max_f32_e32 v75, 0, v75
	v_mul_f32_e32 v75, v75, v75
	v_cvt_pk_bf16_f32 v230, v76, v77
	v_cvt_pk_bf16_f32 v231, v78, v79
	v_cvt_pk_bf16_f32 v232, v72, v73
	v_cvt_pk_bf16_f32 v233, v74, v75
	v_add_co_u32_e32 v246, vcc, 0x60000, v244
	v_addc_co_u32_e32 v247, vcc, 0, v245, vcc
	v_permlane16_swap_b32 v230, v232
	v_permlane16_swap_b32 v231, v233
	global_store_dwordx4 v[246:247], v[230:233], off
	v_max_f32_e32 v68, v68, v68
	v_max_f32_e32 v68, 0, v68
	v_mul_f32_e32 v68, v68, v68
	v_max_f32_e32 v69, v69, v69
	v_max_f32_e32 v69, 0, v69
	v_mul_f32_e32 v69, v69, v69
	v_max_f32_e32 v70, v70, v70
	v_max_f32_e32 v70, 0, v70
	v_mul_f32_e32 v70, v70, v70
	v_max_f32_e32 v71, v71, v71
	v_max_f32_e32 v71, 0, v71
	v_mul_f32_e32 v71, v71, v71
	v_max_f32_e32 v64, v64, v64
	v_max_f32_e32 v64, 0, v64
	v_mul_f32_e32 v64, v64, v64
	v_max_f32_e32 v65, v65, v65
	v_max_f32_e32 v65, 0, v65
	v_mul_f32_e32 v65, v65, v65
	v_max_f32_e32 v66, v66, v66
	v_max_f32_e32 v66, 0, v66
	v_mul_f32_e32 v66, v66, v66
	v_max_f32_e32 v67, v67, v67
	v_max_f32_e32 v67, 0, v67
	v_mul_f32_e32 v67, v67, v67
	v_cvt_pk_bf16_f32 v234, v68, v69
	v_cvt_pk_bf16_f32 v235, v70, v71
	v_cvt_pk_bf16_f32 v236, v64, v65
	v_cvt_pk_bf16_f32 v237, v66, v67
	v_add_co_u32_e32 v246, vcc, 0x60100, v244
	v_addc_co_u32_e32 v247, vcc, 0, v245, vcc
	v_permlane16_swap_b32 v234, v236
	v_permlane16_swap_b32 v235, v237
	global_store_dwordx4 v[246:247], v[234:237], off
	v_max_f32_e32 v60, v60, v60
	v_max_f32_e32 v60, 0, v60
	v_mul_f32_e32 v60, v60, v60
	v_max_f32_e32 v61, v61, v61
	v_max_f32_e32 v61, 0, v61
	v_mul_f32_e32 v61, v61, v61
	v_max_f32_e32 v62, v62, v62
	v_max_f32_e32 v62, 0, v62
	v_mul_f32_e32 v62, v62, v62
	v_max_f32_e32 v63, v63, v63
	v_max_f32_e32 v63, 0, v63
	v_mul_f32_e32 v63, v63, v63
	v_max_f32_e32 v56, v56, v56
	v_max_f32_e32 v56, 0, v56
	v_mul_f32_e32 v56, v56, v56
	v_max_f32_e32 v57, v57, v57
	v_max_f32_e32 v57, 0, v57
	v_mul_f32_e32 v57, v57, v57
	v_max_f32_e32 v58, v58, v58
	v_max_f32_e32 v58, 0, v58
	v_mul_f32_e32 v58, v58, v58
	v_max_f32_e32 v59, v59, v59
	v_max_f32_e32 v59, 0, v59
	v_mul_f32_e32 v59, v59, v59
	v_cvt_pk_bf16_f32 v230, v60, v61
	v_cvt_pk_bf16_f32 v231, v62, v63
	v_cvt_pk_bf16_f32 v232, v56, v57
	v_cvt_pk_bf16_f32 v233, v58, v59
	v_add_co_u32_e32 v246, vcc, 0x100000, v244
	v_addc_co_u32_e32 v247, vcc, 0, v245, vcc
	v_permlane16_swap_b32 v230, v232
	v_permlane16_swap_b32 v231, v233
	global_store_dwordx4 v[246:247], v[230:233], off
	v_max_f32_e32 v52, v52, v52
	v_max_f32_e32 v52, 0, v52
	v_mul_f32_e32 v52, v52, v52
	v_max_f32_e32 v53, v53, v53
	v_max_f32_e32 v53, 0, v53
	v_mul_f32_e32 v53, v53, v53
	v_max_f32_e32 v54, v54, v54
	v_max_f32_e32 v54, 0, v54
	v_mul_f32_e32 v54, v54, v54
	v_max_f32_e32 v55, v55, v55
	v_max_f32_e32 v55, 0, v55
	v_mul_f32_e32 v55, v55, v55
	v_max_f32_e32 v48, v48, v48
	v_max_f32_e32 v48, 0, v48
	v_mul_f32_e32 v48, v48, v48
	v_max_f32_e32 v49, v49, v49
	v_max_f32_e32 v49, 0, v49
	v_mul_f32_e32 v49, v49, v49
	v_max_f32_e32 v50, v50, v50
	v_max_f32_e32 v50, 0, v50
	v_mul_f32_e32 v50, v50, v50
	v_max_f32_e32 v51, v51, v51
	v_max_f32_e32 v51, 0, v51
	v_mul_f32_e32 v51, v51, v51
	v_cvt_pk_bf16_f32 v234, v52, v53
	v_cvt_pk_bf16_f32 v235, v54, v55
	v_cvt_pk_bf16_f32 v236, v48, v49
	v_cvt_pk_bf16_f32 v237, v50, v51
	v_add_co_u32_e32 v246, vcc, 0x100100, v244
	v_addc_co_u32_e32 v247, vcc, 0, v245, vcc
	v_permlane16_swap_b32 v234, v236
	v_permlane16_swap_b32 v235, v237
	global_store_dwordx4 v[246:247], v[234:237], off
	v_max_f32_e32 v44, v44, v44
	v_max_f32_e32 v44, 0, v44
	v_mul_f32_e32 v44, v44, v44
	v_max_f32_e32 v45, v45, v45
	v_max_f32_e32 v45, 0, v45
	v_mul_f32_e32 v45, v45, v45
	v_max_f32_e32 v46, v46, v46
	v_max_f32_e32 v46, 0, v46
	v_mul_f32_e32 v46, v46, v46
	v_max_f32_e32 v47, v47, v47
	v_max_f32_e32 v47, 0, v47
	v_mul_f32_e32 v47, v47, v47
	v_max_f32_e32 v40, v40, v40
	v_max_f32_e32 v40, 0, v40
	v_mul_f32_e32 v40, v40, v40
	v_max_f32_e32 v41, v41, v41
	v_max_f32_e32 v41, 0, v41
	v_mul_f32_e32 v41, v41, v41
	v_max_f32_e32 v42, v42, v42
	v_max_f32_e32 v42, 0, v42
	v_mul_f32_e32 v42, v42, v42
	v_max_f32_e32 v43, v43, v43
	v_max_f32_e32 v43, 0, v43
	v_mul_f32_e32 v43, v43, v43
	v_cvt_pk_bf16_f32 v230, v44, v45
	v_cvt_pk_bf16_f32 v231, v46, v47
	v_cvt_pk_bf16_f32 v232, v40, v41
	v_cvt_pk_bf16_f32 v233, v42, v43
	v_add_co_u32_e32 v246, vcc, 0x120000, v244
	v_addc_co_u32_e32 v247, vcc, 0, v245, vcc
	v_permlane16_swap_b32 v230, v232
	v_permlane16_swap_b32 v231, v233
	global_store_dwordx4 v[246:247], v[230:233], off
	v_max_f32_e32 v36, v36, v36
	v_max_f32_e32 v36, 0, v36
	v_mul_f32_e32 v36, v36, v36
	v_max_f32_e32 v37, v37, v37
	v_max_f32_e32 v37, 0, v37
	v_mul_f32_e32 v37, v37, v37
	v_max_f32_e32 v38, v38, v38
	v_max_f32_e32 v38, 0, v38
	v_mul_f32_e32 v38, v38, v38
	v_max_f32_e32 v39, v39, v39
	v_max_f32_e32 v39, 0, v39
	v_mul_f32_e32 v39, v39, v39
	v_max_f32_e32 v32, v32, v32
	v_max_f32_e32 v32, 0, v32
	v_mul_f32_e32 v32, v32, v32
	v_max_f32_e32 v33, v33, v33
	v_max_f32_e32 v33, 0, v33
	v_mul_f32_e32 v33, v33, v33
	v_max_f32_e32 v34, v34, v34
	v_max_f32_e32 v34, 0, v34
	v_mul_f32_e32 v34, v34, v34
	v_max_f32_e32 v35, v35, v35
	v_max_f32_e32 v35, 0, v35
	v_mul_f32_e32 v35, v35, v35
	v_cvt_pk_bf16_f32 v234, v36, v37
	v_cvt_pk_bf16_f32 v235, v38, v39
	v_cvt_pk_bf16_f32 v236, v32, v33
	v_cvt_pk_bf16_f32 v237, v34, v35
	v_add_co_u32_e32 v246, vcc, 0x120100, v244
	v_addc_co_u32_e32 v247, vcc, 0, v245, vcc
	v_permlane16_swap_b32 v234, v236
	v_permlane16_swap_b32 v235, v237
	global_store_dwordx4 v[246:247], v[234:237], off
	v_max_f32_e32 v28, v28, v28
	v_max_f32_e32 v28, 0, v28
	v_mul_f32_e32 v28, v28, v28
	v_max_f32_e32 v29, v29, v29
	v_max_f32_e32 v29, 0, v29
	v_mul_f32_e32 v29, v29, v29
	v_max_f32_e32 v30, v30, v30
	v_max_f32_e32 v30, 0, v30
	v_mul_f32_e32 v30, v30, v30
	v_max_f32_e32 v31, v31, v31
	v_max_f32_e32 v31, 0, v31
	v_mul_f32_e32 v31, v31, v31
	v_max_f32_e32 v24, v24, v24
	v_max_f32_e32 v24, 0, v24
	v_mul_f32_e32 v24, v24, v24
	v_max_f32_e32 v25, v25, v25
	v_max_f32_e32 v25, 0, v25
	v_mul_f32_e32 v25, v25, v25
	v_max_f32_e32 v26, v26, v26
	v_max_f32_e32 v26, 0, v26
	v_mul_f32_e32 v26, v26, v26
	v_max_f32_e32 v27, v27, v27
	v_max_f32_e32 v27, 0, v27
	v_mul_f32_e32 v27, v27, v27
	v_cvt_pk_bf16_f32 v230, v28, v29
	v_cvt_pk_bf16_f32 v231, v30, v31
	v_cvt_pk_bf16_f32 v232, v24, v25
	v_cvt_pk_bf16_f32 v233, v26, v27
	v_add_co_u32_e32 v246, vcc, 0x140000, v244
	v_addc_co_u32_e32 v247, vcc, 0, v245, vcc
	v_permlane16_swap_b32 v230, v232
	v_permlane16_swap_b32 v231, v233
	global_store_dwordx4 v[246:247], v[230:233], off
	v_max_f32_e32 v20, v20, v20
	v_max_f32_e32 v20, 0, v20
	v_mul_f32_e32 v20, v20, v20
	v_max_f32_e32 v21, v21, v21
	v_max_f32_e32 v21, 0, v21
	v_mul_f32_e32 v21, v21, v21
	v_max_f32_e32 v22, v22, v22
	v_max_f32_e32 v22, 0, v22
	v_mul_f32_e32 v22, v22, v22
	v_max_f32_e32 v23, v23, v23
	v_max_f32_e32 v23, 0, v23
	v_mul_f32_e32 v23, v23, v23
	v_max_f32_e32 v16, v16, v16
	v_max_f32_e32 v16, 0, v16
	v_mul_f32_e32 v16, v16, v16
	v_max_f32_e32 v17, v17, v17
	v_max_f32_e32 v17, 0, v17
	v_mul_f32_e32 v17, v17, v17
	v_max_f32_e32 v18, v18, v18
	v_max_f32_e32 v18, 0, v18
	v_mul_f32_e32 v18, v18, v18
	v_max_f32_e32 v19, v19, v19
	v_max_f32_e32 v19, 0, v19
	v_mul_f32_e32 v19, v19, v19
	v_cvt_pk_bf16_f32 v234, v20, v21
	v_cvt_pk_bf16_f32 v235, v22, v23
	v_cvt_pk_bf16_f32 v236, v16, v17
	v_cvt_pk_bf16_f32 v237, v18, v19
	v_add_co_u32_e32 v246, vcc, 0x140100, v244
	v_addc_co_u32_e32 v247, vcc, 0, v245, vcc
	v_permlane16_swap_b32 v234, v236
	v_permlane16_swap_b32 v235, v237
	global_store_dwordx4 v[246:247], v[234:237], off
	v_max_f32_e32 v12, v12, v12
	v_max_f32_e32 v12, 0, v12
	v_mul_f32_e32 v12, v12, v12
	v_max_f32_e32 v13, v13, v13
	v_max_f32_e32 v13, 0, v13
	v_mul_f32_e32 v13, v13, v13
	v_max_f32_e32 v14, v14, v14
	v_max_f32_e32 v14, 0, v14
	v_mul_f32_e32 v14, v14, v14
	v_max_f32_e32 v15, v15, v15
	v_max_f32_e32 v15, 0, v15
	v_mul_f32_e32 v15, v15, v15
	v_max_f32_e32 v8, v8, v8
	v_max_f32_e32 v8, 0, v8
	v_mul_f32_e32 v8, v8, v8
	v_max_f32_e32 v9, v9, v9
	v_max_f32_e32 v9, 0, v9
	v_mul_f32_e32 v9, v9, v9
	v_max_f32_e32 v10, v10, v10
	v_max_f32_e32 v10, 0, v10
	v_mul_f32_e32 v10, v10, v10
	v_max_f32_e32 v11, v11, v11
	v_max_f32_e32 v11, 0, v11
	v_mul_f32_e32 v11, v11, v11
	v_cvt_pk_bf16_f32 v230, v12, v13
	v_cvt_pk_bf16_f32 v231, v14, v15
	v_cvt_pk_bf16_f32 v232, v8, v9
	v_cvt_pk_bf16_f32 v233, v10, v11
	v_add_co_u32_e32 v246, vcc, 0x160000, v244
	v_addc_co_u32_e32 v247, vcc, 0, v245, vcc
	v_permlane16_swap_b32 v230, v232
	v_permlane16_swap_b32 v231, v233
	global_store_dwordx4 v[246:247], v[230:233], off
	v_max_f32_e32 v4, v4, v4
	v_max_f32_e32 v4, 0, v4
	v_mul_f32_e32 v4, v4, v4
	v_max_f32_e32 v5, v5, v5
	v_max_f32_e32 v5, 0, v5
	v_mul_f32_e32 v5, v5, v5
	v_max_f32_e32 v6, v6, v6
	v_max_f32_e32 v6, 0, v6
	v_mul_f32_e32 v6, v6, v6
	v_max_f32_e32 v7, v7, v7
	v_max_f32_e32 v7, 0, v7
	v_mul_f32_e32 v7, v7, v7
	v_max_f32_e32 v0, v0, v0
	v_max_f32_e32 v0, 0, v0
	v_mul_f32_e32 v0, v0, v0
	v_max_f32_e32 v1, v1, v1
	v_max_f32_e32 v1, 0, v1
	v_mul_f32_e32 v1, v1, v1
	v_max_f32_e32 v2, v2, v2
	v_max_f32_e32 v2, 0, v2
	v_mul_f32_e32 v2, v2, v2
	v_max_f32_e32 v3, v3, v3
	v_max_f32_e32 v3, 0, v3
	v_mul_f32_e32 v3, v3, v3
	v_cvt_pk_bf16_f32 v234, v4, v5
	v_cvt_pk_bf16_f32 v235, v6, v7
	v_cvt_pk_bf16_f32 v236, v0, v1
	v_cvt_pk_bf16_f32 v237, v2, v3
	v_add_co_u32_e32 v246, vcc, 0x160100, v244
	v_addc_co_u32_e32 v247, vcc, 0, v245, vcc
	v_permlane16_swap_b32 v234, v236
	v_permlane16_swap_b32 v235, v237
	global_store_dwordx4 v[246:247], v[234:237], off
	s_branch .LBB0_1065

.Lfb_no:
	s_cmp_lt_i32 s79, 22
	s_mov_b64 s[2:3], 0
	s_cbranch_scc1 .LBB0_117
	s_cmp_gt_i32 s79, 23
	s_cbranch_scc0 .LBB0_111
	s_cmp_gt_i32 s79, 24
	s_cbranch_scc0 .LBB0_108
	s_cmp_gt_i32 s79, 25
	s_cbranch_scc0 .LBB0_97
	s_cmp_eq_u32 s79, 26
	s_mov_b64 s[2:3], -1
	s_cbranch_scc0 .LBB0_96
	v_max_f32_e32 v137, v124, v124
	v_max_f32_e32 v137, 0, v137
	v_max_f32_e32 v140, v120, v120
	v_max_f32_e32 v140, 0, v140
	v_mul_f32_e32 v144, v137, v137
	v_max_f32_e32 v137, v125, v125
	v_mul_f32_e32 v152, v140, v140
	v_max_f32_e32 v137, 0, v137
	v_max_f32_e32 v140, v121, v121
	v_max_f32_e32 v140, 0, v140
	v_mul_f32_e32 v145, v137, v137
	v_max_f32_e32 v137, v126, v126
	v_mul_f32_e32 v166, v140, v140
	v_max_f32_e32 v137, 0, v137
	v_max_f32_e32 v140, v122, v122
	v_max_f32_e32 v140, 0, v140
	v_mul_f32_e32 v167, v137, v137
	v_max_f32_e32 v137, v127, v127
	v_mul_f32_e32 v168, v140, v140
	v_max_f32_e32 v137, 0, v137
	v_max_f32_e32 v140, v123, v123
	v_max_f32_e32 v140, 0, v140
	v_mul_f32_e32 v169, v137, v137
	v_ashrrev_i32_e32 v137, 31, v136
	v_mul_f32_e32 v170, v140, v140
	v_lshl_add_u64 v[140:141], v[136:137], 1, v[148:149]
	v_cvt_pk_bf16_f32 v144, v144, v145
	v_cvt_pk_bf16_f32 v145, v167, v169
	v_mov_b32_e32 v194, v144
	v_mov_b32_e32 v195, v145
	v_cvt_pk_bf16_f32 v144, v152, v166
	v_cvt_pk_bf16_f32 v145, v168, v170
	v_mov_b32_e32 v196, v144
	v_mov_b32_e32 v197, v145
	v_lshl_add_u64 v[198:199], v[200:201], 0, v[140:141]
	s_nop 0
	v_permlane16_swap_b32 v194, v196
	v_permlane16_swap_b32 v195, v197
	global_store_dwordx4 v[198:199], v[194:197], off
	s_mov_b64 s[2:3], 0

.LBB0_108:
	s_and_b64 vcc, exec, s[58:59]
	s_cbranch_vccz .LBB0_110
	v_ashrrev_i32_e32 v137, 31, v136
	v_lshl_add_u64 v[140:141], v[142:143], 0, v[136:137]
	v_lshlrev_b64 v[140:141], 1, v[140:141]
	v_lshl_add_u64 v[144:145], s[40:41], 0, v[140:141]
	v_lshl_add_u64 v[140:141], s[36:37], 0, v[140:141]
	global_load_dwordx2 v[166:167], v[144:145], off
	global_load_dwordx2 v[172:173], v[140:141], off
	s_waitcnt vmcnt(0)
	v_lshlrev_b32_e32 v168, 16, v166
	v_and_b32_e32 v169, 0xffff0000, v166
	v_lshlrev_b32_e32 v166, 16, v167
	v_and_b32_e32 v167, 0xffff0000, v167
	v_lshlrev_b32_e32 v184, 16, v172
	v_and_b32_e32 v185, 0xffff0000, v172
	v_lshlrev_b32_e32 v172, 16, v173
	v_and_b32_e32 v173, 0xffff0000, v173
	global_load_dwordx2 v[144:145], v[144:145], off offset:32
	v_pk_fma_f32 v[166:167], v[126:127], v[166:167], v[172:173]
	global_load_dwordx2 v[172:173], v[140:141], off offset:32
	v_pk_fma_f32 v[168:169], v[124:125], v[168:169], v[184:185]
	s_waitcnt vmcnt(1)
	v_lshlrev_b32_e32 v170, 16, v144
	v_and_b32_e32 v171, 0xffff0000, v144
	v_lshlrev_b32_e32 v144, 16, v145
	v_and_b32_e32 v145, 0xffff0000, v145
	s_waitcnt vmcnt(0)
	v_lshlrev_b32_e32 v184, 16, v172
	v_and_b32_e32 v185, 0xffff0000, v172
	v_lshlrev_b32_e32 v172, 16, v173
	v_and_b32_e32 v173, 0xffff0000, v173
	v_pk_fma_f32 v[144:145], v[122:123], v[144:145], v[172:173]
	v_pk_fma_f32 v[170:171], v[120:121], v[170:171], v[184:185]
	v_cvt_pk_bf16_f32 v168, v168, v169
	v_cvt_pk_bf16_f32 v169, v166, v167
	v_mov_b32_e32 v194, v168
	v_mov_b32_e32 v195, v169
	v_cvt_pk_bf16_f32 v166, v170, v171
	v_cvt_pk_bf16_f32 v167, v144, v145
	v_mov_b32_e32 v196, v166
	v_mov_b32_e32 v197, v167
	v_lshl_add_u64 v[198:199], v[200:201], 0, v[140:141]
	s_nop 0
	v_permlane16_swap_b32 v194, v196
	v_permlane16_swap_b32 v195, v197
	global_store_dwordx4 v[198:199], v[194:197], off

.LBB0_111:
	s_and_b64 vcc, exec, s[58:59]
	s_cbranch_vccz .LBB0_116
	s_cmp_gt_i32 s79, 22
	s_mov_b64 s[58:59], -1
	s_cbranch_scc0 .LBB0_114
	v_ashrrev_i32_e32 v137, 31, v136
	v_lshl_add_u64 v[140:141], v[142:143], 0, v[136:137]
	v_lshlrev_b64 v[140:141], 1, v[140:141]
	v_lshl_add_u64 v[144:145], s[34:35], 0, v[140:141]
	v_lshl_add_u64 v[140:141], s[36:37], 0, v[140:141]
	global_load_dwordx2 v[166:167], v[144:145], off
	global_load_dwordx2 v[172:173], v[140:141], off
	s_mov_b64 s[58:59], 0
	global_load_dwordx2 v[144:145], v[144:145], off offset:32
	s_waitcnt vmcnt(0)
	v_lshlrev_b32_e32 v168, 16, v166
	v_and_b32_e32 v169, 0xffff0000, v166
	v_lshlrev_b32_e32 v166, 16, v167
	v_and_b32_e32 v167, 0xffff0000, v167
	v_lshlrev_b32_e32 v184, 16, v172
	v_and_b32_e32 v185, 0xffff0000, v172
	v_lshlrev_b32_e32 v172, 16, v173
	v_and_b32_e32 v173, 0xffff0000, v173
	v_pk_fma_f32 v[166:167], v[126:127], v[166:167], v[172:173]
	global_load_dwordx2 v[172:173], v[140:141], off offset:32
	v_lshlrev_b32_e32 v170, 16, v144
	v_and_b32_e32 v171, 0xffff0000, v144
	v_lshlrev_b32_e32 v144, 16, v145
	v_and_b32_e32 v145, 0xffff0000, v145
	v_pk_fma_f32 v[168:169], v[124:125], v[168:169], v[184:185]
	s_waitcnt vmcnt(0)
	v_lshlrev_b32_e32 v184, 16, v172
	v_and_b32_e32 v185, 0xffff0000, v172
	v_lshlrev_b32_e32 v172, 16, v173
	v_and_b32_e32 v173, 0xffff0000, v173
	v_pk_fma_f32 v[144:145], v[122:123], v[144:145], v[172:173]
	v_pk_fma_f32 v[170:171], v[120:121], v[170:171], v[184:185]
	v_cvt_pk_bf16_f32 v168, v168, v169
	v_cvt_pk_bf16_f32 v169, v166, v167
	v_mov_b32_e32 v194, v168
	v_mov_b32_e32 v195, v169
	v_cvt_pk_bf16_f32 v166, v170, v171
	v_cvt_pk_bf16_f32 v167, v144, v145
	v_mov_b32_e32 v196, v166
	v_mov_b32_e32 v197, v167
	v_lshl_add_u64 v[198:199], v[200:201], 0, v[140:141]
	s_nop 0
	v_permlane16_swap_b32 v194, v196
	v_permlane16_swap_b32 v195, v197
	global_store_dwordx4 v[198:199], v[194:197], off
.LBB0_114:
	s_andn2_b64 vcc, exec, s[58:59]
	s_cbranch_vccnz .LBB0_116
	v_ashrrev_i32_e32 v137, 31, v136
	v_lshl_add_u64 v[140:141], v[142:143], 0, v[136:137]
	v_lshlrev_b64 v[140:141], 1, v[140:141]
	v_lshl_add_u64 v[144:145], s[38:39], 0, v[140:141]
	global_load_dwordx2 v[166:167], v[144:145], off
	s_nop 0
	global_load_dwordx2 v[144:145], v[144:145], off offset:32
	v_lshl_add_u64 v[140:141], s[36:37], 0, v[140:141]
	s_waitcnt vmcnt(0)
	v_lshlrev_b32_e32 v168, 16, v166
	v_and_b32_e32 v169, 0xffff0000, v166
	v_lshlrev_b32_e32 v166, 16, v167
	v_and_b32_e32 v167, 0xffff0000, v167
	v_pk_mul_f32 v[168:169], v[124:125], v[168:169]
	v_lshlrev_b32_e32 v170, 16, v144
	v_and_b32_e32 v171, 0xffff0000, v144
	v_lshlrev_b32_e32 v144, 16, v145
	v_and_b32_e32 v145, 0xffff0000, v145
	v_pk_mul_f32 v[166:167], v[126:127], v[166:167]
	v_cvt_pk_bf16_f32 v168, v168, v169
	v_pk_mul_f32 v[144:145], v[122:123], v[144:145]
	v_cvt_pk_bf16_f32 v169, v166, v167
	v_pk_mul_f32 v[170:171], v[120:121], v[170:171]
	v_cvt_pk_bf16_f32 v167, v144, v145
	s_nop 0
	v_cvt_pk_bf16_f32 v166, v170, v171
	v_mov_b32_e32 v194, v168
	v_mov_b32_e32 v195, v169
	v_mov_b32_e32 v196, v166
	v_mov_b32_e32 v197, v167
	v_lshl_add_u64 v[198:199], v[200:201], 0, v[140:141]
	s_nop 0
	v_permlane16_swap_b32 v194, v196
	v_permlane16_swap_b32 v195, v197
	global_store_dwordx4 v[198:199], v[194:197], off

.LBB0_124:
	s_ashr_i32 s33, s67, 2
	s_add_i32 s33, s33, 2
	v_and_b32_e32 v137, 0x36c, v136
	v_mad_i64_i32 v[186:187], s[56:57], s33, v154, v[140:141]
	v_lshlrev_b32_e32 v188, 1, v137
	v_mov_b32_e32 v189, v153
	v_lshl_add_u64 v[186:187], v[186:187], 0, v[188:189]
	v_cvt_pk_bf16_f32 v172, v172, v173
	v_cvt_pk_bf16_f32 v173, v168, v169
	v_mov_b32_e32 v194, v172
	v_mov_b32_e32 v195, v173
	v_cvt_pk_bf16_f32 v168, v170, v171
	v_cvt_pk_bf16_f32 v169, v166, v167
	v_mov_b32_e32 v196, v168
	v_mov_b32_e32 v197, v169
	v_lshl_add_u64 v[198:199], v[200:201], 0, v[186:187]
	s_nop 0
	v_permlane16_swap_b32 v194, v196
	v_permlane16_swap_b32 v195, v197
	global_store_dwordx4 v[198:199], v[194:197], off

.LBB0_137:
	s_or_b64 exec, exec, s[56:57]
	s_add_i32 s33, s33, 1
	v_mad_i64_i32 v[186:187], s[56:57], s33, v154, v[140:141]
	v_lshlrev_b32_e32 v188, 1, v137
	v_mov_b32_e32 v189, v153
	v_lshl_add_u64 v[186:187], v[186:187], 0, v[188:189]
	v_cvt_pk_bf16_f32 v168, v168, v169
	v_cvt_pk_bf16_f32 v169, v166, v167
	v_mov_b32_e32 v194, v168
	v_mov_b32_e32 v195, v169
	v_cvt_pk_bf16_f32 v166, v172, v173
	v_cvt_pk_bf16_f32 v167, v170, v171
	v_mov_b32_e32 v196, v166
	v_mov_b32_e32 v197, v167
	v_lshl_add_u64 v[198:199], v[200:201], 0, v[186:187]
	s_nop 0
	v_permlane16_swap_b32 v194, v196
	v_permlane16_swap_b32 v195, v197
	global_store_dwordx4 v[198:199], v[194:197], off
	s_mov_b64 s[56:57], 0

.LBB0_150:
	v_and_b32_e32 v168, 0x36c, v136
	s_andn2_b64 vcc, exec, s[56:57]
	v_lshlrev_b32_e32 v138, 1, v168
	s_cbranch_vccnz .LBB0_152
	s_ashr_i32 s2, s67, 2
	s_add_i32 s2, s2, 1
	v_mad_i64_i32 v[170:171], s[2:3], s2, v154, v[140:141]
	v_mov_b32_e32 v139, v153
	v_lshl_add_u64 v[170:171], v[170:171], 0, v[138:139]
	v_cvt_pk_f16_f32 v127, v126, v127
	v_cvt_pk_f16_f32 v126, v124, v125
	v_cvt_pk_f16_f32 v123, v122, v123
	v_cvt_pk_f16_f32 v122, v120, v121
	v_mov_b32_e32 v194, v126
	v_mov_b32_e32 v195, v127
	v_mov_b32_e32 v196, v122
	v_mov_b32_e32 v197, v123
	v_lshl_add_u64 v[198:199], v[200:201], 0, v[170:171]
	s_nop 0
	v_permlane16_swap_b32 v194, v196
	v_permlane16_swap_b32 v195, v197
	global_store_dwordx4 v[198:199], v[194:197], off
.LBB0_152:
	v_or_b32_e32 v120, 0x80, v136
	s_mov_b64 s[58:59], -1
	s_mov_b64 s[56:57], 0
	s_cmp_lt_i32 s79, 22
	s_mov_b64 s[2:3], 0
	s_cbranch_scc1 .LBB0_177
	s_cmp_gt_i32 s79, 23
	s_cbranch_scc0 .LBB0_171
	s_cmp_gt_i32 s79, 24
	s_cbranch_scc0 .LBB0_168
	s_cmp_gt_i32 s79, 25
	s_cbranch_scc0 .LBB0_159
	s_cmp_eq_u32 s79, 26
	s_mov_b64 s[2:3], -1
	s_cbranch_scc0 .LBB0_158
	v_max_f32_e32 v122, v112, v112
	v_max_f32_e32 v122, 0, v122
	v_mul_f32_e32 v126, v122, v122
	v_max_f32_e32 v122, v117, v117
	v_max_f32_e32 v123, v113, v113
	v_max_f32_e32 v122, 0, v122
	v_max_f32_e32 v123, 0, v123
	v_mul_f32_e32 v124, v122, v122
	v_mul_f32_e32 v127, v123, v123
	v_max_f32_e32 v122, v118, v118
	v_max_f32_e32 v123, v114, v114
	v_max_f32_e32 v122, 0, v122
	v_max_f32_e32 v123, 0, v123
	v_max_f32_e32 v121, v116, v116
	v_mul_f32_e32 v125, v122, v122
	v_mul_f32_e32 v139, v123, v123
	v_max_f32_e32 v122, v119, v119
	v_max_f32_e32 v123, v115, v115
	v_max_f32_e32 v121, 0, v121
	v_max_f32_e32 v122, 0, v122
	v_max_f32_e32 v123, 0, v123
	v_ashrrev_i32_e32 v137, 31, v136
	v_mul_f32_e32 v121, v121, v121
	v_mul_f32_e32 v169, v122, v122
	v_mul_f32_e32 v170, v123, v123
	v_lshl_add_u64 v[122:123], v[136:137], 1, v[148:149]
	v_cvt_pk_bf16_f32 v124, v121, v124
	v_cvt_pk_bf16_f32 v125, v125, v169
	s_mov_b64 s[2:3], 0
	v_mov_b32_e32 v194, v124
	v_mov_b32_e32 v195, v125
	v_cvt_pk_bf16_f32 v124, v126, v127
	v_cvt_pk_bf16_f32 v125, v139, v170
	v_mov_b32_e32 v196, v124
	v_mov_b32_e32 v197, v125
	v_lshl_add_u64 v[198:199], v[200:201], 0, v[122:123]
	s_nop 0
	v_permlane16_swap_b32 v194, v196
	v_permlane16_swap_b32 v195, v197
	global_store_dwordx4 v[198:199], v[194:197], off offset:256

.LBB0_168:
	s_and_b64 vcc, exec, s[58:59]
	s_cbranch_vccz .LBB0_170
	v_ashrrev_i32_e32 v121, 31, v120
	v_lshl_add_u64 v[122:123], v[142:143], 0, v[120:121]
	v_lshlrev_b64 v[122:123], 1, v[122:123]
	v_lshl_add_u64 v[124:125], s[40:41], 0, v[122:123]
	v_lshl_add_u64 v[122:123], s[36:37], 0, v[122:123]
	global_load_dwordx2 v[126:127], v[124:125], off
	global_load_dwordx2 v[170:171], v[122:123], off
	s_waitcnt vmcnt(0)
	v_lshlrev_b32_e32 v146, 16, v126
	v_and_b32_e32 v147, 0xffff0000, v126
	v_lshlrev_b32_e32 v126, 16, v127
	v_and_b32_e32 v127, 0xffff0000, v127
	v_lshlrev_b32_e32 v172, 16, v170
	v_and_b32_e32 v173, 0xffff0000, v170
	v_lshlrev_b32_e32 v170, 16, v171
	v_and_b32_e32 v171, 0xffff0000, v171
	global_load_dwordx2 v[124:125], v[124:125], off offset:32
	v_pk_fma_f32 v[126:127], v[118:119], v[126:127], v[170:171]
	global_load_dwordx2 v[170:171], v[122:123], off offset:32
	v_pk_fma_f32 v[146:147], v[116:117], v[146:147], v[172:173]
	s_waitcnt vmcnt(1)
	v_lshlrev_b32_e32 v148, 16, v124
	v_and_b32_e32 v149, 0xffff0000, v124
	v_lshlrev_b32_e32 v124, 16, v125
	v_and_b32_e32 v125, 0xffff0000, v125
	s_waitcnt vmcnt(0)
	v_lshlrev_b32_e32 v172, 16, v170
	v_and_b32_e32 v173, 0xffff0000, v170
	v_lshlrev_b32_e32 v170, 16, v171
	v_and_b32_e32 v171, 0xffff0000, v171
	v_pk_fma_f32 v[124:125], v[114:115], v[124:125], v[170:171]
	v_pk_fma_f32 v[148:149], v[112:113], v[148:149], v[172:173]
	v_cvt_pk_bf16_f32 v146, v146, v147
	v_cvt_pk_bf16_f32 v147, v126, v127
	v_mov_b32_e32 v194, v146
	v_mov_b32_e32 v195, v147
	v_cvt_pk_bf16_f32 v126, v148, v149
	v_cvt_pk_bf16_f32 v127, v124, v125
	v_mov_b32_e32 v196, v126
	v_mov_b32_e32 v197, v127
	v_lshl_add_u64 v[198:199], v[200:201], 0, v[122:123]
	s_nop 0
	v_permlane16_swap_b32 v194, v196
	v_permlane16_swap_b32 v195, v197
	global_store_dwordx4 v[198:199], v[194:197], off

.LBB0_171:
	s_and_b64 vcc, exec, s[58:59]
	s_cbranch_vccz .LBB0_176
	s_cmp_gt_i32 s79, 22
	s_mov_b64 s[58:59], -1
	s_cbranch_scc0 .LBB0_174
	v_ashrrev_i32_e32 v121, 31, v120
	v_lshl_add_u64 v[122:123], v[142:143], 0, v[120:121]
	v_lshlrev_b64 v[122:123], 1, v[122:123]
	v_lshl_add_u64 v[124:125], s[34:35], 0, v[122:123]
	v_lshl_add_u64 v[122:123], s[36:37], 0, v[122:123]
	global_load_dwordx2 v[126:127], v[124:125], off
	global_load_dwordx2 v[170:171], v[122:123], off
	s_mov_b64 s[58:59], 0
	global_load_dwordx2 v[124:125], v[124:125], off offset:32
	s_waitcnt vmcnt(0)
	v_lshlrev_b32_e32 v146, 16, v126
	v_and_b32_e32 v147, 0xffff0000, v126
	v_lshlrev_b32_e32 v126, 16, v127
	v_and_b32_e32 v127, 0xffff0000, v127
	v_lshlrev_b32_e32 v172, 16, v170
	v_and_b32_e32 v173, 0xffff0000, v170
	v_lshlrev_b32_e32 v170, 16, v171
	v_and_b32_e32 v171, 0xffff0000, v171
	v_pk_fma_f32 v[126:127], v[118:119], v[126:127], v[170:171]
	global_load_dwordx2 v[170:171], v[122:123], off offset:32
	v_lshlrev_b32_e32 v148, 16, v124
	v_and_b32_e32 v149, 0xffff0000, v124
	v_lshlrev_b32_e32 v124, 16, v125
	v_and_b32_e32 v125, 0xffff0000, v125
	v_pk_fma_f32 v[146:147], v[116:117], v[146:147], v[172:173]
	s_waitcnt vmcnt(0)
	v_lshlrev_b32_e32 v172, 16, v170
	v_and_b32_e32 v173, 0xffff0000, v170
	v_lshlrev_b32_e32 v170, 16, v171
	v_and_b32_e32 v171, 0xffff0000, v171
	v_pk_fma_f32 v[124:125], v[114:115], v[124:125], v[170:171]
	v_pk_fma_f32 v[148:149], v[112:113], v[148:149], v[172:173]
	v_cvt_pk_bf16_f32 v146, v146, v147
	v_cvt_pk_bf16_f32 v147, v126, v127
	v_mov_b32_e32 v194, v146
	v_mov_b32_e32 v195, v147
	v_cvt_pk_bf16_f32 v126, v148, v149
	v_cvt_pk_bf16_f32 v127, v124, v125
	v_mov_b32_e32 v196, v126
	v_mov_b32_e32 v197, v127
	v_lshl_add_u64 v[198:199], v[200:201], 0, v[122:123]
	s_nop 0
	v_permlane16_swap_b32 v194, v196
	v_permlane16_swap_b32 v195, v197
	global_store_dwordx4 v[198:199], v[194:197], off
.LBB0_174:
	s_andn2_b64 vcc, exec, s[58:59]
	s_cbranch_vccnz .LBB0_176
	v_ashrrev_i32_e32 v121, 31, v120
	v_lshl_add_u64 v[122:123], v[142:143], 0, v[120:121]
	v_lshlrev_b64 v[122:123], 1, v[122:123]
	v_lshl_add_u64 v[124:125], s[38:39], 0, v[122:123]
	global_load_dwordx2 v[126:127], v[124:125], off
	s_nop 0
	global_load_dwordx2 v[124:125], v[124:125], off offset:32
	v_lshl_add_u64 v[122:123], s[36:37], 0, v[122:123]
	s_waitcnt vmcnt(0)
	v_lshlrev_b32_e32 v142, 16, v126
	v_and_b32_e32 v143, 0xffff0000, v126
	v_lshlrev_b32_e32 v126, 16, v127
	v_and_b32_e32 v127, 0xffff0000, v127
	v_pk_mul_f32 v[142:143], v[116:117], v[142:143]
	v_lshlrev_b32_e32 v146, 16, v124
	v_and_b32_e32 v147, 0xffff0000, v124
	v_lshlrev_b32_e32 v124, 16, v125
	v_and_b32_e32 v125, 0xffff0000, v125
	v_pk_mul_f32 v[126:127], v[118:119], v[126:127]
	v_cvt_pk_bf16_f32 v142, v142, v143
	v_pk_mul_f32 v[124:125], v[114:115], v[124:125]
	v_cvt_pk_bf16_f32 v143, v126, v127
	v_pk_mul_f32 v[146:147], v[112:113], v[146:147]
	v_cvt_pk_bf16_f32 v127, v124, v125
	s_nop 0
	v_cvt_pk_bf16_f32 v126, v146, v147
	v_mov_b32_e32 v194, v142
	v_mov_b32_e32 v195, v143
	v_mov_b32_e32 v196, v126
	v_mov_b32_e32 v197, v127
	v_lshl_add_u64 v[198:199], v[200:201], 0, v[122:123]
	s_nop 0
	v_permlane16_swap_b32 v194, v196
	v_permlane16_swap_b32 v195, v197
	global_store_dwordx4 v[198:199], v[194:197], off

.LBB0_184:
	s_ashr_i32 s33, s67, 2
	s_add_i32 s33, s33, 2
	v_and_b32_e32 v121, 0x3ec, v120
	v_mad_i64_i32 v[146:147], s[56:57], s33, v154, v[140:141]
	v_lshlrev_b32_e32 v148, 1, v121
	v_mov_b32_e32 v149, v153
	v_lshl_add_u64 v[146:147], v[146:147], 0, v[148:149]
	v_cvt_pk_bf16_f32 v142, v142, v143
	v_cvt_pk_bf16_f32 v143, v124, v125
	v_mov_b32_e32 v194, v142
	v_mov_b32_e32 v195, v143
	v_cvt_pk_bf16_f32 v124, v126, v127
	v_cvt_pk_bf16_f32 v125, v122, v123
	v_mov_b32_e32 v196, v124
	v_mov_b32_e32 v197, v125
	v_lshl_add_u64 v[198:199], v[200:201], 0, v[146:147]
	s_nop 0
	v_permlane16_swap_b32 v194, v196
	v_permlane16_swap_b32 v195, v197
	global_store_dwordx4 v[198:199], v[194:197], off

.LBB0_197:
	s_or_b64 exec, exec, s[56:57]
	s_add_i32 s33, s33, 1
	v_mad_i64_i32 v[144:145], s[10:11], s33, v154, v[140:141]
	v_lshlrev_b32_e32 v152, 1, v121
	v_lshl_add_u64 v[144:145], v[144:145], 0, v[152:153]
	v_cvt_pk_bf16_f32 v124, v124, v125
	v_cvt_pk_bf16_f32 v125, v122, v123
	v_mov_b32_e32 v194, v124
	v_mov_b32_e32 v195, v125
	v_cvt_pk_bf16_f32 v122, v142, v143
	v_cvt_pk_bf16_f32 v123, v126, v127
	v_mov_b32_e32 v196, v122
	v_mov_b32_e32 v197, v123
	v_lshl_add_u64 v[198:199], v[200:201], 0, v[144:145]
	s_nop 0
	v_permlane16_swap_b32 v194, v196
	v_permlane16_swap_b32 v195, v197
	global_store_dwordx4 v[198:199], v[194:197], off

.LBB0_209:
	v_and_b32_e32 v150, 0x3ec, v120
	s_andn2_b64 vcc, exec, s[56:57]
	v_lshlrev_b32_e32 v122, 1, v150
	s_cbranch_vccnz .LBB0_211
	s_ashr_i32 s2, s67, 2
	s_add_i32 s2, s2, 1
	v_mad_i64_i32 v[124:125], s[2:3], s2, v154, v[140:141]
	v_mov_b32_e32 v123, v153
	v_lshl_add_u64 v[124:125], v[124:125], 0, v[122:123]
	v_cvt_pk_f16_f32 v119, v118, v119
	v_cvt_pk_f16_f32 v118, v116, v117
	v_cvt_pk_f16_f32 v115, v114, v115
	v_cvt_pk_f16_f32 v114, v112, v113
	v_mov_b32_e32 v194, v118
	v_mov_b32_e32 v195, v119
	v_mov_b32_e32 v196, v114
	v_mov_b32_e32 v197, v115
	v_lshl_add_u64 v[198:199], v[200:201], 0, v[124:125]
	s_nop 0
	v_permlane16_swap_b32 v194, v196
	v_permlane16_swap_b32 v195, v197
	global_store_dwordx4 v[198:199], v[194:197], off
.LBB0_211:
	v_or_b32_e32 v140, s62, v175
	v_ashrrev_i32_e32 v141, 31, v140
	v_lshlrev_b64 v[112:113], 13, v[140:141]
	v_add_u32_e32 v126, 0xffffc000, v140
	v_mov_b32_e32 v127, v153
	v_lshl_add_u64 v[124:125], s[52:53], 0, v[112:113]
	v_cmp_gt_i32_e64 s[10:11], s92, v140
	v_cmp_lt_i32_e64 s[8:9], s80, v140
	v_lshlrev_b64 v[118:119], 10, v[126:127]
	v_lshlrev_b64 v[114:115], 10, v[140:141]
	s_mov_b64 s[58:59], -1
	s_mov_b64 s[56:57], 0
	s_cmp_lt_i32 s79, 22
	s_mov_b64 s[2:3], 0
	s_cbranch_scc1 .LBB0_236
	s_cmp_gt_i32 s79, 23
	s_cbranch_scc0 .LBB0_230
	s_cmp_gt_i32 s79, 24
	s_cbranch_scc0 .LBB0_227
	s_cmp_gt_i32 s79, 25
	s_cbranch_scc0 .LBB0_218
	s_cmp_eq_u32 s79, 26
	s_mov_b64 s[2:3], -1
	s_cbranch_scc0 .LBB0_217
	v_max_f32_e32 v112, v108, v108
	v_max_f32_e32 v113, v104, v104
	v_max_f32_e32 v112, 0, v112
	v_max_f32_e32 v113, 0, v113
	v_mul_f32_e32 v116, v112, v112
	v_mul_f32_e32 v121, v113, v113
	v_max_f32_e32 v112, v109, v109
	v_max_f32_e32 v113, v105, v105
	v_max_f32_e32 v112, 0, v112
	v_max_f32_e32 v113, 0, v113
	v_mul_f32_e32 v117, v112, v112
	v_mul_f32_e32 v123, v113, v113
	v_max_f32_e32 v112, v110, v110
	v_max_f32_e32 v113, v106, v106
	v_max_f32_e32 v112, 0, v112
	v_max_f32_e32 v113, 0, v113
	v_mul_f32_e32 v139, v112, v112
	v_mul_f32_e32 v142, v113, v113
	v_max_f32_e32 v112, v111, v111
	v_max_f32_e32 v113, v107, v107
	v_max_f32_e32 v112, 0, v112
	v_max_f32_e32 v113, 0, v113
	v_ashrrev_i32_e32 v137, 31, v136
	v_mul_f32_e32 v143, v112, v112
	v_mul_f32_e32 v144, v113, v113
	v_lshl_add_u64 v[112:113], v[136:137], 1, v[124:125]
	v_cvt_pk_bf16_f32 v116, v116, v117
	v_cvt_pk_bf16_f32 v117, v139, v143
	s_mov_b64 s[2:3], 0
	v_mov_b32_e32 v194, v116
	v_mov_b32_e32 v195, v117
	v_cvt_pk_bf16_f32 v116, v121, v123
	v_cvt_pk_bf16_f32 v117, v142, v144
	v_mov_b32_e32 v196, v116
	v_mov_b32_e32 v197, v117
	v_lshl_add_u64 v[198:199], v[200:201], 0, v[112:113]
	s_nop 0
	v_permlane16_swap_b32 v194, v196
	v_permlane16_swap_b32 v195, v197
	global_store_dwordx4 v[198:199], v[194:197], off

.LBB0_227:
	s_and_b64 vcc, exec, s[58:59]
	s_cbranch_vccz .LBB0_229
	v_ashrrev_i32_e32 v137, 31, v136
	v_lshl_add_u64 v[112:113], v[114:115], 0, v[136:137]
	v_lshlrev_b64 v[112:113], 1, v[112:113]
	v_lshl_add_u64 v[116:117], s[40:41], 0, v[112:113]
	v_lshl_add_u64 v[112:113], s[36:37], 0, v[112:113]
	global_load_dwordx2 v[142:143], v[116:117], off
	global_load_dwordx2 v[148:149], v[112:113], off
	s_waitcnt vmcnt(0)
	v_lshlrev_b32_e32 v144, 16, v142
	v_and_b32_e32 v145, 0xffff0000, v142
	v_lshlrev_b32_e32 v142, 16, v143
	v_and_b32_e32 v143, 0xffff0000, v143
	v_lshlrev_b32_e32 v166, 16, v148
	v_and_b32_e32 v167, 0xffff0000, v148
	v_lshlrev_b32_e32 v148, 16, v149
	v_and_b32_e32 v149, 0xffff0000, v149
	global_load_dwordx2 v[116:117], v[116:117], off offset:32
	v_pk_fma_f32 v[142:143], v[110:111], v[142:143], v[148:149]
	global_load_dwordx2 v[148:149], v[112:113], off offset:32
	v_pk_fma_f32 v[144:145], v[108:109], v[144:145], v[166:167]
	s_waitcnt vmcnt(1)
	v_lshlrev_b32_e32 v146, 16, v116
	v_and_b32_e32 v147, 0xffff0000, v116
	v_lshlrev_b32_e32 v116, 16, v117
	v_and_b32_e32 v117, 0xffff0000, v117
	s_waitcnt vmcnt(0)
	v_lshlrev_b32_e32 v166, 16, v148
	v_and_b32_e32 v167, 0xffff0000, v148
	v_lshlrev_b32_e32 v148, 16, v149
	v_and_b32_e32 v149, 0xffff0000, v149
	v_pk_fma_f32 v[116:117], v[106:107], v[116:117], v[148:149]
	v_pk_fma_f32 v[146:147], v[104:105], v[146:147], v[166:167]
	v_cvt_pk_bf16_f32 v144, v144, v145
	v_cvt_pk_bf16_f32 v145, v142, v143
	v_mov_b32_e32 v194, v144
	v_mov_b32_e32 v195, v145
	v_cvt_pk_bf16_f32 v142, v146, v147
	v_cvt_pk_bf16_f32 v143, v116, v117
	v_mov_b32_e32 v196, v142
	v_mov_b32_e32 v197, v143
	v_lshl_add_u64 v[198:199], v[200:201], 0, v[112:113]
	s_nop 0
	v_permlane16_swap_b32 v194, v196
	v_permlane16_swap_b32 v195, v197
	global_store_dwordx4 v[198:199], v[194:197], off

.LBB0_230:
	s_and_b64 vcc, exec, s[58:59]
	s_cbranch_vccz .LBB0_235
	s_cmp_gt_i32 s79, 22
	s_mov_b64 s[58:59], -1
	s_cbranch_scc0 .LBB0_233
	v_ashrrev_i32_e32 v137, 31, v136
	v_lshl_add_u64 v[112:113], v[114:115], 0, v[136:137]
	v_lshlrev_b64 v[112:113], 1, v[112:113]
	v_lshl_add_u64 v[116:117], s[34:35], 0, v[112:113]
	v_lshl_add_u64 v[112:113], s[36:37], 0, v[112:113]
	global_load_dwordx2 v[142:143], v[116:117], off
	global_load_dwordx2 v[148:149], v[112:113], off
	s_mov_b64 s[58:59], 0
	global_load_dwordx2 v[116:117], v[116:117], off offset:32
	s_waitcnt vmcnt(0)
	v_lshlrev_b32_e32 v144, 16, v142
	v_and_b32_e32 v145, 0xffff0000, v142
	v_lshlrev_b32_e32 v142, 16, v143
	v_and_b32_e32 v143, 0xffff0000, v143
	v_lshlrev_b32_e32 v166, 16, v148
	v_and_b32_e32 v167, 0xffff0000, v148
	v_lshlrev_b32_e32 v148, 16, v149
	v_and_b32_e32 v149, 0xffff0000, v149
	v_pk_fma_f32 v[142:143], v[110:111], v[142:143], v[148:149]
	global_load_dwordx2 v[148:149], v[112:113], off offset:32
	v_lshlrev_b32_e32 v146, 16, v116
	v_and_b32_e32 v147, 0xffff0000, v116
	v_lshlrev_b32_e32 v116, 16, v117
	v_and_b32_e32 v117, 0xffff0000, v117
	v_pk_fma_f32 v[144:145], v[108:109], v[144:145], v[166:167]
	s_waitcnt vmcnt(0)
	v_lshlrev_b32_e32 v166, 16, v148
	v_and_b32_e32 v167, 0xffff0000, v148
	v_lshlrev_b32_e32 v148, 16, v149
	v_and_b32_e32 v149, 0xffff0000, v149
	v_pk_fma_f32 v[116:117], v[106:107], v[116:117], v[148:149]
	v_pk_fma_f32 v[146:147], v[104:105], v[146:147], v[166:167]
	v_cvt_pk_bf16_f32 v144, v144, v145
	v_cvt_pk_bf16_f32 v145, v142, v143
	v_mov_b32_e32 v194, v144
	v_mov_b32_e32 v195, v145
	v_cvt_pk_bf16_f32 v142, v146, v147
	v_cvt_pk_bf16_f32 v143, v116, v117
	v_mov_b32_e32 v196, v142
	v_mov_b32_e32 v197, v143
	v_lshl_add_u64 v[198:199], v[200:201], 0, v[112:113]
	s_nop 0
	v_permlane16_swap_b32 v194, v196
	v_permlane16_swap_b32 v195, v197
	global_store_dwordx4 v[198:199], v[194:197], off
.LBB0_233:
	s_andn2_b64 vcc, exec, s[58:59]
	s_cbranch_vccnz .LBB0_235
	v_ashrrev_i32_e32 v137, 31, v136
	v_lshl_add_u64 v[112:113], v[114:115], 0, v[136:137]
	v_lshlrev_b64 v[112:113], 1, v[112:113]
	v_lshl_add_u64 v[116:117], s[38:39], 0, v[112:113]
	global_load_dwordx2 v[142:143], v[116:117], off
	s_nop 0
	global_load_dwordx2 v[116:117], v[116:117], off offset:32
	v_lshl_add_u64 v[112:113], s[36:37], 0, v[112:113]
	s_waitcnt vmcnt(0)
	v_lshlrev_b32_e32 v144, 16, v142
	v_and_b32_e32 v145, 0xffff0000, v142
	v_lshlrev_b32_e32 v142, 16, v143
	v_and_b32_e32 v143, 0xffff0000, v143
	v_pk_mul_f32 v[144:145], v[108:109], v[144:145]
	v_lshlrev_b32_e32 v146, 16, v116
	v_and_b32_e32 v147, 0xffff0000, v116
	v_lshlrev_b32_e32 v116, 16, v117
	v_and_b32_e32 v117, 0xffff0000, v117
	v_pk_mul_f32 v[142:143], v[110:111], v[142:143]
	v_cvt_pk_bf16_f32 v144, v144, v145
	v_pk_mul_f32 v[116:117], v[106:107], v[116:117]
	v_cvt_pk_bf16_f32 v145, v142, v143
	v_pk_mul_f32 v[146:147], v[104:105], v[146:147]
	v_cvt_pk_bf16_f32 v143, v116, v117
	s_nop 0
	v_cvt_pk_bf16_f32 v142, v146, v147
	v_mov_b32_e32 v194, v144
	v_mov_b32_e32 v195, v145
	v_mov_b32_e32 v196, v142
	v_mov_b32_e32 v197, v143
	v_lshl_add_u64 v[198:199], v[200:201], 0, v[112:113]
	s_nop 0
	v_permlane16_swap_b32 v194, v196
	v_permlane16_swap_b32 v195, v197
	global_store_dwordx4 v[198:199], v[194:197], off

.LBB0_236:
	v_lshrrev_b32_e32 v116, 4, v126
	v_and_b32_e32 v166, 0xffffff0, v116
	v_mov_b32_e32 v116, s64
	s_movk_i32 s33, 0xdf
	v_cndmask_b32_e64 v116, v175, v116, s[4:5]
	v_lshlrev_b64 v[112:113], 11, v[140:141]
	v_and_or_b32 v152, v140, s33, v163
	s_movk_i32 s33, 0x1fdf
	v_lshl_or_b32 v116, v116, 7, v182
	v_mov_b32_e32 v117, v153
	v_lshl_add_u64 v[112:113], s[48:49], 0, v[112:113]
	v_and_or_b32 v151, v140, s33, v174
	v_lshl_add_u64 v[116:117], s[50:51], 0, v[116:117]
	s_and_b64 vcc, exec, s[58:59]
	s_cbranch_vccz .LBB0_260
	s_cmp_gt_i32 s79, 19
	s_mov_b64 s[56:57], -1
	s_cbranch_scc0 .LBB0_245
	s_cmp_gt_i32 s79, 20
	s_cbranch_scc0 .LBB0_240
	s_and_b32 s33, s67, 0xfffffc
	s_cmp_eq_u32 s33, 4
	s_mov_b32 s33, 0x6300000
	s_cselect_b32 s33, s33, 0xc600000
	s_cmpk_gt_u32 s27, 0x3ff
	s_cselect_b32 s76, s33, 0x4200000
	v_lshl_add_u64 v[142:143], v[112:113], 0, s[76:77]
	v_mov_b32_e32 v139, v153
	v_lshl_add_u64 v[142:143], v[142:143], 0, v[138:139]
	v_mul_f32_e32 v121, 0xbfb8aa3b, v108
	v_mul_f32_e32 v123, 0xbfb8aa3b, v109
	v_mul_f32_e32 v137, 0xbfb8aa3b, v110
	v_mul_f32_e32 v139, 0xbfb8aa3b, v111
	v_exp_f32_e32 v121, v121
	v_exp_f32_e32 v123, v123
	v_exp_f32_e32 v137, v137
	v_exp_f32_e32 v139, v139
	v_add_f32_e32 v121, 1.0, v121
	v_add_f32_e32 v123, 1.0, v123
	v_add_f32_e32 v137, 1.0, v137
	v_add_f32_e32 v139, 1.0, v139
	v_rcp_f32_e32 v121, v121
	v_rcp_f32_e32 v123, v123
	v_rcp_f32_e32 v137, v137
	v_rcp_f32_e32 v139, v139
	v_cvt_pk_bf16_f32 v144, v121, v123
	v_cvt_pk_bf16_f32 v145, v137, v139
	v_mul_f32_e32 v121, 0xbfb8aa3b, v104
	v_mul_f32_e32 v123, 0xbfb8aa3b, v105
	v_mul_f32_e32 v137, 0xbfb8aa3b, v106
	v_mul_f32_e32 v139, 0xbfb8aa3b, v107
	v_exp_f32_e32 v121, v121
	v_exp_f32_e32 v123, v123
	v_exp_f32_e32 v137, v137
	v_exp_f32_e32 v139, v139
	v_add_f32_e32 v121, 1.0, v121
	v_add_f32_e32 v123, 1.0, v123
	v_add_f32_e32 v137, 1.0, v137
	v_add_f32_e32 v139, 1.0, v139
	s_mov_b64 s[56:57], 0
	v_mov_b32_e32 v194, v144
	v_mov_b32_e32 v195, v145
	v_rcp_f32_e32 v121, v121
	v_rcp_f32_e32 v123, v123
	v_rcp_f32_e32 v137, v137
	v_rcp_f32_e32 v139, v139
	v_cvt_pk_bf16_f32 v144, v121, v123
	v_cvt_pk_bf16_f32 v145, v137, v139
	v_mov_b32_e32 v196, v144
	v_mov_b32_e32 v197, v145
	v_lshl_add_u64 v[198:199], v[200:201], 0, v[142:143]
	s_nop 0
	v_permlane16_swap_b32 v194, v196
	v_permlane16_swap_b32 v195, v197
	global_store_dwordx4 v[198:199], v[194:197], off

.LBB0_243:
	s_ashr_i32 s33, s67, 2
	s_add_i32 s33, s33, 2
	v_mad_i64_i32 v[170:171], s[56:57], s33, v154, v[112:113]
	v_mov_b32_e32 v139, v153
	v_lshl_add_u64 v[170:171], v[170:171], 0, v[138:139]
	v_cvt_pk_bf16_f32 v148, v148, v149
	v_cvt_pk_bf16_f32 v149, v144, v145
	v_mov_b32_e32 v194, v148
	v_mov_b32_e32 v195, v149
	v_cvt_pk_bf16_f32 v144, v146, v147
	v_cvt_pk_bf16_f32 v145, v142, v143
	v_mov_b32_e32 v196, v144
	v_mov_b32_e32 v197, v145
	v_lshl_add_u64 v[198:199], v[200:201], 0, v[170:171]
	s_nop 0
	v_permlane16_swap_b32 v194, v196
	v_permlane16_swap_b32 v195, v197
	global_store_dwordx4 v[198:199], v[194:197], off

.LBB0_256:
	s_or_b64 exec, exec, s[56:57]
	s_add_i32 s33, s33, 1
	v_mad_i64_i32 v[170:171], s[56:57], s33, v154, v[112:113]
	v_mov_b32_e32 v139, v153
	v_lshl_add_u64 v[170:171], v[170:171], 0, v[138:139]
	v_cvt_pk_bf16_f32 v144, v144, v145
	v_cvt_pk_bf16_f32 v145, v142, v143
	v_mov_b32_e32 v194, v144
	v_mov_b32_e32 v195, v145
	v_cvt_pk_bf16_f32 v142, v148, v149
	v_cvt_pk_bf16_f32 v143, v146, v147
	v_mov_b32_e32 v196, v142
	v_mov_b32_e32 v197, v143
	v_lshl_add_u64 v[198:199], v[200:201], 0, v[170:171]
	s_nop 0
	v_permlane16_swap_b32 v194, v196
	v_permlane16_swap_b32 v195, v197
	global_store_dwordx4 v[198:199], v[194:197], off

.LBB0_268:
	s_andn2_b64 vcc, exec, s[56:57]
	s_cbranch_vccnz .LBB0_270
	s_ashr_i32 s2, s67, 2
	s_add_i32 s2, s2, 1
	v_mad_i64_i32 v[142:143], s[2:3], s2, v154, v[112:113]
	v_mov_b32_e32 v139, v153
	v_lshl_add_u64 v[142:143], v[142:143], 0, v[138:139]
	v_cvt_pk_f16_f32 v111, v110, v111
	v_cvt_pk_f16_f32 v110, v108, v109
	v_cvt_pk_f16_f32 v107, v106, v107
	v_cvt_pk_f16_f32 v106, v104, v105
	v_mov_b32_e32 v194, v110
	v_mov_b32_e32 v195, v111
	v_mov_b32_e32 v196, v106
	v_mov_b32_e32 v197, v107
	v_lshl_add_u64 v[198:199], v[200:201], 0, v[142:143]
	s_nop 0
	v_permlane16_swap_b32 v194, v196
	v_permlane16_swap_b32 v195, v197
	global_store_dwordx4 v[198:199], v[194:197], off
.LBB0_270:
	s_mov_b64 s[58:59], -1
	s_mov_b64 s[56:57], 0
	s_cmp_lt_i32 s79, 22
	s_mov_b64 s[2:3], 0
	s_cbranch_scc1 .LBB0_295
	s_cmp_gt_i32 s79, 23
	s_cbranch_scc0 .LBB0_289
	s_cmp_gt_i32 s79, 24
	s_cbranch_scc0 .LBB0_286
	s_cmp_gt_i32 s79, 25
	s_cbranch_scc0 .LBB0_277
	s_cmp_eq_u32 s79, 26
	s_mov_b64 s[2:3], -1
	s_cbranch_scc0 .LBB0_276
	v_max_f32_e32 v104, v100, v100
	v_max_f32_e32 v105, v96, v96
	v_max_f32_e32 v104, 0, v104
	v_max_f32_e32 v105, 0, v105
	v_mul_f32_e32 v106, v104, v104
	v_mul_f32_e32 v108, v105, v105
	v_max_f32_e32 v104, v101, v101
	v_max_f32_e32 v105, v97, v97
	v_max_f32_e32 v104, 0, v104
	v_max_f32_e32 v105, 0, v105
	v_mul_f32_e32 v107, v104, v104
	v_mul_f32_e32 v109, v105, v105
	v_max_f32_e32 v104, v102, v102
	v_max_f32_e32 v105, v98, v98
	v_max_f32_e32 v104, 0, v104
	v_max_f32_e32 v105, 0, v105
	v_mul_f32_e32 v110, v104, v104
	v_mul_f32_e32 v111, v105, v105
	v_max_f32_e32 v104, v103, v103
	v_max_f32_e32 v105, v99, v99
	v_max_f32_e32 v104, 0, v104
	v_max_f32_e32 v105, 0, v105
	v_ashrrev_i32_e32 v137, 31, v136
	v_mul_f32_e32 v121, v104, v104
	v_mul_f32_e32 v123, v105, v105
	v_lshl_add_u64 v[104:105], v[136:137], 1, v[124:125]
	v_cvt_pk_bf16_f32 v106, v106, v107
	v_cvt_pk_bf16_f32 v107, v110, v121
	s_mov_b64 s[2:3], 0
	v_mov_b32_e32 v194, v106
	v_mov_b32_e32 v195, v107
	v_cvt_pk_bf16_f32 v106, v108, v109
	v_cvt_pk_bf16_f32 v107, v111, v123
	v_mov_b32_e32 v196, v106
	v_mov_b32_e32 v197, v107
	v_lshl_add_u64 v[198:199], v[200:201], 0, v[104:105]
	s_nop 0
	v_permlane16_swap_b32 v194, v196
	v_permlane16_swap_b32 v195, v197
	global_store_dwordx4 v[198:199], v[194:197], off offset:256

.LBB0_286:
	s_and_b64 vcc, exec, s[58:59]
	s_cbranch_vccz .LBB0_288
	v_ashrrev_i32_e32 v121, 31, v120
	v_lshl_add_u64 v[104:105], v[114:115], 0, v[120:121]
	v_lshlrev_b64 v[104:105], 1, v[104:105]
	v_lshl_add_u64 v[106:107], s[40:41], 0, v[104:105]
	v_lshl_add_u64 v[104:105], s[36:37], 0, v[104:105]
	global_load_dwordx2 v[108:109], v[106:107], off
	global_load_dwordx2 v[124:125], v[104:105], off
	s_waitcnt vmcnt(0)
	v_lshlrev_b32_e32 v110, 16, v108
	v_and_b32_e32 v111, 0xffff0000, v108
	v_lshlrev_b32_e32 v108, 16, v109
	v_and_b32_e32 v109, 0xffff0000, v109
	v_lshlrev_b32_e32 v142, 16, v124
	v_and_b32_e32 v143, 0xffff0000, v124
	v_lshlrev_b32_e32 v124, 16, v125
	v_and_b32_e32 v125, 0xffff0000, v125
	global_load_dwordx2 v[106:107], v[106:107], off offset:32
	v_pk_fma_f32 v[108:109], v[102:103], v[108:109], v[124:125]
	global_load_dwordx2 v[124:125], v[104:105], off offset:32
	v_pk_fma_f32 v[110:111], v[100:101], v[110:111], v[142:143]
	s_waitcnt vmcnt(1)
	v_lshlrev_b32_e32 v118, 16, v106
	v_and_b32_e32 v119, 0xffff0000, v106
	v_lshlrev_b32_e32 v106, 16, v107
	v_and_b32_e32 v107, 0xffff0000, v107
	s_waitcnt vmcnt(0)
	v_lshlrev_b32_e32 v142, 16, v124
	v_and_b32_e32 v143, 0xffff0000, v124
	v_lshlrev_b32_e32 v124, 16, v125
	v_and_b32_e32 v125, 0xffff0000, v125
	v_pk_fma_f32 v[106:107], v[98:99], v[106:107], v[124:125]
	v_pk_fma_f32 v[118:119], v[96:97], v[118:119], v[142:143]
	v_cvt_pk_bf16_f32 v110, v110, v111
	v_cvt_pk_bf16_f32 v111, v108, v109
	v_mov_b32_e32 v194, v110
	v_mov_b32_e32 v195, v111
	v_cvt_pk_bf16_f32 v108, v118, v119
	v_cvt_pk_bf16_f32 v109, v106, v107
	v_mov_b32_e32 v196, v108
	v_mov_b32_e32 v197, v109
	v_lshl_add_u64 v[198:199], v[200:201], 0, v[104:105]
	s_nop 0
	v_permlane16_swap_b32 v194, v196
	v_permlane16_swap_b32 v195, v197
	global_store_dwordx4 v[198:199], v[194:197], off

.LBB0_289:
	s_and_b64 vcc, exec, s[58:59]
	s_cbranch_vccz .LBB0_294
	s_cmp_gt_i32 s79, 22
	s_mov_b64 s[58:59], -1
	s_cbranch_scc0 .LBB0_292
	v_ashrrev_i32_e32 v121, 31, v120
	v_lshl_add_u64 v[104:105], v[114:115], 0, v[120:121]
	v_lshlrev_b64 v[104:105], 1, v[104:105]
	v_lshl_add_u64 v[106:107], s[34:35], 0, v[104:105]
	v_lshl_add_u64 v[104:105], s[36:37], 0, v[104:105]
	global_load_dwordx2 v[108:109], v[106:107], off
	global_load_dwordx2 v[124:125], v[104:105], off
	s_mov_b64 s[58:59], 0
	global_load_dwordx2 v[106:107], v[106:107], off offset:32
	s_waitcnt vmcnt(0)
	v_lshlrev_b32_e32 v110, 16, v108
	v_and_b32_e32 v111, 0xffff0000, v108
	v_lshlrev_b32_e32 v108, 16, v109
	v_and_b32_e32 v109, 0xffff0000, v109
	v_lshlrev_b32_e32 v142, 16, v124
	v_and_b32_e32 v143, 0xffff0000, v124
	v_lshlrev_b32_e32 v124, 16, v125
	v_and_b32_e32 v125, 0xffff0000, v125
	v_pk_fma_f32 v[108:109], v[102:103], v[108:109], v[124:125]
	global_load_dwordx2 v[124:125], v[104:105], off offset:32
	v_lshlrev_b32_e32 v118, 16, v106
	v_and_b32_e32 v119, 0xffff0000, v106
	v_lshlrev_b32_e32 v106, 16, v107
	v_and_b32_e32 v107, 0xffff0000, v107
	v_pk_fma_f32 v[110:111], v[100:101], v[110:111], v[142:143]
	s_waitcnt vmcnt(0)
	v_lshlrev_b32_e32 v142, 16, v124
	v_and_b32_e32 v143, 0xffff0000, v124
	v_lshlrev_b32_e32 v124, 16, v125
	v_and_b32_e32 v125, 0xffff0000, v125
	v_pk_fma_f32 v[106:107], v[98:99], v[106:107], v[124:125]
	v_pk_fma_f32 v[118:119], v[96:97], v[118:119], v[142:143]
	v_cvt_pk_bf16_f32 v110, v110, v111
	v_cvt_pk_bf16_f32 v111, v108, v109
	v_mov_b32_e32 v194, v110
	v_mov_b32_e32 v195, v111
	v_cvt_pk_bf16_f32 v108, v118, v119
	v_cvt_pk_bf16_f32 v109, v106, v107
	v_mov_b32_e32 v196, v108
	v_mov_b32_e32 v197, v109
	v_lshl_add_u64 v[198:199], v[200:201], 0, v[104:105]
	s_nop 0
	v_permlane16_swap_b32 v194, v196
	v_permlane16_swap_b32 v195, v197
	global_store_dwordx4 v[198:199], v[194:197], off
.LBB0_292:
	s_andn2_b64 vcc, exec, s[58:59]
	s_cbranch_vccnz .LBB0_294
	v_ashrrev_i32_e32 v121, 31, v120
	v_lshl_add_u64 v[104:105], v[114:115], 0, v[120:121]
	v_lshlrev_b64 v[104:105], 1, v[104:105]
	v_lshl_add_u64 v[106:107], s[38:39], 0, v[104:105]
	global_load_dwordx2 v[108:109], v[106:107], off
	s_nop 0
	global_load_dwordx2 v[106:107], v[106:107], off offset:32
	v_lshl_add_u64 v[104:105], s[36:37], 0, v[104:105]
	s_waitcnt vmcnt(0)
	v_lshlrev_b32_e32 v110, 16, v108
	v_and_b32_e32 v111, 0xffff0000, v108
	v_lshlrev_b32_e32 v108, 16, v109
	v_and_b32_e32 v109, 0xffff0000, v109
	v_pk_mul_f32 v[110:111], v[100:101], v[110:111]
	v_lshlrev_b32_e32 v114, 16, v106
	v_and_b32_e32 v115, 0xffff0000, v106
	v_lshlrev_b32_e32 v106, 16, v107
	v_and_b32_e32 v107, 0xffff0000, v107
	v_pk_mul_f32 v[108:109], v[102:103], v[108:109]
	v_cvt_pk_bf16_f32 v110, v110, v111
	v_pk_mul_f32 v[106:107], v[98:99], v[106:107]
	v_cvt_pk_bf16_f32 v111, v108, v109
	v_pk_mul_f32 v[114:115], v[96:97], v[114:115]
	v_cvt_pk_bf16_f32 v109, v106, v107
	s_nop 0
	v_cvt_pk_bf16_f32 v108, v114, v115
	v_mov_b32_e32 v194, v110
	v_mov_b32_e32 v195, v111
	v_mov_b32_e32 v196, v108
	v_mov_b32_e32 v197, v109
	v_lshl_add_u64 v[198:199], v[200:201], 0, v[104:105]
	s_nop 0
	v_permlane16_swap_b32 v194, v196
	v_permlane16_swap_b32 v195, v197
	global_store_dwordx4 v[198:199], v[194:197], off

.LBB0_302:
	s_ashr_i32 s33, s67, 2
	s_add_i32 s33, s33, 2
	v_mad_i64_i32 v[114:115], s[56:57], s33, v154, v[112:113]
	v_mov_b32_e32 v123, v153
	v_lshl_add_u64 v[114:115], v[114:115], 0, v[122:123]
	v_cvt_pk_bf16_f32 v110, v110, v111
	v_cvt_pk_bf16_f32 v111, v106, v107
	v_mov_b32_e32 v194, v110
	v_mov_b32_e32 v195, v111
	v_cvt_pk_bf16_f32 v106, v108, v109
	v_cvt_pk_bf16_f32 v107, v104, v105
	v_mov_b32_e32 v196, v106
	v_mov_b32_e32 v197, v107
	v_lshl_add_u64 v[198:199], v[200:201], 0, v[114:115]
	s_nop 0
	v_permlane16_swap_b32 v194, v196
	v_permlane16_swap_b32 v195, v197
	global_store_dwordx4 v[198:199], v[194:197], off

.LBB0_315:
	s_or_b64 exec, exec, s[56:57]
	s_add_i32 s33, s33, 1
	v_mad_i64_i32 v[114:115], s[10:11], s33, v154, v[112:113]
	v_mov_b32_e32 v123, v153
	v_lshl_add_u64 v[114:115], v[114:115], 0, v[122:123]
	v_cvt_pk_bf16_f32 v106, v106, v107
	v_cvt_pk_bf16_f32 v107, v104, v105
	v_mov_b32_e32 v194, v106
	v_mov_b32_e32 v195, v107
	v_cvt_pk_bf16_f32 v104, v110, v111
	v_cvt_pk_bf16_f32 v105, v108, v109
	v_mov_b32_e32 v196, v104
	v_mov_b32_e32 v197, v105
	v_lshl_add_u64 v[198:199], v[200:201], 0, v[114:115]
	s_nop 0
	v_permlane16_swap_b32 v194, v196
	v_permlane16_swap_b32 v195, v197
	global_store_dwordx4 v[198:199], v[194:197], off

.LBB0_327:
	s_andn2_b64 vcc, exec, s[56:57]
	s_cbranch_vccnz .LBB0_329
	s_ashr_i32 s2, s67, 2
	s_add_i32 s2, s2, 1
	v_mad_i64_i32 v[104:105], s[2:3], s2, v154, v[112:113]
	v_mov_b32_e32 v123, v153
	v_lshl_add_u64 v[104:105], v[104:105], 0, v[122:123]
	v_cvt_pk_f16_f32 v103, v102, v103
	v_cvt_pk_f16_f32 v102, v100, v101
	v_cvt_pk_f16_f32 v99, v98, v99
	v_cvt_pk_f16_f32 v98, v96, v97
	v_mov_b32_e32 v194, v102
	v_mov_b32_e32 v195, v103
	v_mov_b32_e32 v196, v98
	v_mov_b32_e32 v197, v99
	v_lshl_add_u64 v[198:199], v[200:201], 0, v[104:105]
	s_nop 0
	v_permlane16_swap_b32 v194, v196
	v_permlane16_swap_b32 v195, v197
	global_store_dwordx4 v[198:199], v[194:197], off
.LBB0_329:
	v_or_b32_e32 v108, s62, v176
	v_ashrrev_i32_e32 v109, 31, v108
	v_lshlrev_b64 v[96:97], 13, v[108:109]
	v_add_u32_e32 v106, 0xffffc000, v108
	v_mov_b32_e32 v107, v153
	v_lshl_add_u64 v[104:105], s[52:53], 0, v[96:97]
	v_cmp_gt_i32_e64 s[10:11], s92, v108
	v_cmp_lt_i32_e64 s[8:9], s80, v108
	v_lshlrev_b64 v[102:103], 10, v[106:107]
	v_lshlrev_b64 v[98:99], 10, v[108:109]
	s_mov_b64 s[58:59], -1
	s_mov_b64 s[56:57], 0
	s_cmp_lt_i32 s79, 22
	s_mov_b64 s[2:3], 0
	s_cbranch_scc1 .LBB0_354
	s_cmp_gt_i32 s79, 23
	s_cbranch_scc0 .LBB0_348
	s_cmp_gt_i32 s79, 24
	s_cbranch_scc0 .LBB0_345
	s_cmp_gt_i32 s79, 25
	s_cbranch_scc0 .LBB0_336
	s_cmp_eq_u32 s79, 26
	s_mov_b64 s[2:3], -1
	s_cbranch_scc0 .LBB0_335
	v_max_f32_e32 v96, v92, v92
	v_max_f32_e32 v97, v88, v88
	v_max_f32_e32 v96, 0, v96
	v_max_f32_e32 v97, 0, v97
	v_mul_f32_e32 v100, v96, v96
	v_mul_f32_e32 v110, v97, v97
	v_max_f32_e32 v96, v93, v93
	v_max_f32_e32 v97, v89, v89
	v_max_f32_e32 v96, 0, v96
	v_max_f32_e32 v97, 0, v97
	v_mul_f32_e32 v101, v96, v96
	v_mul_f32_e32 v111, v97, v97
	v_max_f32_e32 v96, v94, v94
	v_max_f32_e32 v97, v90, v90
	v_max_f32_e32 v96, 0, v96
	v_max_f32_e32 v97, 0, v97
	v_mul_f32_e32 v112, v96, v96
	v_mul_f32_e32 v113, v97, v97
	v_max_f32_e32 v96, v95, v95
	v_max_f32_e32 v97, v91, v91
	v_max_f32_e32 v96, 0, v96
	v_max_f32_e32 v97, 0, v97
	v_ashrrev_i32_e32 v137, 31, v136
	v_mul_f32_e32 v114, v96, v96
	v_mul_f32_e32 v115, v97, v97
	v_lshl_add_u64 v[96:97], v[136:137], 1, v[104:105]
	v_cvt_pk_bf16_f32 v100, v100, v101
	v_cvt_pk_bf16_f32 v101, v112, v114
	s_mov_b64 s[2:3], 0
	v_mov_b32_e32 v194, v100
	v_mov_b32_e32 v195, v101
	v_cvt_pk_bf16_f32 v100, v110, v111
	v_cvt_pk_bf16_f32 v101, v113, v115
	v_mov_b32_e32 v196, v100
	v_mov_b32_e32 v197, v101
	v_lshl_add_u64 v[198:199], v[200:201], 0, v[96:97]
	s_nop 0
	v_permlane16_swap_b32 v194, v196
	v_permlane16_swap_b32 v195, v197
	global_store_dwordx4 v[198:199], v[194:197], off

.LBB0_345:
	s_and_b64 vcc, exec, s[58:59]
	s_cbranch_vccz .LBB0_347
	v_ashrrev_i32_e32 v137, 31, v136
	v_lshl_add_u64 v[96:97], v[98:99], 0, v[136:137]
	v_lshlrev_b64 v[96:97], 1, v[96:97]
	v_lshl_add_u64 v[100:101], s[40:41], 0, v[96:97]
	v_lshl_add_u64 v[96:97], s[36:37], 0, v[96:97]
	global_load_dwordx2 v[110:111], v[100:101], off
	global_load_dwordx2 v[116:117], v[96:97], off
	s_waitcnt vmcnt(0)
	v_lshlrev_b32_e32 v112, 16, v110
	v_and_b32_e32 v113, 0xffff0000, v110
	v_lshlrev_b32_e32 v110, 16, v111
	v_and_b32_e32 v111, 0xffff0000, v111
	v_lshlrev_b32_e32 v118, 16, v116
	v_and_b32_e32 v119, 0xffff0000, v116
	v_lshlrev_b32_e32 v116, 16, v117
	v_and_b32_e32 v117, 0xffff0000, v117
	global_load_dwordx2 v[100:101], v[100:101], off offset:32
	v_pk_fma_f32 v[110:111], v[94:95], v[110:111], v[116:117]
	global_load_dwordx2 v[116:117], v[96:97], off offset:32
	v_pk_fma_f32 v[112:113], v[92:93], v[112:113], v[118:119]
	s_waitcnt vmcnt(1)
	v_lshlrev_b32_e32 v114, 16, v100
	v_and_b32_e32 v115, 0xffff0000, v100
	v_lshlrev_b32_e32 v100, 16, v101
	v_and_b32_e32 v101, 0xffff0000, v101
	s_waitcnt vmcnt(0)
	v_lshlrev_b32_e32 v118, 16, v116
	v_and_b32_e32 v119, 0xffff0000, v116
	v_lshlrev_b32_e32 v116, 16, v117
	v_and_b32_e32 v117, 0xffff0000, v117
	v_pk_fma_f32 v[100:101], v[90:91], v[100:101], v[116:117]
	v_pk_fma_f32 v[114:115], v[88:89], v[114:115], v[118:119]
	v_cvt_pk_bf16_f32 v112, v112, v113
	v_cvt_pk_bf16_f32 v113, v110, v111
	v_mov_b32_e32 v194, v112
	v_mov_b32_e32 v195, v113
	v_cvt_pk_bf16_f32 v110, v114, v115
	v_cvt_pk_bf16_f32 v111, v100, v101
	v_mov_b32_e32 v196, v110
	v_mov_b32_e32 v197, v111
	v_lshl_add_u64 v[198:199], v[200:201], 0, v[96:97]
	s_nop 0
	v_permlane16_swap_b32 v194, v196
	v_permlane16_swap_b32 v195, v197
	global_store_dwordx4 v[198:199], v[194:197], off

.LBB0_348:
	s_and_b64 vcc, exec, s[58:59]
	s_cbranch_vccz .LBB0_353
	s_cmp_gt_i32 s79, 22
	s_mov_b64 s[58:59], -1
	s_cbranch_scc0 .LBB0_351
	v_ashrrev_i32_e32 v137, 31, v136
	v_lshl_add_u64 v[96:97], v[98:99], 0, v[136:137]
	v_lshlrev_b64 v[96:97], 1, v[96:97]
	v_lshl_add_u64 v[100:101], s[34:35], 0, v[96:97]
	v_lshl_add_u64 v[96:97], s[36:37], 0, v[96:97]
	global_load_dwordx2 v[110:111], v[100:101], off
	global_load_dwordx2 v[116:117], v[96:97], off
	s_mov_b64 s[58:59], 0
	global_load_dwordx2 v[100:101], v[100:101], off offset:32
	s_waitcnt vmcnt(0)
	v_lshlrev_b32_e32 v112, 16, v110
	v_and_b32_e32 v113, 0xffff0000, v110
	v_lshlrev_b32_e32 v110, 16, v111
	v_and_b32_e32 v111, 0xffff0000, v111
	v_lshlrev_b32_e32 v118, 16, v116
	v_and_b32_e32 v119, 0xffff0000, v116
	v_lshlrev_b32_e32 v116, 16, v117
	v_and_b32_e32 v117, 0xffff0000, v117
	v_pk_fma_f32 v[110:111], v[94:95], v[110:111], v[116:117]
	global_load_dwordx2 v[116:117], v[96:97], off offset:32
	v_lshlrev_b32_e32 v114, 16, v100
	v_and_b32_e32 v115, 0xffff0000, v100
	v_lshlrev_b32_e32 v100, 16, v101
	v_and_b32_e32 v101, 0xffff0000, v101
	v_pk_fma_f32 v[112:113], v[92:93], v[112:113], v[118:119]
	s_waitcnt vmcnt(0)
	v_lshlrev_b32_e32 v118, 16, v116
	v_and_b32_e32 v119, 0xffff0000, v116
	v_lshlrev_b32_e32 v116, 16, v117
	v_and_b32_e32 v117, 0xffff0000, v117
	v_pk_fma_f32 v[100:101], v[90:91], v[100:101], v[116:117]
	v_pk_fma_f32 v[114:115], v[88:89], v[114:115], v[118:119]
	v_cvt_pk_bf16_f32 v112, v112, v113
	v_cvt_pk_bf16_f32 v113, v110, v111
	v_mov_b32_e32 v194, v112
	v_mov_b32_e32 v195, v113
	v_cvt_pk_bf16_f32 v110, v114, v115
	v_cvt_pk_bf16_f32 v111, v100, v101
	v_mov_b32_e32 v196, v110
	v_mov_b32_e32 v197, v111
	v_lshl_add_u64 v[198:199], v[200:201], 0, v[96:97]
	s_nop 0
	v_permlane16_swap_b32 v194, v196
	v_permlane16_swap_b32 v195, v197
	global_store_dwordx4 v[198:199], v[194:197], off
.LBB0_351:
	s_andn2_b64 vcc, exec, s[58:59]
	s_cbranch_vccnz .LBB0_353
	v_ashrrev_i32_e32 v137, 31, v136
	v_lshl_add_u64 v[96:97], v[98:99], 0, v[136:137]
	v_lshlrev_b64 v[96:97], 1, v[96:97]
	v_lshl_add_u64 v[100:101], s[38:39], 0, v[96:97]
	global_load_dwordx2 v[110:111], v[100:101], off
	s_nop 0
	global_load_dwordx2 v[100:101], v[100:101], off offset:32
	v_lshl_add_u64 v[96:97], s[36:37], 0, v[96:97]
	s_waitcnt vmcnt(0)
	v_lshlrev_b32_e32 v112, 16, v110
	v_and_b32_e32 v113, 0xffff0000, v110
	v_lshlrev_b32_e32 v110, 16, v111
	v_and_b32_e32 v111, 0xffff0000, v111
	v_pk_mul_f32 v[112:113], v[92:93], v[112:113]
	v_lshlrev_b32_e32 v114, 16, v100
	v_and_b32_e32 v115, 0xffff0000, v100
	v_lshlrev_b32_e32 v100, 16, v101
	v_and_b32_e32 v101, 0xffff0000, v101
	v_pk_mul_f32 v[110:111], v[94:95], v[110:111]
	v_cvt_pk_bf16_f32 v112, v112, v113
	v_pk_mul_f32 v[100:101], v[90:91], v[100:101]
	v_cvt_pk_bf16_f32 v113, v110, v111
	v_pk_mul_f32 v[114:115], v[88:89], v[114:115]
	v_cvt_pk_bf16_f32 v111, v100, v101
	s_nop 0
	v_cvt_pk_bf16_f32 v110, v114, v115
	v_mov_b32_e32 v194, v112
	v_mov_b32_e32 v195, v113
	v_mov_b32_e32 v196, v110
	v_mov_b32_e32 v197, v111
	v_lshl_add_u64 v[198:199], v[200:201], 0, v[96:97]
	s_nop 0
	v_permlane16_swap_b32 v194, v196
	v_permlane16_swap_b32 v195, v197
	global_store_dwordx4 v[198:199], v[194:197], off

.LBB0_361:
	s_ashr_i32 s33, s67, 2
	s_add_i32 s33, s33, 2
	v_mad_i64_i32 v[124:125], s[56:57], s33, v154, v[96:97]
	v_mov_b32_e32 v139, v153
	v_lshl_add_u64 v[124:125], v[124:125], 0, v[138:139]
	v_cvt_pk_bf16_f32 v116, v116, v117
	v_cvt_pk_bf16_f32 v117, v112, v113
	v_mov_b32_e32 v194, v116
	v_mov_b32_e32 v195, v117
	v_cvt_pk_bf16_f32 v112, v114, v115
	v_cvt_pk_bf16_f32 v113, v110, v111
	v_mov_b32_e32 v196, v112
	v_mov_b32_e32 v197, v113
	v_lshl_add_u64 v[198:199], v[200:201], 0, v[124:125]
	s_nop 0
	v_permlane16_swap_b32 v194, v196
	v_permlane16_swap_b32 v195, v197
	global_store_dwordx4 v[198:199], v[194:197], off

.LBB0_374:
	s_or_b64 exec, exec, s[56:57]
	s_add_i32 s33, s33, 1
	v_mad_i64_i32 v[124:125], s[56:57], s33, v154, v[96:97]
	v_mov_b32_e32 v139, v153
	v_lshl_add_u64 v[124:125], v[124:125], 0, v[138:139]
	v_cvt_pk_bf16_f32 v112, v112, v113
	v_cvt_pk_bf16_f32 v113, v110, v111
	v_mov_b32_e32 v194, v112
	v_mov_b32_e32 v195, v113
	v_cvt_pk_bf16_f32 v110, v116, v117
	v_cvt_pk_bf16_f32 v111, v114, v115
	v_mov_b32_e32 v196, v110
	v_mov_b32_e32 v197, v111
	v_lshl_add_u64 v[198:199], v[200:201], 0, v[124:125]
	s_nop 0
	v_permlane16_swap_b32 v194, v196
	v_permlane16_swap_b32 v195, v197
	global_store_dwordx4 v[198:199], v[194:197], off

.LBB0_386:
	s_andn2_b64 vcc, exec, s[56:57]
	s_cbranch_vccnz .LBB0_388
	s_ashr_i32 s2, s67, 2
	s_add_i32 s2, s2, 1
	v_mad_i64_i32 v[110:111], s[2:3], s2, v154, v[96:97]
	v_mov_b32_e32 v139, v153
	v_lshl_add_u64 v[110:111], v[110:111], 0, v[138:139]
	v_cvt_pk_f16_f32 v95, v94, v95
	v_cvt_pk_f16_f32 v94, v92, v93
	v_cvt_pk_f16_f32 v91, v90, v91
	v_cvt_pk_f16_f32 v90, v88, v89
	v_mov_b32_e32 v194, v94
	v_mov_b32_e32 v195, v95
	v_mov_b32_e32 v196, v90
	v_mov_b32_e32 v197, v91
	v_lshl_add_u64 v[198:199], v[200:201], 0, v[110:111]
	s_nop 0
	v_permlane16_swap_b32 v194, v196
	v_permlane16_swap_b32 v195, v197
	global_store_dwordx4 v[198:199], v[194:197], off
.LBB0_388:
	s_mov_b64 s[58:59], -1
	s_mov_b64 s[56:57], 0
	s_cmp_lt_i32 s79, 22
	s_mov_b64 s[2:3], 0
	s_cbranch_scc1 .LBB0_413
	s_cmp_gt_i32 s79, 23
	s_cbranch_scc0 .LBB0_407
	s_cmp_gt_i32 s79, 24
	s_cbranch_scc0 .LBB0_404
	s_cmp_gt_i32 s79, 25
	s_cbranch_scc0 .LBB0_395
	s_cmp_eq_u32 s79, 26
	s_mov_b64 s[2:3], -1
	s_cbranch_scc0 .LBB0_394
	v_max_f32_e32 v88, v84, v84
	v_max_f32_e32 v89, v80, v80
	v_max_f32_e32 v88, 0, v88
	v_max_f32_e32 v89, 0, v89
	v_mul_f32_e32 v90, v88, v88
	v_mul_f32_e32 v92, v89, v89
	v_max_f32_e32 v88, v85, v85
	v_max_f32_e32 v89, v81, v81
	v_max_f32_e32 v88, 0, v88
	v_max_f32_e32 v89, 0, v89
	v_mul_f32_e32 v91, v88, v88
	v_mul_f32_e32 v93, v89, v89
	v_max_f32_e32 v88, v86, v86
	v_max_f32_e32 v89, v82, v82
	v_max_f32_e32 v88, 0, v88
	v_max_f32_e32 v89, 0, v89
	v_mul_f32_e32 v94, v88, v88
	v_mul_f32_e32 v95, v89, v89
	v_max_f32_e32 v88, v87, v87
	v_max_f32_e32 v89, v83, v83
	v_max_f32_e32 v88, 0, v88
	v_max_f32_e32 v89, 0, v89
	v_ashrrev_i32_e32 v137, 31, v136
	v_mul_f32_e32 v110, v88, v88
	v_mul_f32_e32 v111, v89, v89
	v_lshl_add_u64 v[88:89], v[136:137], 1, v[104:105]
	v_cvt_pk_bf16_f32 v90, v90, v91
	v_cvt_pk_bf16_f32 v91, v94, v110
	s_mov_b64 s[2:3], 0
	v_mov_b32_e32 v194, v90
	v_mov_b32_e32 v195, v91
	v_cvt_pk_bf16_f32 v90, v92, v93
	v_cvt_pk_bf16_f32 v91, v95, v111
	v_mov_b32_e32 v196, v90
	v_mov_b32_e32 v197, v91
	v_lshl_add_u64 v[198:199], v[200:201], 0, v[88:89]
	s_nop 0
	v_permlane16_swap_b32 v194, v196
	v_permlane16_swap_b32 v195, v197
	global_store_dwordx4 v[198:199], v[194:197], off offset:256

.LBB0_404:
	s_and_b64 vcc, exec, s[58:59]
	s_cbranch_vccz .LBB0_406
	v_ashrrev_i32_e32 v121, 31, v120
	v_lshl_add_u64 v[88:89], v[98:99], 0, v[120:121]
	v_lshlrev_b64 v[88:89], 1, v[88:89]
	v_lshl_add_u64 v[90:91], s[40:41], 0, v[88:89]
	v_lshl_add_u64 v[88:89], s[36:37], 0, v[88:89]
	global_load_dwordx2 v[92:93], v[90:91], off
	global_load_dwordx2 v[104:105], v[88:89], off
	s_waitcnt vmcnt(0)
	v_lshlrev_b32_e32 v94, 16, v92
	v_and_b32_e32 v95, 0xffff0000, v92
	v_lshlrev_b32_e32 v92, 16, v93
	v_and_b32_e32 v93, 0xffff0000, v93
	v_lshlrev_b32_e32 v110, 16, v104
	v_and_b32_e32 v111, 0xffff0000, v104
	v_lshlrev_b32_e32 v104, 16, v105
	v_and_b32_e32 v105, 0xffff0000, v105
	global_load_dwordx2 v[90:91], v[90:91], off offset:32
	v_pk_fma_f32 v[92:93], v[86:87], v[92:93], v[104:105]
	global_load_dwordx2 v[104:105], v[88:89], off offset:32
	v_pk_fma_f32 v[94:95], v[84:85], v[94:95], v[110:111]
	s_waitcnt vmcnt(1)
	v_lshlrev_b32_e32 v102, 16, v90
	v_and_b32_e32 v103, 0xffff0000, v90
	v_lshlrev_b32_e32 v90, 16, v91
	v_and_b32_e32 v91, 0xffff0000, v91
	s_waitcnt vmcnt(0)
	v_lshlrev_b32_e32 v110, 16, v104
	v_and_b32_e32 v111, 0xffff0000, v104
	v_lshlrev_b32_e32 v104, 16, v105
	v_and_b32_e32 v105, 0xffff0000, v105
	v_pk_fma_f32 v[90:91], v[82:83], v[90:91], v[104:105]
	v_pk_fma_f32 v[102:103], v[80:81], v[102:103], v[110:111]
	v_cvt_pk_bf16_f32 v94, v94, v95
	v_cvt_pk_bf16_f32 v95, v92, v93
	v_mov_b32_e32 v194, v94
	v_mov_b32_e32 v195, v95
	v_cvt_pk_bf16_f32 v92, v102, v103
	v_cvt_pk_bf16_f32 v93, v90, v91
	v_mov_b32_e32 v196, v92
	v_mov_b32_e32 v197, v93
	v_lshl_add_u64 v[198:199], v[200:201], 0, v[88:89]
	s_nop 0
	v_permlane16_swap_b32 v194, v196
	v_permlane16_swap_b32 v195, v197
	global_store_dwordx4 v[198:199], v[194:197], off

.LBB0_407:
	s_and_b64 vcc, exec, s[58:59]
	s_cbranch_vccz .LBB0_412
	s_cmp_gt_i32 s79, 22
	s_mov_b64 s[58:59], -1
	s_cbranch_scc0 .LBB0_410
	v_ashrrev_i32_e32 v121, 31, v120
	v_lshl_add_u64 v[88:89], v[98:99], 0, v[120:121]
	v_lshlrev_b64 v[88:89], 1, v[88:89]
	v_lshl_add_u64 v[90:91], s[34:35], 0, v[88:89]
	v_lshl_add_u64 v[88:89], s[36:37], 0, v[88:89]
	global_load_dwordx2 v[92:93], v[90:91], off
	global_load_dwordx2 v[104:105], v[88:89], off
	s_mov_b64 s[58:59], 0
	global_load_dwordx2 v[90:91], v[90:91], off offset:32
	s_waitcnt vmcnt(0)
	v_lshlrev_b32_e32 v94, 16, v92
	v_and_b32_e32 v95, 0xffff0000, v92
	v_lshlrev_b32_e32 v92, 16, v93
	v_and_b32_e32 v93, 0xffff0000, v93
	v_lshlrev_b32_e32 v110, 16, v104
	v_and_b32_e32 v111, 0xffff0000, v104
	v_lshlrev_b32_e32 v104, 16, v105
	v_and_b32_e32 v105, 0xffff0000, v105
	v_pk_fma_f32 v[92:93], v[86:87], v[92:93], v[104:105]
	global_load_dwordx2 v[104:105], v[88:89], off offset:32
	v_lshlrev_b32_e32 v102, 16, v90
	v_and_b32_e32 v103, 0xffff0000, v90
	v_lshlrev_b32_e32 v90, 16, v91
	v_and_b32_e32 v91, 0xffff0000, v91
	v_pk_fma_f32 v[94:95], v[84:85], v[94:95], v[110:111]
	s_waitcnt vmcnt(0)
	v_lshlrev_b32_e32 v110, 16, v104
	v_and_b32_e32 v111, 0xffff0000, v104
	v_lshlrev_b32_e32 v104, 16, v105
	v_and_b32_e32 v105, 0xffff0000, v105
	v_pk_fma_f32 v[90:91], v[82:83], v[90:91], v[104:105]
	v_pk_fma_f32 v[102:103], v[80:81], v[102:103], v[110:111]
	v_cvt_pk_bf16_f32 v94, v94, v95
	v_cvt_pk_bf16_f32 v95, v92, v93
	v_mov_b32_e32 v194, v94
	v_mov_b32_e32 v195, v95
	v_cvt_pk_bf16_f32 v92, v102, v103
	v_cvt_pk_bf16_f32 v93, v90, v91
	v_mov_b32_e32 v196, v92
	v_mov_b32_e32 v197, v93
	v_lshl_add_u64 v[198:199], v[200:201], 0, v[88:89]
	s_nop 0
	v_permlane16_swap_b32 v194, v196
	v_permlane16_swap_b32 v195, v197
	global_store_dwordx4 v[198:199], v[194:197], off
.LBB0_410:
	s_andn2_b64 vcc, exec, s[58:59]
	s_cbranch_vccnz .LBB0_412
	v_ashrrev_i32_e32 v121, 31, v120
	v_lshl_add_u64 v[88:89], v[98:99], 0, v[120:121]
	v_lshlrev_b64 v[88:89], 1, v[88:89]
	v_lshl_add_u64 v[90:91], s[38:39], 0, v[88:89]
	global_load_dwordx2 v[92:93], v[90:91], off
	s_nop 0
	global_load_dwordx2 v[90:91], v[90:91], off offset:32
	v_lshl_add_u64 v[88:89], s[36:37], 0, v[88:89]
	s_waitcnt vmcnt(0)
	v_lshlrev_b32_e32 v94, 16, v92
	v_and_b32_e32 v95, 0xffff0000, v92
	v_lshlrev_b32_e32 v92, 16, v93
	v_and_b32_e32 v93, 0xffff0000, v93
	v_pk_mul_f32 v[94:95], v[84:85], v[94:95]
	v_lshlrev_b32_e32 v98, 16, v90
	v_and_b32_e32 v99, 0xffff0000, v90
	v_lshlrev_b32_e32 v90, 16, v91
	v_and_b32_e32 v91, 0xffff0000, v91
	v_pk_mul_f32 v[92:93], v[86:87], v[92:93]
	v_cvt_pk_bf16_f32 v94, v94, v95
	v_pk_mul_f32 v[90:91], v[82:83], v[90:91]
	v_cvt_pk_bf16_f32 v95, v92, v93
	v_pk_mul_f32 v[98:99], v[80:81], v[98:99]
	v_cvt_pk_bf16_f32 v93, v90, v91
	s_nop 0
	v_cvt_pk_bf16_f32 v92, v98, v99
	v_mov_b32_e32 v194, v94
	v_mov_b32_e32 v195, v95
	v_mov_b32_e32 v196, v92
	v_mov_b32_e32 v197, v93
	v_lshl_add_u64 v[198:199], v[200:201], 0, v[88:89]
	s_nop 0
	v_permlane16_swap_b32 v194, v196
	v_permlane16_swap_b32 v195, v197
	global_store_dwordx4 v[198:199], v[194:197], off

.LBB0_420:
	s_ashr_i32 s33, s67, 2
	s_add_i32 s33, s33, 2
	v_mad_i64_i32 v[98:99], s[56:57], s33, v154, v[96:97]
	v_mov_b32_e32 v123, v153
	v_lshl_add_u64 v[98:99], v[98:99], 0, v[122:123]
	v_cvt_pk_bf16_f32 v94, v94, v95
	v_cvt_pk_bf16_f32 v95, v90, v91
	v_mov_b32_e32 v194, v94
	v_mov_b32_e32 v195, v95
	v_cvt_pk_bf16_f32 v90, v92, v93
	v_cvt_pk_bf16_f32 v91, v88, v89
	v_mov_b32_e32 v196, v90
	v_mov_b32_e32 v197, v91
	v_lshl_add_u64 v[198:199], v[200:201], 0, v[98:99]
	s_nop 0
	v_permlane16_swap_b32 v194, v196
	v_permlane16_swap_b32 v195, v197
	global_store_dwordx4 v[198:199], v[194:197], off

.LBB0_433:
	s_or_b64 exec, exec, s[56:57]
	s_add_i32 s33, s33, 1
	v_mad_i64_i32 v[98:99], s[10:11], s33, v154, v[96:97]
	v_mov_b32_e32 v123, v153
	v_lshl_add_u64 v[98:99], v[98:99], 0, v[122:123]
	v_cvt_pk_bf16_f32 v90, v90, v91
	v_cvt_pk_bf16_f32 v91, v88, v89
	v_mov_b32_e32 v194, v90
	v_mov_b32_e32 v195, v91
	v_cvt_pk_bf16_f32 v88, v94, v95
	v_cvt_pk_bf16_f32 v89, v92, v93
	v_mov_b32_e32 v196, v88
	v_mov_b32_e32 v197, v89
	v_lshl_add_u64 v[198:199], v[200:201], 0, v[98:99]
	s_nop 0
	v_permlane16_swap_b32 v194, v196
	v_permlane16_swap_b32 v195, v197
	global_store_dwordx4 v[198:199], v[194:197], off

.LBB0_445:
	s_andn2_b64 vcc, exec, s[56:57]
	s_cbranch_vccnz .LBB0_447
	s_ashr_i32 s2, s67, 2
	s_add_i32 s2, s2, 1
	v_mad_i64_i32 v[88:89], s[2:3], s2, v154, v[96:97]
	v_mov_b32_e32 v123, v153
	v_lshl_add_u64 v[88:89], v[88:89], 0, v[122:123]
	v_cvt_pk_f16_f32 v87, v86, v87
	v_cvt_pk_f16_f32 v86, v84, v85
	v_cvt_pk_f16_f32 v83, v82, v83
	v_cvt_pk_f16_f32 v82, v80, v81
	v_mov_b32_e32 v194, v86
	v_mov_b32_e32 v195, v87
	v_mov_b32_e32 v196, v82
	v_mov_b32_e32 v197, v83
	v_lshl_add_u64 v[198:199], v[200:201], 0, v[88:89]
	s_nop 0
	v_permlane16_swap_b32 v194, v196
	v_permlane16_swap_b32 v195, v197
	global_store_dwordx4 v[198:199], v[194:197], off
.LBB0_447:
	v_or_b32_e32 v92, s62, v177
	v_ashrrev_i32_e32 v93, 31, v92
	v_lshlrev_b64 v[80:81], 13, v[92:93]
	v_add_u32_e32 v90, 0xffffc000, v92
	v_mov_b32_e32 v91, v153
	v_lshl_add_u64 v[88:89], s[52:53], 0, v[80:81]
	v_cmp_gt_i32_e64 s[10:11], s92, v92
	v_cmp_lt_i32_e64 s[8:9], s80, v92
	v_lshlrev_b64 v[86:87], 10, v[90:91]
	v_lshlrev_b64 v[82:83], 10, v[92:93]
	s_mov_b64 s[58:59], -1
	s_mov_b64 s[56:57], 0
	s_cmp_lt_i32 s79, 22
	s_mov_b64 s[2:3], 0
	s_cbranch_scc1 .LBB0_472
	s_cmp_gt_i32 s79, 23
	s_cbranch_scc0 .LBB0_466
	s_cmp_gt_i32 s79, 24
	s_cbranch_scc0 .LBB0_463
	s_cmp_gt_i32 s79, 25
	s_cbranch_scc0 .LBB0_454
	s_cmp_eq_u32 s79, 26
	s_mov_b64 s[2:3], -1
	s_cbranch_scc0 .LBB0_453
	v_max_f32_e32 v80, v76, v76
	v_max_f32_e32 v81, v72, v72
	v_max_f32_e32 v80, 0, v80
	v_max_f32_e32 v81, 0, v81
	v_mul_f32_e32 v84, v80, v80
	v_mul_f32_e32 v94, v81, v81
	v_max_f32_e32 v80, v77, v77
	v_max_f32_e32 v81, v73, v73
	v_max_f32_e32 v80, 0, v80
	v_max_f32_e32 v81, 0, v81
	v_mul_f32_e32 v85, v80, v80
	v_mul_f32_e32 v95, v81, v81
	v_max_f32_e32 v80, v78, v78
	v_max_f32_e32 v81, v74, v74
	v_max_f32_e32 v80, 0, v80
	v_max_f32_e32 v81, 0, v81
	v_mul_f32_e32 v96, v80, v80
	v_mul_f32_e32 v97, v81, v81
	v_max_f32_e32 v80, v79, v79
	v_max_f32_e32 v81, v75, v75
	v_max_f32_e32 v80, 0, v80
	v_max_f32_e32 v81, 0, v81
	v_ashrrev_i32_e32 v137, 31, v136
	v_mul_f32_e32 v98, v80, v80
	v_mul_f32_e32 v99, v81, v81
	v_lshl_add_u64 v[80:81], v[136:137], 1, v[88:89]
	v_cvt_pk_bf16_f32 v84, v84, v85
	v_cvt_pk_bf16_f32 v85, v96, v98
	s_mov_b64 s[2:3], 0
	v_mov_b32_e32 v194, v84
	v_mov_b32_e32 v195, v85
	v_cvt_pk_bf16_f32 v84, v94, v95
	v_cvt_pk_bf16_f32 v85, v97, v99
	v_mov_b32_e32 v196, v84
	v_mov_b32_e32 v197, v85
	v_lshl_add_u64 v[198:199], v[200:201], 0, v[80:81]
	s_nop 0
	v_permlane16_swap_b32 v194, v196
	v_permlane16_swap_b32 v195, v197
	global_store_dwordx4 v[198:199], v[194:197], off

.LBB0_463:
	s_and_b64 vcc, exec, s[58:59]
	s_cbranch_vccz .LBB0_465
	v_ashrrev_i32_e32 v137, 31, v136
	v_lshl_add_u64 v[80:81], v[82:83], 0, v[136:137]
	v_lshlrev_b64 v[80:81], 1, v[80:81]
	v_lshl_add_u64 v[84:85], s[40:41], 0, v[80:81]
	v_lshl_add_u64 v[80:81], s[36:37], 0, v[80:81]
	global_load_dwordx2 v[94:95], v[84:85], off
	global_load_dwordx2 v[100:101], v[80:81], off
	s_waitcnt vmcnt(0)
	v_lshlrev_b32_e32 v96, 16, v94
	v_and_b32_e32 v97, 0xffff0000, v94
	v_lshlrev_b32_e32 v94, 16, v95
	v_and_b32_e32 v95, 0xffff0000, v95
	v_lshlrev_b32_e32 v102, 16, v100
	v_and_b32_e32 v103, 0xffff0000, v100
	v_lshlrev_b32_e32 v100, 16, v101
	v_and_b32_e32 v101, 0xffff0000, v101
	global_load_dwordx2 v[84:85], v[84:85], off offset:32
	v_pk_fma_f32 v[94:95], v[78:79], v[94:95], v[100:101]
	global_load_dwordx2 v[100:101], v[80:81], off offset:32
	v_pk_fma_f32 v[96:97], v[76:77], v[96:97], v[102:103]
	s_waitcnt vmcnt(1)
	v_lshlrev_b32_e32 v98, 16, v84
	v_and_b32_e32 v99, 0xffff0000, v84
	v_lshlrev_b32_e32 v84, 16, v85
	v_and_b32_e32 v85, 0xffff0000, v85
	s_waitcnt vmcnt(0)
	v_lshlrev_b32_e32 v102, 16, v100
	v_and_b32_e32 v103, 0xffff0000, v100
	v_lshlrev_b32_e32 v100, 16, v101
	v_and_b32_e32 v101, 0xffff0000, v101
	v_pk_fma_f32 v[84:85], v[74:75], v[84:85], v[100:101]
	v_pk_fma_f32 v[98:99], v[72:73], v[98:99], v[102:103]
	v_cvt_pk_bf16_f32 v96, v96, v97
	v_cvt_pk_bf16_f32 v97, v94, v95
	v_mov_b32_e32 v194, v96
	v_mov_b32_e32 v195, v97
	v_cvt_pk_bf16_f32 v94, v98, v99
	v_cvt_pk_bf16_f32 v95, v84, v85
	v_mov_b32_e32 v196, v94
	v_mov_b32_e32 v197, v95
	v_lshl_add_u64 v[198:199], v[200:201], 0, v[80:81]
	s_nop 0
	v_permlane16_swap_b32 v194, v196
	v_permlane16_swap_b32 v195, v197
	global_store_dwordx4 v[198:199], v[194:197], off

.LBB0_466:
	s_and_b64 vcc, exec, s[58:59]
	s_cbranch_vccz .LBB0_471
	s_cmp_gt_i32 s79, 22
	s_mov_b64 s[58:59], -1
	s_cbranch_scc0 .LBB0_469
	v_ashrrev_i32_e32 v137, 31, v136
	v_lshl_add_u64 v[80:81], v[82:83], 0, v[136:137]
	v_lshlrev_b64 v[80:81], 1, v[80:81]
	v_lshl_add_u64 v[84:85], s[34:35], 0, v[80:81]
	v_lshl_add_u64 v[80:81], s[36:37], 0, v[80:81]
	global_load_dwordx2 v[94:95], v[84:85], off
	global_load_dwordx2 v[100:101], v[80:81], off
	s_mov_b64 s[58:59], 0
	global_load_dwordx2 v[84:85], v[84:85], off offset:32
	s_waitcnt vmcnt(0)
	v_lshlrev_b32_e32 v96, 16, v94
	v_and_b32_e32 v97, 0xffff0000, v94
	v_lshlrev_b32_e32 v94, 16, v95
	v_and_b32_e32 v95, 0xffff0000, v95
	v_lshlrev_b32_e32 v102, 16, v100
	v_and_b32_e32 v103, 0xffff0000, v100
	v_lshlrev_b32_e32 v100, 16, v101
	v_and_b32_e32 v101, 0xffff0000, v101
	v_pk_fma_f32 v[94:95], v[78:79], v[94:95], v[100:101]
	global_load_dwordx2 v[100:101], v[80:81], off offset:32
	v_lshlrev_b32_e32 v98, 16, v84
	v_and_b32_e32 v99, 0xffff0000, v84
	v_lshlrev_b32_e32 v84, 16, v85
	v_and_b32_e32 v85, 0xffff0000, v85
	v_pk_fma_f32 v[96:97], v[76:77], v[96:97], v[102:103]
	s_waitcnt vmcnt(0)
	v_lshlrev_b32_e32 v102, 16, v100
	v_and_b32_e32 v103, 0xffff0000, v100
	v_lshlrev_b32_e32 v100, 16, v101
	v_and_b32_e32 v101, 0xffff0000, v101
	v_pk_fma_f32 v[84:85], v[74:75], v[84:85], v[100:101]
	v_pk_fma_f32 v[98:99], v[72:73], v[98:99], v[102:103]
	v_cvt_pk_bf16_f32 v96, v96, v97
	v_cvt_pk_bf16_f32 v97, v94, v95
	v_mov_b32_e32 v194, v96
	v_mov_b32_e32 v195, v97
	v_cvt_pk_bf16_f32 v94, v98, v99
	v_cvt_pk_bf16_f32 v95, v84, v85
	v_mov_b32_e32 v196, v94
	v_mov_b32_e32 v197, v95
	v_lshl_add_u64 v[198:199], v[200:201], 0, v[80:81]
	s_nop 0
	v_permlane16_swap_b32 v194, v196
	v_permlane16_swap_b32 v195, v197
	global_store_dwordx4 v[198:199], v[194:197], off
.LBB0_469:
	s_andn2_b64 vcc, exec, s[58:59]
	s_cbranch_vccnz .LBB0_471
	v_ashrrev_i32_e32 v137, 31, v136
	v_lshl_add_u64 v[80:81], v[82:83], 0, v[136:137]
	v_lshlrev_b64 v[80:81], 1, v[80:81]
	v_lshl_add_u64 v[84:85], s[38:39], 0, v[80:81]
	global_load_dwordx2 v[94:95], v[84:85], off
	s_nop 0
	global_load_dwordx2 v[84:85], v[84:85], off offset:32
	v_lshl_add_u64 v[80:81], s[36:37], 0, v[80:81]
	s_waitcnt vmcnt(0)
	v_lshlrev_b32_e32 v96, 16, v94
	v_and_b32_e32 v97, 0xffff0000, v94
	v_lshlrev_b32_e32 v94, 16, v95
	v_and_b32_e32 v95, 0xffff0000, v95
	v_pk_mul_f32 v[96:97], v[76:77], v[96:97]
	v_lshlrev_b32_e32 v98, 16, v84
	v_and_b32_e32 v99, 0xffff0000, v84
	v_lshlrev_b32_e32 v84, 16, v85
	v_and_b32_e32 v85, 0xffff0000, v85
	v_pk_mul_f32 v[94:95], v[78:79], v[94:95]
	v_cvt_pk_bf16_f32 v96, v96, v97
	v_pk_mul_f32 v[84:85], v[74:75], v[84:85]
	v_cvt_pk_bf16_f32 v97, v94, v95
	v_pk_mul_f32 v[98:99], v[72:73], v[98:99]
	v_cvt_pk_bf16_f32 v95, v84, v85
	s_nop 0
	v_cvt_pk_bf16_f32 v94, v98, v99
	v_mov_b32_e32 v194, v96
	v_mov_b32_e32 v195, v97
	v_mov_b32_e32 v196, v94
	v_mov_b32_e32 v197, v95
	v_lshl_add_u64 v[198:199], v[200:201], 0, v[80:81]
	s_nop 0
	v_permlane16_swap_b32 v194, v196
	v_permlane16_swap_b32 v195, v197
	global_store_dwordx4 v[198:199], v[194:197], off

.LBB0_479:
	s_ashr_i32 s33, s67, 2
	s_add_i32 s33, s33, 2
	v_mad_i64_i32 v[104:105], s[56:57], s33, v154, v[80:81]
	v_mov_b32_e32 v139, v153
	v_lshl_add_u64 v[104:105], v[104:105], 0, v[138:139]
	v_cvt_pk_bf16_f32 v100, v100, v101
	v_cvt_pk_bf16_f32 v101, v96, v97
	v_mov_b32_e32 v194, v100
	v_mov_b32_e32 v195, v101
	v_cvt_pk_bf16_f32 v96, v98, v99
	v_cvt_pk_bf16_f32 v97, v94, v95
	v_mov_b32_e32 v196, v96
	v_mov_b32_e32 v197, v97
	v_lshl_add_u64 v[198:199], v[200:201], 0, v[104:105]
	s_nop 0
	v_permlane16_swap_b32 v194, v196
	v_permlane16_swap_b32 v195, v197
	global_store_dwordx4 v[198:199], v[194:197], off

.LBB0_492:
	s_or_b64 exec, exec, s[56:57]
	s_add_i32 s33, s33, 1
	v_mad_i64_i32 v[104:105], s[56:57], s33, v154, v[80:81]
	v_mov_b32_e32 v139, v153
	v_lshl_add_u64 v[104:105], v[104:105], 0, v[138:139]
	v_cvt_pk_bf16_f32 v96, v96, v97
	v_cvt_pk_bf16_f32 v97, v94, v95
	v_mov_b32_e32 v194, v96
	v_mov_b32_e32 v195, v97
	v_cvt_pk_bf16_f32 v94, v100, v101
	v_cvt_pk_bf16_f32 v95, v98, v99
	v_mov_b32_e32 v196, v94
	v_mov_b32_e32 v197, v95
	v_lshl_add_u64 v[198:199], v[200:201], 0, v[104:105]
	s_nop 0
	v_permlane16_swap_b32 v194, v196
	v_permlane16_swap_b32 v195, v197
	global_store_dwordx4 v[198:199], v[194:197], off

.LBB0_504:
	s_andn2_b64 vcc, exec, s[56:57]
	s_cbranch_vccnz .LBB0_506
	s_ashr_i32 s2, s67, 2
	s_add_i32 s2, s2, 1
	v_mad_i64_i32 v[94:95], s[2:3], s2, v154, v[80:81]
	v_mov_b32_e32 v139, v153
	v_lshl_add_u64 v[94:95], v[94:95], 0, v[138:139]
	v_cvt_pk_f16_f32 v79, v78, v79
	v_cvt_pk_f16_f32 v78, v76, v77
	v_cvt_pk_f16_f32 v75, v74, v75
	v_cvt_pk_f16_f32 v74, v72, v73
	v_mov_b32_e32 v194, v78
	v_mov_b32_e32 v195, v79
	v_mov_b32_e32 v196, v74
	v_mov_b32_e32 v197, v75
	v_lshl_add_u64 v[198:199], v[200:201], 0, v[94:95]
	s_nop 0
	v_permlane16_swap_b32 v194, v196
	v_permlane16_swap_b32 v195, v197
	global_store_dwordx4 v[198:199], v[194:197], off
.LBB0_506:
	s_mov_b64 s[58:59], -1
	s_mov_b64 s[56:57], 0
	s_cmp_lt_i32 s79, 22
	s_mov_b64 s[2:3], 0
	s_cbranch_scc1 .LBB0_531
	s_cmp_gt_i32 s79, 23
	s_cbranch_scc0 .LBB0_525
	s_cmp_gt_i32 s79, 24
	s_cbranch_scc0 .LBB0_522
	s_cmp_gt_i32 s79, 25
	s_cbranch_scc0 .LBB0_513
	s_cmp_eq_u32 s79, 26
	s_mov_b64 s[2:3], -1
	s_cbranch_scc0 .LBB0_512
	v_max_f32_e32 v72, v68, v68
	v_max_f32_e32 v73, v64, v64
	v_max_f32_e32 v72, 0, v72
	v_max_f32_e32 v73, 0, v73
	v_mul_f32_e32 v74, v72, v72
	v_mul_f32_e32 v76, v73, v73
	v_max_f32_e32 v72, v69, v69
	v_max_f32_e32 v73, v65, v65
	v_max_f32_e32 v72, 0, v72
	v_max_f32_e32 v73, 0, v73
	v_mul_f32_e32 v75, v72, v72
	v_mul_f32_e32 v77, v73, v73
	v_max_f32_e32 v72, v70, v70
	v_max_f32_e32 v73, v66, v66
	v_max_f32_e32 v72, 0, v72
	v_max_f32_e32 v73, 0, v73
	v_mul_f32_e32 v78, v72, v72
	v_mul_f32_e32 v79, v73, v73
	v_max_f32_e32 v72, v71, v71
	v_max_f32_e32 v73, v67, v67
	v_max_f32_e32 v72, 0, v72
	v_max_f32_e32 v73, 0, v73
	v_ashrrev_i32_e32 v137, 31, v136
	v_mul_f32_e32 v94, v72, v72
	v_mul_f32_e32 v95, v73, v73
	v_lshl_add_u64 v[72:73], v[136:137], 1, v[88:89]
	v_cvt_pk_bf16_f32 v74, v74, v75
	v_cvt_pk_bf16_f32 v75, v78, v94
	s_mov_b64 s[2:3], 0
	v_mov_b32_e32 v194, v74
	v_mov_b32_e32 v195, v75
	v_cvt_pk_bf16_f32 v74, v76, v77
	v_cvt_pk_bf16_f32 v75, v79, v95
	v_mov_b32_e32 v196, v74
	v_mov_b32_e32 v197, v75
	v_lshl_add_u64 v[198:199], v[200:201], 0, v[72:73]
	s_nop 0
	v_permlane16_swap_b32 v194, v196
	v_permlane16_swap_b32 v195, v197
	global_store_dwordx4 v[198:199], v[194:197], off offset:256

.LBB0_522:
	s_and_b64 vcc, exec, s[58:59]
	s_cbranch_vccz .LBB0_524
	v_ashrrev_i32_e32 v121, 31, v120
	v_lshl_add_u64 v[72:73], v[82:83], 0, v[120:121]
	v_lshlrev_b64 v[72:73], 1, v[72:73]
	v_lshl_add_u64 v[74:75], s[40:41], 0, v[72:73]
	v_lshl_add_u64 v[72:73], s[36:37], 0, v[72:73]
	global_load_dwordx2 v[76:77], v[74:75], off
	global_load_dwordx2 v[88:89], v[72:73], off
	s_waitcnt vmcnt(0)
	v_lshlrev_b32_e32 v78, 16, v76
	v_and_b32_e32 v79, 0xffff0000, v76
	v_lshlrev_b32_e32 v76, 16, v77
	v_and_b32_e32 v77, 0xffff0000, v77
	v_lshlrev_b32_e32 v94, 16, v88
	v_and_b32_e32 v95, 0xffff0000, v88
	v_lshlrev_b32_e32 v88, 16, v89
	v_and_b32_e32 v89, 0xffff0000, v89
	global_load_dwordx2 v[74:75], v[74:75], off offset:32
	v_pk_fma_f32 v[76:77], v[70:71], v[76:77], v[88:89]
	global_load_dwordx2 v[88:89], v[72:73], off offset:32
	v_pk_fma_f32 v[78:79], v[68:69], v[78:79], v[94:95]
	s_waitcnt vmcnt(1)
	v_lshlrev_b32_e32 v86, 16, v74
	v_and_b32_e32 v87, 0xffff0000, v74
	v_lshlrev_b32_e32 v74, 16, v75
	v_and_b32_e32 v75, 0xffff0000, v75
	s_waitcnt vmcnt(0)
	v_lshlrev_b32_e32 v94, 16, v88
	v_and_b32_e32 v95, 0xffff0000, v88
	v_lshlrev_b32_e32 v88, 16, v89
	v_and_b32_e32 v89, 0xffff0000, v89
	v_pk_fma_f32 v[74:75], v[66:67], v[74:75], v[88:89]
	v_pk_fma_f32 v[86:87], v[64:65], v[86:87], v[94:95]
	v_cvt_pk_bf16_f32 v78, v78, v79
	v_cvt_pk_bf16_f32 v79, v76, v77
	v_mov_b32_e32 v194, v78
	v_mov_b32_e32 v195, v79
	v_cvt_pk_bf16_f32 v76, v86, v87
	v_cvt_pk_bf16_f32 v77, v74, v75
	v_mov_b32_e32 v196, v76
	v_mov_b32_e32 v197, v77
	v_lshl_add_u64 v[198:199], v[200:201], 0, v[72:73]
	s_nop 0
	v_permlane16_swap_b32 v194, v196
	v_permlane16_swap_b32 v195, v197
	global_store_dwordx4 v[198:199], v[194:197], off

.LBB0_525:
	s_and_b64 vcc, exec, s[58:59]
	s_cbranch_vccz .LBB0_530
	s_cmp_gt_i32 s79, 22
	s_mov_b64 s[58:59], -1
	s_cbranch_scc0 .LBB0_528
	v_ashrrev_i32_e32 v121, 31, v120
	v_lshl_add_u64 v[72:73], v[82:83], 0, v[120:121]
	v_lshlrev_b64 v[72:73], 1, v[72:73]
	v_lshl_add_u64 v[74:75], s[34:35], 0, v[72:73]
	v_lshl_add_u64 v[72:73], s[36:37], 0, v[72:73]
	global_load_dwordx2 v[76:77], v[74:75], off
	global_load_dwordx2 v[88:89], v[72:73], off
	s_mov_b64 s[58:59], 0
	global_load_dwordx2 v[74:75], v[74:75], off offset:32
	s_waitcnt vmcnt(0)
	v_lshlrev_b32_e32 v78, 16, v76
	v_and_b32_e32 v79, 0xffff0000, v76
	v_lshlrev_b32_e32 v76, 16, v77
	v_and_b32_e32 v77, 0xffff0000, v77
	v_lshlrev_b32_e32 v94, 16, v88
	v_and_b32_e32 v95, 0xffff0000, v88
	v_lshlrev_b32_e32 v88, 16, v89
	v_and_b32_e32 v89, 0xffff0000, v89
	v_pk_fma_f32 v[76:77], v[70:71], v[76:77], v[88:89]
	global_load_dwordx2 v[88:89], v[72:73], off offset:32
	v_lshlrev_b32_e32 v86, 16, v74
	v_and_b32_e32 v87, 0xffff0000, v74
	v_lshlrev_b32_e32 v74, 16, v75
	v_and_b32_e32 v75, 0xffff0000, v75
	v_pk_fma_f32 v[78:79], v[68:69], v[78:79], v[94:95]
	s_waitcnt vmcnt(0)
	v_lshlrev_b32_e32 v94, 16, v88
	v_and_b32_e32 v95, 0xffff0000, v88
	v_lshlrev_b32_e32 v88, 16, v89
	v_and_b32_e32 v89, 0xffff0000, v89
	v_pk_fma_f32 v[74:75], v[66:67], v[74:75], v[88:89]
	v_pk_fma_f32 v[86:87], v[64:65], v[86:87], v[94:95]
	v_cvt_pk_bf16_f32 v78, v78, v79
	v_cvt_pk_bf16_f32 v79, v76, v77
	v_mov_b32_e32 v194, v78
	v_mov_b32_e32 v195, v79
	v_cvt_pk_bf16_f32 v76, v86, v87
	v_cvt_pk_bf16_f32 v77, v74, v75
	v_mov_b32_e32 v196, v76
	v_mov_b32_e32 v197, v77
	v_lshl_add_u64 v[198:199], v[200:201], 0, v[72:73]
	s_nop 0
	v_permlane16_swap_b32 v194, v196
	v_permlane16_swap_b32 v195, v197
	global_store_dwordx4 v[198:199], v[194:197], off
.LBB0_528:
	s_andn2_b64 vcc, exec, s[58:59]
	s_cbranch_vccnz .LBB0_530
	v_ashrrev_i32_e32 v121, 31, v120
	v_lshl_add_u64 v[72:73], v[82:83], 0, v[120:121]
	v_lshlrev_b64 v[72:73], 1, v[72:73]
	v_lshl_add_u64 v[74:75], s[38:39], 0, v[72:73]
	global_load_dwordx2 v[76:77], v[74:75], off
	s_nop 0
	global_load_dwordx2 v[74:75], v[74:75], off offset:32
	v_lshl_add_u64 v[72:73], s[36:37], 0, v[72:73]
	s_waitcnt vmcnt(0)
	v_lshlrev_b32_e32 v78, 16, v76
	v_and_b32_e32 v79, 0xffff0000, v76
	v_lshlrev_b32_e32 v76, 16, v77
	v_and_b32_e32 v77, 0xffff0000, v77
	v_pk_mul_f32 v[78:79], v[68:69], v[78:79]
	v_lshlrev_b32_e32 v82, 16, v74
	v_and_b32_e32 v83, 0xffff0000, v74
	v_lshlrev_b32_e32 v74, 16, v75
	v_and_b32_e32 v75, 0xffff0000, v75
	v_pk_mul_f32 v[76:77], v[70:71], v[76:77]
	v_cvt_pk_bf16_f32 v78, v78, v79
	v_pk_mul_f32 v[74:75], v[66:67], v[74:75]
	v_cvt_pk_bf16_f32 v79, v76, v77
	v_pk_mul_f32 v[82:83], v[64:65], v[82:83]
	v_cvt_pk_bf16_f32 v77, v74, v75
	s_nop 0
	v_cvt_pk_bf16_f32 v76, v82, v83
	v_mov_b32_e32 v194, v78
	v_mov_b32_e32 v195, v79
	v_mov_b32_e32 v196, v76
	v_mov_b32_e32 v197, v77
	v_lshl_add_u64 v[198:199], v[200:201], 0, v[72:73]
	s_nop 0
	v_permlane16_swap_b32 v194, v196
	v_permlane16_swap_b32 v195, v197
	global_store_dwordx4 v[198:199], v[194:197], off

.LBB0_538:
	s_ashr_i32 s33, s67, 2
	s_add_i32 s33, s33, 2
	v_mad_i64_i32 v[82:83], s[56:57], s33, v154, v[80:81]
	v_mov_b32_e32 v123, v153
	v_lshl_add_u64 v[82:83], v[82:83], 0, v[122:123]
	v_cvt_pk_bf16_f32 v78, v78, v79
	v_cvt_pk_bf16_f32 v79, v74, v75
	v_mov_b32_e32 v194, v78
	v_mov_b32_e32 v195, v79
	v_cvt_pk_bf16_f32 v74, v76, v77
	v_cvt_pk_bf16_f32 v75, v72, v73
	v_mov_b32_e32 v196, v74
	v_mov_b32_e32 v197, v75
	v_lshl_add_u64 v[198:199], v[200:201], 0, v[82:83]
	s_nop 0
	v_permlane16_swap_b32 v194, v196
	v_permlane16_swap_b32 v195, v197
	global_store_dwordx4 v[198:199], v[194:197], off

.LBB0_551:
	s_or_b64 exec, exec, s[56:57]
	s_add_i32 s33, s33, 1
	v_mad_i64_i32 v[82:83], s[10:11], s33, v154, v[80:81]
	v_mov_b32_e32 v123, v153
	v_lshl_add_u64 v[82:83], v[82:83], 0, v[122:123]
	v_cvt_pk_bf16_f32 v74, v74, v75
	v_cvt_pk_bf16_f32 v75, v72, v73
	v_mov_b32_e32 v194, v74
	v_mov_b32_e32 v195, v75
	v_cvt_pk_bf16_f32 v72, v78, v79
	v_cvt_pk_bf16_f32 v73, v76, v77
	v_mov_b32_e32 v196, v72
	v_mov_b32_e32 v197, v73
	v_lshl_add_u64 v[198:199], v[200:201], 0, v[82:83]
	s_nop 0
	v_permlane16_swap_b32 v194, v196
	v_permlane16_swap_b32 v195, v197
	global_store_dwordx4 v[198:199], v[194:197], off

.LBB0_563:
	s_andn2_b64 vcc, exec, s[56:57]
	s_cbranch_vccnz .LBB0_565
	s_ashr_i32 s2, s67, 2
	s_add_i32 s2, s2, 1
	v_mad_i64_i32 v[72:73], s[2:3], s2, v154, v[80:81]
	v_mov_b32_e32 v123, v153
	v_lshl_add_u64 v[72:73], v[72:73], 0, v[122:123]
	v_cvt_pk_f16_f32 v71, v70, v71
	v_cvt_pk_f16_f32 v70, v68, v69
	v_cvt_pk_f16_f32 v67, v66, v67
	v_cvt_pk_f16_f32 v66, v64, v65
	v_mov_b32_e32 v194, v70
	v_mov_b32_e32 v195, v71
	v_mov_b32_e32 v196, v66
	v_mov_b32_e32 v197, v67
	v_lshl_add_u64 v[198:199], v[200:201], 0, v[72:73]
	s_nop 0
	v_permlane16_swap_b32 v194, v196
	v_permlane16_swap_b32 v195, v197
	global_store_dwordx4 v[198:199], v[194:197], off
.LBB0_565:
	s_add_i32 s63, s62, 0x80
	v_or_b32_e32 v76, s63, v157
	s_ashr_i32 s2, s63, 13
	v_ashrrev_i32_e32 v77, 31, v76
	s_mul_i32 s54, s2, 0x1800
	v_lshlrev_b64 v[64:65], 13, v[76:77]
	v_add_u32_e32 v74, 0xffffc000, v76
	v_mov_b32_e32 v75, v153
	s_ashr_i32 s55, s54, 31
	v_lshl_add_u64 v[72:73], s[52:53], 0, v[64:65]
	v_cmp_gt_i32_e64 s[10:11], s92, v76
	v_cmp_lt_i32_e64 s[8:9], s80, v76
	v_lshlrev_b64 v[70:71], 10, v[74:75]
	v_lshlrev_b64 v[66:67], 10, v[76:77]
	s_mov_b64 s[58:59], -1
	s_mov_b64 s[56:57], 0
	s_cmp_lt_i32 s79, 22
	s_mov_b64 s[2:3], 0
	s_cbranch_scc1 .LBB0_590
	s_cmp_gt_i32 s79, 23
	s_cbranch_scc0 .LBB0_584
	s_cmp_gt_i32 s79, 24
	s_cbranch_scc0 .LBB0_581
	s_cmp_gt_i32 s79, 25
	s_cbranch_scc0 .LBB0_572
	s_cmp_eq_u32 s79, 26
	s_mov_b64 s[2:3], -1
	s_cbranch_scc0 .LBB0_571
	v_max_f32_e32 v64, v60, v60
	v_max_f32_e32 v65, v56, v56
	v_max_f32_e32 v64, 0, v64
	v_max_f32_e32 v65, 0, v65
	v_mul_f32_e32 v68, v64, v64
	v_mul_f32_e32 v78, v65, v65
	v_max_f32_e32 v64, v61, v61
	v_max_f32_e32 v65, v57, v57
	v_max_f32_e32 v64, 0, v64
	v_max_f32_e32 v65, 0, v65
	v_mul_f32_e32 v69, v64, v64
	v_mul_f32_e32 v79, v65, v65
	v_max_f32_e32 v64, v62, v62
	v_max_f32_e32 v65, v58, v58
	v_max_f32_e32 v64, 0, v64
	v_max_f32_e32 v65, 0, v65
	v_mul_f32_e32 v80, v64, v64
	v_mul_f32_e32 v81, v65, v65
	v_max_f32_e32 v64, v63, v63
	v_max_f32_e32 v65, v59, v59
	v_max_f32_e32 v64, 0, v64
	v_max_f32_e32 v65, 0, v65
	v_ashrrev_i32_e32 v137, 31, v136
	v_mul_f32_e32 v82, v64, v64
	v_mul_f32_e32 v83, v65, v65
	v_lshl_add_u64 v[64:65], v[136:137], 1, v[72:73]
	v_cvt_pk_bf16_f32 v68, v68, v69
	v_cvt_pk_bf16_f32 v69, v80, v82
	s_mov_b64 s[2:3], 0
	v_mov_b32_e32 v194, v68
	v_mov_b32_e32 v195, v69
	v_cvt_pk_bf16_f32 v68, v78, v79
	v_cvt_pk_bf16_f32 v69, v81, v83
	v_mov_b32_e32 v196, v68
	v_mov_b32_e32 v197, v69
	v_lshl_add_u64 v[198:199], v[200:201], 0, v[64:65]
	s_nop 0
	v_permlane16_swap_b32 v194, v196
	v_permlane16_swap_b32 v195, v197
	global_store_dwordx4 v[198:199], v[194:197], off

.LBB0_581:
	s_and_b64 vcc, exec, s[58:59]
	s_cbranch_vccz .LBB0_583
	v_ashrrev_i32_e32 v137, 31, v136
	v_lshl_add_u64 v[64:65], v[66:67], 0, v[136:137]
	v_lshlrev_b64 v[64:65], 1, v[64:65]
	v_lshl_add_u64 v[68:69], s[40:41], 0, v[64:65]
	v_lshl_add_u64 v[64:65], s[36:37], 0, v[64:65]
	global_load_dwordx2 v[78:79], v[68:69], off
	global_load_dwordx2 v[84:85], v[64:65], off
	s_waitcnt vmcnt(0)
	v_lshlrev_b32_e32 v80, 16, v78
	v_and_b32_e32 v81, 0xffff0000, v78
	v_lshlrev_b32_e32 v78, 16, v79
	v_and_b32_e32 v79, 0xffff0000, v79
	v_lshlrev_b32_e32 v86, 16, v84
	v_and_b32_e32 v87, 0xffff0000, v84
	v_lshlrev_b32_e32 v84, 16, v85
	v_and_b32_e32 v85, 0xffff0000, v85
	global_load_dwordx2 v[68:69], v[68:69], off offset:32
	v_pk_fma_f32 v[78:79], v[62:63], v[78:79], v[84:85]
	global_load_dwordx2 v[84:85], v[64:65], off offset:32
	v_pk_fma_f32 v[80:81], v[60:61], v[80:81], v[86:87]
	s_waitcnt vmcnt(1)
	v_lshlrev_b32_e32 v82, 16, v68
	v_and_b32_e32 v83, 0xffff0000, v68
	v_lshlrev_b32_e32 v68, 16, v69
	v_and_b32_e32 v69, 0xffff0000, v69
	s_waitcnt vmcnt(0)
	v_lshlrev_b32_e32 v86, 16, v84
	v_and_b32_e32 v87, 0xffff0000, v84
	v_lshlrev_b32_e32 v84, 16, v85
	v_and_b32_e32 v85, 0xffff0000, v85
	v_pk_fma_f32 v[68:69], v[58:59], v[68:69], v[84:85]
	v_pk_fma_f32 v[82:83], v[56:57], v[82:83], v[86:87]
	v_cvt_pk_bf16_f32 v80, v80, v81
	v_cvt_pk_bf16_f32 v81, v78, v79
	v_mov_b32_e32 v194, v80
	v_mov_b32_e32 v195, v81
	v_cvt_pk_bf16_f32 v78, v82, v83
	v_cvt_pk_bf16_f32 v79, v68, v69
	v_mov_b32_e32 v196, v78
	v_mov_b32_e32 v197, v79
	v_lshl_add_u64 v[198:199], v[200:201], 0, v[64:65]
	s_nop 0
	v_permlane16_swap_b32 v194, v196
	v_permlane16_swap_b32 v195, v197
	global_store_dwordx4 v[198:199], v[194:197], off

.LBB0_584:
	s_and_b64 vcc, exec, s[58:59]
	s_cbranch_vccz .LBB0_589
	s_cmp_gt_i32 s79, 22
	s_mov_b64 s[58:59], -1
	s_cbranch_scc0 .LBB0_587
	v_ashrrev_i32_e32 v137, 31, v136
	v_lshl_add_u64 v[64:65], v[66:67], 0, v[136:137]
	v_lshlrev_b64 v[64:65], 1, v[64:65]
	v_lshl_add_u64 v[68:69], s[34:35], 0, v[64:65]
	v_lshl_add_u64 v[64:65], s[36:37], 0, v[64:65]
	global_load_dwordx2 v[78:79], v[68:69], off
	global_load_dwordx2 v[84:85], v[64:65], off
	s_mov_b64 s[58:59], 0
	global_load_dwordx2 v[68:69], v[68:69], off offset:32
	s_waitcnt vmcnt(0)
	v_lshlrev_b32_e32 v80, 16, v78
	v_and_b32_e32 v81, 0xffff0000, v78
	v_lshlrev_b32_e32 v78, 16, v79
	v_and_b32_e32 v79, 0xffff0000, v79
	v_lshlrev_b32_e32 v86, 16, v84
	v_and_b32_e32 v87, 0xffff0000, v84
	v_lshlrev_b32_e32 v84, 16, v85
	v_and_b32_e32 v85, 0xffff0000, v85
	v_pk_fma_f32 v[78:79], v[62:63], v[78:79], v[84:85]
	global_load_dwordx2 v[84:85], v[64:65], off offset:32
	v_lshlrev_b32_e32 v82, 16, v68
	v_and_b32_e32 v83, 0xffff0000, v68
	v_lshlrev_b32_e32 v68, 16, v69
	v_and_b32_e32 v69, 0xffff0000, v69
	v_pk_fma_f32 v[80:81], v[60:61], v[80:81], v[86:87]
	s_waitcnt vmcnt(0)
	v_lshlrev_b32_e32 v86, 16, v84
	v_and_b32_e32 v87, 0xffff0000, v84
	v_lshlrev_b32_e32 v84, 16, v85
	v_and_b32_e32 v85, 0xffff0000, v85
	v_pk_fma_f32 v[68:69], v[58:59], v[68:69], v[84:85]
	v_pk_fma_f32 v[82:83], v[56:57], v[82:83], v[86:87]
	v_cvt_pk_bf16_f32 v80, v80, v81
	v_cvt_pk_bf16_f32 v81, v78, v79
	v_mov_b32_e32 v194, v80
	v_mov_b32_e32 v195, v81
	v_cvt_pk_bf16_f32 v78, v82, v83
	v_cvt_pk_bf16_f32 v79, v68, v69
	v_mov_b32_e32 v196, v78
	v_mov_b32_e32 v197, v79
	v_lshl_add_u64 v[198:199], v[200:201], 0, v[64:65]
	s_nop 0
	v_permlane16_swap_b32 v194, v196
	v_permlane16_swap_b32 v195, v197
	global_store_dwordx4 v[198:199], v[194:197], off
.LBB0_587:
	s_andn2_b64 vcc, exec, s[58:59]
	s_cbranch_vccnz .LBB0_589
	v_ashrrev_i32_e32 v137, 31, v136
	v_lshl_add_u64 v[64:65], v[66:67], 0, v[136:137]
	v_lshlrev_b64 v[64:65], 1, v[64:65]
	v_lshl_add_u64 v[68:69], s[38:39], 0, v[64:65]
	global_load_dwordx2 v[78:79], v[68:69], off
	s_nop 0
	global_load_dwordx2 v[68:69], v[68:69], off offset:32
	v_lshl_add_u64 v[64:65], s[36:37], 0, v[64:65]
	s_waitcnt vmcnt(0)
	v_lshlrev_b32_e32 v80, 16, v78
	v_and_b32_e32 v81, 0xffff0000, v78
	v_lshlrev_b32_e32 v78, 16, v79
	v_and_b32_e32 v79, 0xffff0000, v79
	v_pk_mul_f32 v[80:81], v[60:61], v[80:81]
	v_lshlrev_b32_e32 v82, 16, v68
	v_and_b32_e32 v83, 0xffff0000, v68
	v_lshlrev_b32_e32 v68, 16, v69
	v_and_b32_e32 v69, 0xffff0000, v69
	v_pk_mul_f32 v[78:79], v[62:63], v[78:79]
	v_cvt_pk_bf16_f32 v80, v80, v81
	v_pk_mul_f32 v[68:69], v[58:59], v[68:69]
	v_cvt_pk_bf16_f32 v81, v78, v79
	v_pk_mul_f32 v[82:83], v[56:57], v[82:83]
	v_cvt_pk_bf16_f32 v79, v68, v69
	s_nop 0
	v_cvt_pk_bf16_f32 v78, v82, v83
	v_mov_b32_e32 v194, v80
	v_mov_b32_e32 v195, v81
	v_mov_b32_e32 v196, v78
	v_mov_b32_e32 v197, v79
	v_lshl_add_u64 v[198:199], v[200:201], 0, v[64:65]
	s_nop 0
	v_permlane16_swap_b32 v194, v196
	v_permlane16_swap_b32 v195, v197
	global_store_dwordx4 v[198:199], v[194:197], off

.LBB0_597:
	s_ashr_i32 s33, s67, 2
	s_add_i32 s33, s33, 2
	v_mad_i64_i32 v[88:89], s[56:57], s33, v154, v[64:65]
	v_mov_b32_e32 v139, v153
	v_lshl_add_u64 v[88:89], v[88:89], 0, v[138:139]
	v_cvt_pk_bf16_f32 v84, v84, v85
	v_cvt_pk_bf16_f32 v85, v80, v81
	v_mov_b32_e32 v194, v84
	v_mov_b32_e32 v195, v85
	v_cvt_pk_bf16_f32 v80, v82, v83
	v_cvt_pk_bf16_f32 v81, v78, v79
	v_mov_b32_e32 v196, v80
	v_mov_b32_e32 v197, v81
	v_lshl_add_u64 v[198:199], v[200:201], 0, v[88:89]
	s_nop 0
	v_permlane16_swap_b32 v194, v196
	v_permlane16_swap_b32 v195, v197
	global_store_dwordx4 v[198:199], v[194:197], off

.LBB0_610:
	s_or_b64 exec, exec, s[56:57]
	s_add_i32 s33, s33, 1
	v_mad_i64_i32 v[88:89], s[56:57], s33, v154, v[64:65]
	v_mov_b32_e32 v139, v153
	v_lshl_add_u64 v[88:89], v[88:89], 0, v[138:139]
	v_cvt_pk_bf16_f32 v80, v80, v81
	v_cvt_pk_bf16_f32 v81, v78, v79
	v_mov_b32_e32 v194, v80
	v_mov_b32_e32 v195, v81
	v_cvt_pk_bf16_f32 v78, v84, v85
	v_cvt_pk_bf16_f32 v79, v82, v83
	v_mov_b32_e32 v196, v78
	v_mov_b32_e32 v197, v79
	v_lshl_add_u64 v[198:199], v[200:201], 0, v[88:89]
	s_nop 0
	v_permlane16_swap_b32 v194, v196
	v_permlane16_swap_b32 v195, v197
	global_store_dwordx4 v[198:199], v[194:197], off

.LBB0_622:
	s_andn2_b64 vcc, exec, s[56:57]
	s_cbranch_vccnz .LBB0_624
	s_ashr_i32 s2, s67, 2
	s_add_i32 s2, s2, 1
	v_mad_i64_i32 v[78:79], s[2:3], s2, v154, v[64:65]
	v_mov_b32_e32 v139, v153
	v_lshl_add_u64 v[78:79], v[78:79], 0, v[138:139]
	v_cvt_pk_f16_f32 v63, v62, v63
	v_cvt_pk_f16_f32 v62, v60, v61
	v_cvt_pk_f16_f32 v59, v58, v59
	v_cvt_pk_f16_f32 v58, v56, v57
	v_mov_b32_e32 v194, v62
	v_mov_b32_e32 v195, v63
	v_mov_b32_e32 v196, v58
	v_mov_b32_e32 v197, v59
	v_lshl_add_u64 v[198:199], v[200:201], 0, v[78:79]
	s_nop 0
	v_permlane16_swap_b32 v194, v196
	v_permlane16_swap_b32 v195, v197
	global_store_dwordx4 v[198:199], v[194:197], off
.LBB0_624:
	s_mov_b64 s[58:59], -1
	s_mov_b64 s[56:57], 0
	s_cmp_lt_i32 s79, 22
	s_mov_b64 s[2:3], 0
	s_cbranch_scc1 .LBB0_649
	s_cmp_gt_i32 s79, 23
	s_cbranch_scc0 .LBB0_643
	s_cmp_gt_i32 s79, 24
	s_cbranch_scc0 .LBB0_640
	s_cmp_gt_i32 s79, 25
	s_cbranch_scc0 .LBB0_631
	s_cmp_eq_u32 s79, 26
	s_mov_b64 s[2:3], -1
	s_cbranch_scc0 .LBB0_630
	v_max_f32_e32 v56, v52, v52
	v_max_f32_e32 v57, v48, v48
	v_max_f32_e32 v56, 0, v56
	v_max_f32_e32 v57, 0, v57
	v_mul_f32_e32 v58, v56, v56
	v_mul_f32_e32 v60, v57, v57
	v_max_f32_e32 v56, v53, v53
	v_max_f32_e32 v57, v49, v49
	v_max_f32_e32 v56, 0, v56
	v_max_f32_e32 v57, 0, v57
	v_mul_f32_e32 v59, v56, v56
	v_mul_f32_e32 v61, v57, v57
	v_max_f32_e32 v56, v54, v54
	v_max_f32_e32 v57, v50, v50
	v_max_f32_e32 v56, 0, v56
	v_max_f32_e32 v57, 0, v57
	v_mul_f32_e32 v62, v56, v56
	v_mul_f32_e32 v63, v57, v57
	v_max_f32_e32 v56, v55, v55
	v_max_f32_e32 v57, v51, v51
	v_max_f32_e32 v56, 0, v56
	v_max_f32_e32 v57, 0, v57
	v_ashrrev_i32_e32 v137, 31, v136
	v_mul_f32_e32 v78, v56, v56
	v_mul_f32_e32 v79, v57, v57
	v_lshl_add_u64 v[56:57], v[136:137], 1, v[72:73]
	v_cvt_pk_bf16_f32 v58, v58, v59
	v_cvt_pk_bf16_f32 v59, v62, v78
	s_mov_b64 s[2:3], 0
	v_mov_b32_e32 v194, v58
	v_mov_b32_e32 v195, v59
	v_cvt_pk_bf16_f32 v58, v60, v61
	v_cvt_pk_bf16_f32 v59, v63, v79
	v_mov_b32_e32 v196, v58
	v_mov_b32_e32 v197, v59
	v_lshl_add_u64 v[198:199], v[200:201], 0, v[56:57]
	s_nop 0
	v_permlane16_swap_b32 v194, v196
	v_permlane16_swap_b32 v195, v197
	global_store_dwordx4 v[198:199], v[194:197], off offset:256

.LBB0_640:
	s_and_b64 vcc, exec, s[58:59]
	s_cbranch_vccz .LBB0_642
	v_ashrrev_i32_e32 v121, 31, v120
	v_lshl_add_u64 v[56:57], v[66:67], 0, v[120:121]
	v_lshlrev_b64 v[56:57], 1, v[56:57]
	v_lshl_add_u64 v[58:59], s[40:41], 0, v[56:57]
	v_lshl_add_u64 v[56:57], s[36:37], 0, v[56:57]
	global_load_dwordx2 v[60:61], v[58:59], off
	global_load_dwordx2 v[72:73], v[56:57], off
	s_waitcnt vmcnt(0)
	v_lshlrev_b32_e32 v62, 16, v60
	v_and_b32_e32 v63, 0xffff0000, v60
	v_lshlrev_b32_e32 v60, 16, v61
	v_and_b32_e32 v61, 0xffff0000, v61
	v_lshlrev_b32_e32 v78, 16, v72
	v_and_b32_e32 v79, 0xffff0000, v72
	v_lshlrev_b32_e32 v72, 16, v73
	v_and_b32_e32 v73, 0xffff0000, v73
	global_load_dwordx2 v[58:59], v[58:59], off offset:32
	v_pk_fma_f32 v[60:61], v[54:55], v[60:61], v[72:73]
	global_load_dwordx2 v[72:73], v[56:57], off offset:32
	v_pk_fma_f32 v[62:63], v[52:53], v[62:63], v[78:79]
	s_waitcnt vmcnt(1)
	v_lshlrev_b32_e32 v70, 16, v58
	v_and_b32_e32 v71, 0xffff0000, v58
	v_lshlrev_b32_e32 v58, 16, v59
	v_and_b32_e32 v59, 0xffff0000, v59
	s_waitcnt vmcnt(0)
	v_lshlrev_b32_e32 v78, 16, v72
	v_and_b32_e32 v79, 0xffff0000, v72
	v_lshlrev_b32_e32 v72, 16, v73
	v_and_b32_e32 v73, 0xffff0000, v73
	v_pk_fma_f32 v[58:59], v[50:51], v[58:59], v[72:73]
	v_pk_fma_f32 v[70:71], v[48:49], v[70:71], v[78:79]
	v_cvt_pk_bf16_f32 v62, v62, v63
	v_cvt_pk_bf16_f32 v63, v60, v61
	v_mov_b32_e32 v194, v62
	v_mov_b32_e32 v195, v63
	v_cvt_pk_bf16_f32 v60, v70, v71
	v_cvt_pk_bf16_f32 v61, v58, v59
	v_mov_b32_e32 v196, v60
	v_mov_b32_e32 v197, v61
	v_lshl_add_u64 v[198:199], v[200:201], 0, v[56:57]
	s_nop 0
	v_permlane16_swap_b32 v194, v196
	v_permlane16_swap_b32 v195, v197
	global_store_dwordx4 v[198:199], v[194:197], off

.LBB0_643:
	s_and_b64 vcc, exec, s[58:59]
	s_cbranch_vccz .LBB0_648
	s_cmp_gt_i32 s79, 22
	s_mov_b64 s[58:59], -1
	s_cbranch_scc0 .LBB0_646
	v_ashrrev_i32_e32 v121, 31, v120
	v_lshl_add_u64 v[56:57], v[66:67], 0, v[120:121]
	v_lshlrev_b64 v[56:57], 1, v[56:57]
	v_lshl_add_u64 v[58:59], s[34:35], 0, v[56:57]
	v_lshl_add_u64 v[56:57], s[36:37], 0, v[56:57]
	global_load_dwordx2 v[60:61], v[58:59], off
	global_load_dwordx2 v[72:73], v[56:57], off
	s_mov_b64 s[58:59], 0
	global_load_dwordx2 v[58:59], v[58:59], off offset:32
	s_waitcnt vmcnt(0)
	v_lshlrev_b32_e32 v62, 16, v60
	v_and_b32_e32 v63, 0xffff0000, v60
	v_lshlrev_b32_e32 v60, 16, v61
	v_and_b32_e32 v61, 0xffff0000, v61
	v_lshlrev_b32_e32 v78, 16, v72
	v_and_b32_e32 v79, 0xffff0000, v72
	v_lshlrev_b32_e32 v72, 16, v73
	v_and_b32_e32 v73, 0xffff0000, v73
	v_pk_fma_f32 v[60:61], v[54:55], v[60:61], v[72:73]
	global_load_dwordx2 v[72:73], v[56:57], off offset:32
	v_lshlrev_b32_e32 v70, 16, v58
	v_and_b32_e32 v71, 0xffff0000, v58
	v_lshlrev_b32_e32 v58, 16, v59
	v_and_b32_e32 v59, 0xffff0000, v59
	v_pk_fma_f32 v[62:63], v[52:53], v[62:63], v[78:79]
	s_waitcnt vmcnt(0)
	v_lshlrev_b32_e32 v78, 16, v72
	v_and_b32_e32 v79, 0xffff0000, v72
	v_lshlrev_b32_e32 v72, 16, v73
	v_and_b32_e32 v73, 0xffff0000, v73
	v_pk_fma_f32 v[58:59], v[50:51], v[58:59], v[72:73]
	v_pk_fma_f32 v[70:71], v[48:49], v[70:71], v[78:79]
	v_cvt_pk_bf16_f32 v62, v62, v63
	v_cvt_pk_bf16_f32 v63, v60, v61
	v_mov_b32_e32 v194, v62
	v_mov_b32_e32 v195, v63
	v_cvt_pk_bf16_f32 v60, v70, v71
	v_cvt_pk_bf16_f32 v61, v58, v59
	v_mov_b32_e32 v196, v60
	v_mov_b32_e32 v197, v61
	v_lshl_add_u64 v[198:199], v[200:201], 0, v[56:57]
	s_nop 0
	v_permlane16_swap_b32 v194, v196
	v_permlane16_swap_b32 v195, v197
	global_store_dwordx4 v[198:199], v[194:197], off
.LBB0_646:
	s_andn2_b64 vcc, exec, s[58:59]
	s_cbranch_vccnz .LBB0_648
	v_ashrrev_i32_e32 v121, 31, v120
	v_lshl_add_u64 v[56:57], v[66:67], 0, v[120:121]
	v_lshlrev_b64 v[56:57], 1, v[56:57]
	v_lshl_add_u64 v[58:59], s[38:39], 0, v[56:57]
	global_load_dwordx2 v[60:61], v[58:59], off
	s_nop 0
	global_load_dwordx2 v[58:59], v[58:59], off offset:32
	v_lshl_add_u64 v[56:57], s[36:37], 0, v[56:57]
	s_waitcnt vmcnt(0)
	v_lshlrev_b32_e32 v62, 16, v60
	v_and_b32_e32 v63, 0xffff0000, v60
	v_lshlrev_b32_e32 v60, 16, v61
	v_and_b32_e32 v61, 0xffff0000, v61
	v_pk_mul_f32 v[62:63], v[52:53], v[62:63]
	v_lshlrev_b32_e32 v66, 16, v58
	v_and_b32_e32 v67, 0xffff0000, v58
	v_lshlrev_b32_e32 v58, 16, v59
	v_and_b32_e32 v59, 0xffff0000, v59
	v_pk_mul_f32 v[60:61], v[54:55], v[60:61]
	v_cvt_pk_bf16_f32 v62, v62, v63
	v_pk_mul_f32 v[58:59], v[50:51], v[58:59]
	v_cvt_pk_bf16_f32 v63, v60, v61
	v_pk_mul_f32 v[66:67], v[48:49], v[66:67]
	v_cvt_pk_bf16_f32 v61, v58, v59
	s_nop 0
	v_cvt_pk_bf16_f32 v60, v66, v67
	v_mov_b32_e32 v194, v62
	v_mov_b32_e32 v195, v63
	v_mov_b32_e32 v196, v60
	v_mov_b32_e32 v197, v61
	v_lshl_add_u64 v[198:199], v[200:201], 0, v[56:57]
	s_nop 0
	v_permlane16_swap_b32 v194, v196
	v_permlane16_swap_b32 v195, v197
	global_store_dwordx4 v[198:199], v[194:197], off

.LBB0_656:
	s_ashr_i32 s33, s67, 2
	s_add_i32 s33, s33, 2
	v_mad_i64_i32 v[66:67], s[56:57], s33, v154, v[64:65]
	v_mov_b32_e32 v123, v153
	v_lshl_add_u64 v[66:67], v[66:67], 0, v[122:123]
	v_cvt_pk_bf16_f32 v62, v62, v63
	v_cvt_pk_bf16_f32 v63, v58, v59
	v_mov_b32_e32 v194, v62
	v_mov_b32_e32 v195, v63
	v_cvt_pk_bf16_f32 v58, v60, v61
	v_cvt_pk_bf16_f32 v59, v56, v57
	v_mov_b32_e32 v196, v58
	v_mov_b32_e32 v197, v59
	v_lshl_add_u64 v[198:199], v[200:201], 0, v[66:67]
	s_nop 0
	v_permlane16_swap_b32 v194, v196
	v_permlane16_swap_b32 v195, v197
	global_store_dwordx4 v[198:199], v[194:197], off

.LBB0_669:
	s_or_b64 exec, exec, s[56:57]
	s_add_i32 s33, s33, 1
	v_mad_i64_i32 v[66:67], s[10:11], s33, v154, v[64:65]
	v_mov_b32_e32 v123, v153
	v_lshl_add_u64 v[66:67], v[66:67], 0, v[122:123]
	v_cvt_pk_bf16_f32 v58, v58, v59
	v_cvt_pk_bf16_f32 v59, v56, v57
	v_mov_b32_e32 v194, v58
	v_mov_b32_e32 v195, v59
	v_cvt_pk_bf16_f32 v56, v62, v63
	v_cvt_pk_bf16_f32 v57, v60, v61
	v_mov_b32_e32 v196, v56
	v_mov_b32_e32 v197, v57
	v_lshl_add_u64 v[198:199], v[200:201], 0, v[66:67]
	s_nop 0
	v_permlane16_swap_b32 v194, v196
	v_permlane16_swap_b32 v195, v197
	global_store_dwordx4 v[198:199], v[194:197], off

.LBB0_681:
	s_andn2_b64 vcc, exec, s[56:57]
	s_cbranch_vccnz .LBB0_683
	s_ashr_i32 s2, s67, 2
	s_add_i32 s2, s2, 1
	v_mad_i64_i32 v[56:57], s[2:3], s2, v154, v[64:65]
	v_mov_b32_e32 v123, v153
	v_lshl_add_u64 v[56:57], v[56:57], 0, v[122:123]
	v_cvt_pk_f16_f32 v55, v54, v55
	v_cvt_pk_f16_f32 v54, v52, v53
	v_cvt_pk_f16_f32 v51, v50, v51
	v_cvt_pk_f16_f32 v50, v48, v49
	v_mov_b32_e32 v194, v54
	v_mov_b32_e32 v195, v55
	v_mov_b32_e32 v196, v50
	v_mov_b32_e32 v197, v51
	v_lshl_add_u64 v[198:199], v[200:201], 0, v[56:57]
	s_nop 0
	v_permlane16_swap_b32 v194, v196
	v_permlane16_swap_b32 v195, v197
	global_store_dwordx4 v[198:199], v[194:197], off
.LBB0_683:
	v_or_b32_e32 v60, s63, v175
	v_ashrrev_i32_e32 v61, 31, v60
	v_lshlrev_b64 v[48:49], 13, v[60:61]
	v_add_u32_e32 v58, 0xffffc000, v60
	v_mov_b32_e32 v59, v153
	v_lshl_add_u64 v[56:57], s[52:53], 0, v[48:49]
	v_cmp_gt_i32_e64 s[10:11], s92, v60
	v_cmp_lt_i32_e64 s[8:9], s80, v60
	v_lshlrev_b64 v[54:55], 10, v[58:59]
	v_lshlrev_b64 v[50:51], 10, v[60:61]
	s_mov_b64 s[58:59], -1
	s_mov_b64 s[56:57], 0
	s_cmp_lt_i32 s79, 22
	s_mov_b64 s[2:3], 0
	s_cbranch_scc1 .LBB0_708
	s_cmp_gt_i32 s79, 23
	s_cbranch_scc0 .LBB0_702
	s_cmp_gt_i32 s79, 24
	s_cbranch_scc0 .LBB0_699
	s_cmp_gt_i32 s79, 25
	s_cbranch_scc0 .LBB0_690
	s_cmp_eq_u32 s79, 26
	s_mov_b64 s[2:3], -1
	s_cbranch_scc0 .LBB0_689
	v_max_f32_e32 v48, v44, v44
	v_max_f32_e32 v49, v40, v40
	v_max_f32_e32 v48, 0, v48
	v_max_f32_e32 v49, 0, v49
	v_mul_f32_e32 v52, v48, v48
	v_mul_f32_e32 v62, v49, v49
	v_max_f32_e32 v48, v45, v45
	v_max_f32_e32 v49, v41, v41
	v_max_f32_e32 v48, 0, v48
	v_max_f32_e32 v49, 0, v49
	v_mul_f32_e32 v53, v48, v48
	v_mul_f32_e32 v63, v49, v49
	v_max_f32_e32 v48, v46, v46
	v_max_f32_e32 v49, v42, v42
	v_max_f32_e32 v48, 0, v48
	v_max_f32_e32 v49, 0, v49
	v_mul_f32_e32 v64, v48, v48
	v_mul_f32_e32 v65, v49, v49
	v_max_f32_e32 v48, v47, v47
	v_max_f32_e32 v49, v43, v43
	v_max_f32_e32 v48, 0, v48
	v_max_f32_e32 v49, 0, v49
	v_ashrrev_i32_e32 v137, 31, v136
	v_mul_f32_e32 v66, v48, v48
	v_mul_f32_e32 v67, v49, v49
	v_lshl_add_u64 v[48:49], v[136:137], 1, v[56:57]
	v_cvt_pk_bf16_f32 v52, v52, v53
	v_cvt_pk_bf16_f32 v53, v64, v66
	s_mov_b64 s[2:3], 0
	v_mov_b32_e32 v194, v52
	v_mov_b32_e32 v195, v53
	v_cvt_pk_bf16_f32 v52, v62, v63
	v_cvt_pk_bf16_f32 v53, v65, v67
	v_mov_b32_e32 v196, v52
	v_mov_b32_e32 v197, v53
	v_lshl_add_u64 v[198:199], v[200:201], 0, v[48:49]
	s_nop 0
	v_permlane16_swap_b32 v194, v196
	v_permlane16_swap_b32 v195, v197
	global_store_dwordx4 v[198:199], v[194:197], off

.LBB0_699:
	s_and_b64 vcc, exec, s[58:59]
	s_cbranch_vccz .LBB0_701
	v_ashrrev_i32_e32 v137, 31, v136
	v_lshl_add_u64 v[48:49], v[50:51], 0, v[136:137]
	v_lshlrev_b64 v[48:49], 1, v[48:49]
	v_lshl_add_u64 v[52:53], s[40:41], 0, v[48:49]
	v_lshl_add_u64 v[48:49], s[36:37], 0, v[48:49]
	global_load_dwordx2 v[62:63], v[52:53], off
	global_load_dwordx2 v[68:69], v[48:49], off
	s_waitcnt vmcnt(0)
	v_lshlrev_b32_e32 v64, 16, v62
	v_and_b32_e32 v65, 0xffff0000, v62
	v_lshlrev_b32_e32 v62, 16, v63
	v_and_b32_e32 v63, 0xffff0000, v63
	v_lshlrev_b32_e32 v70, 16, v68
	v_and_b32_e32 v71, 0xffff0000, v68
	v_lshlrev_b32_e32 v68, 16, v69
	v_and_b32_e32 v69, 0xffff0000, v69
	global_load_dwordx2 v[52:53], v[52:53], off offset:32
	v_pk_fma_f32 v[62:63], v[46:47], v[62:63], v[68:69]
	global_load_dwordx2 v[68:69], v[48:49], off offset:32
	v_pk_fma_f32 v[64:65], v[44:45], v[64:65], v[70:71]
	s_waitcnt vmcnt(1)
	v_lshlrev_b32_e32 v66, 16, v52
	v_and_b32_e32 v67, 0xffff0000, v52
	v_lshlrev_b32_e32 v52, 16, v53
	v_and_b32_e32 v53, 0xffff0000, v53
	s_waitcnt vmcnt(0)
	v_lshlrev_b32_e32 v70, 16, v68
	v_and_b32_e32 v71, 0xffff0000, v68
	v_lshlrev_b32_e32 v68, 16, v69
	v_and_b32_e32 v69, 0xffff0000, v69
	v_pk_fma_f32 v[52:53], v[42:43], v[52:53], v[68:69]
	v_pk_fma_f32 v[66:67], v[40:41], v[66:67], v[70:71]
	v_cvt_pk_bf16_f32 v64, v64, v65
	v_cvt_pk_bf16_f32 v65, v62, v63
	v_mov_b32_e32 v194, v64
	v_mov_b32_e32 v195, v65
	v_cvt_pk_bf16_f32 v62, v66, v67
	v_cvt_pk_bf16_f32 v63, v52, v53
	v_mov_b32_e32 v196, v62
	v_mov_b32_e32 v197, v63
	v_lshl_add_u64 v[198:199], v[200:201], 0, v[48:49]
	s_nop 0
	v_permlane16_swap_b32 v194, v196
	v_permlane16_swap_b32 v195, v197
	global_store_dwordx4 v[198:199], v[194:197], off

.LBB0_702:
	s_and_b64 vcc, exec, s[58:59]
	s_cbranch_vccz .LBB0_707
	s_cmp_gt_i32 s79, 22
	s_mov_b64 s[58:59], -1
	s_cbranch_scc0 .LBB0_705
	v_ashrrev_i32_e32 v137, 31, v136
	v_lshl_add_u64 v[48:49], v[50:51], 0, v[136:137]
	v_lshlrev_b64 v[48:49], 1, v[48:49]
	v_lshl_add_u64 v[52:53], s[34:35], 0, v[48:49]
	v_lshl_add_u64 v[48:49], s[36:37], 0, v[48:49]
	global_load_dwordx2 v[62:63], v[52:53], off
	global_load_dwordx2 v[68:69], v[48:49], off
	s_mov_b64 s[58:59], 0
	global_load_dwordx2 v[52:53], v[52:53], off offset:32
	s_waitcnt vmcnt(0)
	v_lshlrev_b32_e32 v64, 16, v62
	v_and_b32_e32 v65, 0xffff0000, v62
	v_lshlrev_b32_e32 v62, 16, v63
	v_and_b32_e32 v63, 0xffff0000, v63
	v_lshlrev_b32_e32 v70, 16, v68
	v_and_b32_e32 v71, 0xffff0000, v68
	v_lshlrev_b32_e32 v68, 16, v69
	v_and_b32_e32 v69, 0xffff0000, v69
	v_pk_fma_f32 v[62:63], v[46:47], v[62:63], v[68:69]
	global_load_dwordx2 v[68:69], v[48:49], off offset:32
	v_lshlrev_b32_e32 v66, 16, v52
	v_and_b32_e32 v67, 0xffff0000, v52
	v_lshlrev_b32_e32 v52, 16, v53
	v_and_b32_e32 v53, 0xffff0000, v53
	v_pk_fma_f32 v[64:65], v[44:45], v[64:65], v[70:71]
	s_waitcnt vmcnt(0)
	v_lshlrev_b32_e32 v70, 16, v68
	v_and_b32_e32 v71, 0xffff0000, v68
	v_lshlrev_b32_e32 v68, 16, v69
	v_and_b32_e32 v69, 0xffff0000, v69
	v_pk_fma_f32 v[52:53], v[42:43], v[52:53], v[68:69]
	v_pk_fma_f32 v[66:67], v[40:41], v[66:67], v[70:71]
	v_cvt_pk_bf16_f32 v64, v64, v65
	v_cvt_pk_bf16_f32 v65, v62, v63
	v_mov_b32_e32 v194, v64
	v_mov_b32_e32 v195, v65
	v_cvt_pk_bf16_f32 v62, v66, v67
	v_cvt_pk_bf16_f32 v63, v52, v53
	v_mov_b32_e32 v196, v62
	v_mov_b32_e32 v197, v63
	v_lshl_add_u64 v[198:199], v[200:201], 0, v[48:49]
	s_nop 0
	v_permlane16_swap_b32 v194, v196
	v_permlane16_swap_b32 v195, v197
	global_store_dwordx4 v[198:199], v[194:197], off
.LBB0_705:
	s_andn2_b64 vcc, exec, s[58:59]
	s_cbranch_vccnz .LBB0_707
	v_ashrrev_i32_e32 v137, 31, v136
	v_lshl_add_u64 v[48:49], v[50:51], 0, v[136:137]
	v_lshlrev_b64 v[48:49], 1, v[48:49]
	v_lshl_add_u64 v[52:53], s[38:39], 0, v[48:49]
	global_load_dwordx2 v[62:63], v[52:53], off
	s_nop 0
	global_load_dwordx2 v[52:53], v[52:53], off offset:32
	v_lshl_add_u64 v[48:49], s[36:37], 0, v[48:49]
	s_waitcnt vmcnt(0)
	v_lshlrev_b32_e32 v64, 16, v62
	v_and_b32_e32 v65, 0xffff0000, v62
	v_lshlrev_b32_e32 v62, 16, v63
	v_and_b32_e32 v63, 0xffff0000, v63
	v_pk_mul_f32 v[64:65], v[44:45], v[64:65]
	v_lshlrev_b32_e32 v66, 16, v52
	v_and_b32_e32 v67, 0xffff0000, v52
	v_lshlrev_b32_e32 v52, 16, v53
	v_and_b32_e32 v53, 0xffff0000, v53
	v_pk_mul_f32 v[62:63], v[46:47], v[62:63]
	v_cvt_pk_bf16_f32 v64, v64, v65
	v_pk_mul_f32 v[52:53], v[42:43], v[52:53]
	v_cvt_pk_bf16_f32 v65, v62, v63
	v_pk_mul_f32 v[66:67], v[40:41], v[66:67]
	v_cvt_pk_bf16_f32 v63, v52, v53
	s_nop 0
	v_cvt_pk_bf16_f32 v62, v66, v67
	v_mov_b32_e32 v194, v64
	v_mov_b32_e32 v195, v65
	v_mov_b32_e32 v196, v62
	v_mov_b32_e32 v197, v63
	v_lshl_add_u64 v[198:199], v[200:201], 0, v[48:49]
	s_nop 0
	v_permlane16_swap_b32 v194, v196
	v_permlane16_swap_b32 v195, v197
	global_store_dwordx4 v[198:199], v[194:197], off

.LBB0_715:
	s_ashr_i32 s33, s67, 2
	s_add_i32 s33, s33, 2
	v_mad_i64_i32 v[72:73], s[56:57], s33, v154, v[48:49]
	v_mov_b32_e32 v139, v153
	v_lshl_add_u64 v[72:73], v[72:73], 0, v[138:139]
	v_cvt_pk_bf16_f32 v68, v68, v69
	v_cvt_pk_bf16_f32 v69, v64, v65
	v_mov_b32_e32 v194, v68
	v_mov_b32_e32 v195, v69
	v_cvt_pk_bf16_f32 v64, v66, v67
	v_cvt_pk_bf16_f32 v65, v62, v63
	v_mov_b32_e32 v196, v64
	v_mov_b32_e32 v197, v65
	v_lshl_add_u64 v[198:199], v[200:201], 0, v[72:73]
	s_nop 0
	v_permlane16_swap_b32 v194, v196
	v_permlane16_swap_b32 v195, v197
	global_store_dwordx4 v[198:199], v[194:197], off

.LBB0_728:
	s_or_b64 exec, exec, s[56:57]
	s_add_i32 s33, s33, 1
	v_mad_i64_i32 v[72:73], s[56:57], s33, v154, v[48:49]
	v_mov_b32_e32 v139, v153
	v_lshl_add_u64 v[72:73], v[72:73], 0, v[138:139]
	v_cvt_pk_bf16_f32 v64, v64, v65
	v_cvt_pk_bf16_f32 v65, v62, v63
	v_mov_b32_e32 v194, v64
	v_mov_b32_e32 v195, v65
	v_cvt_pk_bf16_f32 v62, v68, v69
	v_cvt_pk_bf16_f32 v63, v66, v67
	v_mov_b32_e32 v196, v62
	v_mov_b32_e32 v197, v63
	v_lshl_add_u64 v[198:199], v[200:201], 0, v[72:73]
	s_nop 0
	v_permlane16_swap_b32 v194, v196
	v_permlane16_swap_b32 v195, v197
	global_store_dwordx4 v[198:199], v[194:197], off

.LBB0_740:
	s_andn2_b64 vcc, exec, s[56:57]
	s_cbranch_vccnz .LBB0_742
	s_ashr_i32 s2, s67, 2
	s_add_i32 s2, s2, 1
	v_mad_i64_i32 v[62:63], s[2:3], s2, v154, v[48:49]
	v_mov_b32_e32 v139, v153
	v_lshl_add_u64 v[62:63], v[62:63], 0, v[138:139]
	v_cvt_pk_f16_f32 v47, v46, v47
	v_cvt_pk_f16_f32 v46, v44, v45
	v_cvt_pk_f16_f32 v43, v42, v43
	v_cvt_pk_f16_f32 v42, v40, v41
	v_mov_b32_e32 v194, v46
	v_mov_b32_e32 v195, v47
	v_mov_b32_e32 v196, v42
	v_mov_b32_e32 v197, v43
	v_lshl_add_u64 v[198:199], v[200:201], 0, v[62:63]
	s_nop 0
	v_permlane16_swap_b32 v194, v196
	v_permlane16_swap_b32 v195, v197
	global_store_dwordx4 v[198:199], v[194:197], off
.LBB0_742:
	s_mov_b64 s[58:59], -1
	s_mov_b64 s[56:57], 0
	s_cmp_lt_i32 s79, 22
	s_mov_b64 s[2:3], 0
	s_cbranch_scc1 .LBB0_767
	s_cmp_gt_i32 s79, 23
	s_cbranch_scc0 .LBB0_761
	s_cmp_gt_i32 s79, 24
	s_cbranch_scc0 .LBB0_758
	s_cmp_gt_i32 s79, 25
	s_cbranch_scc0 .LBB0_749
	s_cmp_eq_u32 s79, 26
	s_mov_b64 s[2:3], -1
	s_cbranch_scc0 .LBB0_748
	v_max_f32_e32 v40, v36, v36
	v_max_f32_e32 v41, v32, v32
	v_max_f32_e32 v40, 0, v40
	v_max_f32_e32 v41, 0, v41
	v_mul_f32_e32 v42, v40, v40
	v_mul_f32_e32 v44, v41, v41
	v_max_f32_e32 v40, v37, v37
	v_max_f32_e32 v41, v33, v33
	v_max_f32_e32 v40, 0, v40
	v_max_f32_e32 v41, 0, v41
	v_mul_f32_e32 v43, v40, v40
	v_mul_f32_e32 v45, v41, v41
	v_max_f32_e32 v40, v38, v38
	v_max_f32_e32 v41, v34, v34
	v_max_f32_e32 v40, 0, v40
	v_max_f32_e32 v41, 0, v41
	v_mul_f32_e32 v46, v40, v40
	v_mul_f32_e32 v47, v41, v41
	v_max_f32_e32 v40, v39, v39
	v_max_f32_e32 v41, v35, v35
	v_max_f32_e32 v40, 0, v40
	v_max_f32_e32 v41, 0, v41
	v_ashrrev_i32_e32 v137, 31, v136
	v_mul_f32_e32 v62, v40, v40
	v_mul_f32_e32 v63, v41, v41
	v_lshl_add_u64 v[40:41], v[136:137], 1, v[56:57]
	v_cvt_pk_bf16_f32 v42, v42, v43
	v_cvt_pk_bf16_f32 v43, v46, v62
	s_mov_b64 s[2:3], 0
	v_mov_b32_e32 v194, v42
	v_mov_b32_e32 v195, v43
	v_cvt_pk_bf16_f32 v42, v44, v45
	v_cvt_pk_bf16_f32 v43, v47, v63
	v_mov_b32_e32 v196, v42
	v_mov_b32_e32 v197, v43
	v_lshl_add_u64 v[198:199], v[200:201], 0, v[40:41]
	s_nop 0
	v_permlane16_swap_b32 v194, v196
	v_permlane16_swap_b32 v195, v197
	global_store_dwordx4 v[198:199], v[194:197], off offset:256

.LBB0_758:
	s_and_b64 vcc, exec, s[58:59]
	s_cbranch_vccz .LBB0_760
	v_ashrrev_i32_e32 v121, 31, v120
	v_lshl_add_u64 v[40:41], v[50:51], 0, v[120:121]
	v_lshlrev_b64 v[40:41], 1, v[40:41]
	v_lshl_add_u64 v[42:43], s[40:41], 0, v[40:41]
	v_lshl_add_u64 v[40:41], s[36:37], 0, v[40:41]
	global_load_dwordx2 v[44:45], v[42:43], off
	global_load_dwordx2 v[56:57], v[40:41], off
	s_waitcnt vmcnt(0)
	v_lshlrev_b32_e32 v46, 16, v44
	v_and_b32_e32 v47, 0xffff0000, v44
	v_lshlrev_b32_e32 v44, 16, v45
	v_and_b32_e32 v45, 0xffff0000, v45
	v_lshlrev_b32_e32 v62, 16, v56
	v_and_b32_e32 v63, 0xffff0000, v56
	v_lshlrev_b32_e32 v56, 16, v57
	v_and_b32_e32 v57, 0xffff0000, v57
	global_load_dwordx2 v[42:43], v[42:43], off offset:32
	v_pk_fma_f32 v[44:45], v[38:39], v[44:45], v[56:57]
	global_load_dwordx2 v[56:57], v[40:41], off offset:32
	v_pk_fma_f32 v[46:47], v[36:37], v[46:47], v[62:63]
	s_waitcnt vmcnt(1)
	v_lshlrev_b32_e32 v54, 16, v42
	v_and_b32_e32 v55, 0xffff0000, v42
	v_lshlrev_b32_e32 v42, 16, v43
	v_and_b32_e32 v43, 0xffff0000, v43
	s_waitcnt vmcnt(0)
	v_lshlrev_b32_e32 v62, 16, v56
	v_and_b32_e32 v63, 0xffff0000, v56
	v_lshlrev_b32_e32 v56, 16, v57
	v_and_b32_e32 v57, 0xffff0000, v57
	v_pk_fma_f32 v[42:43], v[34:35], v[42:43], v[56:57]
	v_pk_fma_f32 v[54:55], v[32:33], v[54:55], v[62:63]
	v_cvt_pk_bf16_f32 v46, v46, v47
	v_cvt_pk_bf16_f32 v47, v44, v45
	v_mov_b32_e32 v194, v46
	v_mov_b32_e32 v195, v47
	v_cvt_pk_bf16_f32 v44, v54, v55
	v_cvt_pk_bf16_f32 v45, v42, v43
	v_mov_b32_e32 v196, v44
	v_mov_b32_e32 v197, v45
	v_lshl_add_u64 v[198:199], v[200:201], 0, v[40:41]
	s_nop 0
	v_permlane16_swap_b32 v194, v196
	v_permlane16_swap_b32 v195, v197
	global_store_dwordx4 v[198:199], v[194:197], off

.LBB0_761:
	s_and_b64 vcc, exec, s[58:59]
	s_cbranch_vccz .LBB0_766
	s_cmp_gt_i32 s79, 22
	s_mov_b64 s[58:59], -1
	s_cbranch_scc0 .LBB0_764
	v_ashrrev_i32_e32 v121, 31, v120
	v_lshl_add_u64 v[40:41], v[50:51], 0, v[120:121]
	v_lshlrev_b64 v[40:41], 1, v[40:41]
	v_lshl_add_u64 v[42:43], s[34:35], 0, v[40:41]
	v_lshl_add_u64 v[40:41], s[36:37], 0, v[40:41]
	global_load_dwordx2 v[44:45], v[42:43], off
	global_load_dwordx2 v[56:57], v[40:41], off
	s_mov_b64 s[58:59], 0
	global_load_dwordx2 v[42:43], v[42:43], off offset:32
	s_waitcnt vmcnt(0)
	v_lshlrev_b32_e32 v46, 16, v44
	v_and_b32_e32 v47, 0xffff0000, v44
	v_lshlrev_b32_e32 v44, 16, v45
	v_and_b32_e32 v45, 0xffff0000, v45
	v_lshlrev_b32_e32 v62, 16, v56
	v_and_b32_e32 v63, 0xffff0000, v56
	v_lshlrev_b32_e32 v56, 16, v57
	v_and_b32_e32 v57, 0xffff0000, v57
	v_pk_fma_f32 v[44:45], v[38:39], v[44:45], v[56:57]
	global_load_dwordx2 v[56:57], v[40:41], off offset:32
	v_lshlrev_b32_e32 v54, 16, v42
	v_and_b32_e32 v55, 0xffff0000, v42
	v_lshlrev_b32_e32 v42, 16, v43
	v_and_b32_e32 v43, 0xffff0000, v43
	v_pk_fma_f32 v[46:47], v[36:37], v[46:47], v[62:63]
	s_waitcnt vmcnt(0)
	v_lshlrev_b32_e32 v62, 16, v56
	v_and_b32_e32 v63, 0xffff0000, v56
	v_lshlrev_b32_e32 v56, 16, v57
	v_and_b32_e32 v57, 0xffff0000, v57
	v_pk_fma_f32 v[42:43], v[34:35], v[42:43], v[56:57]
	v_pk_fma_f32 v[54:55], v[32:33], v[54:55], v[62:63]
	v_cvt_pk_bf16_f32 v46, v46, v47
	v_cvt_pk_bf16_f32 v47, v44, v45
	v_mov_b32_e32 v194, v46
	v_mov_b32_e32 v195, v47
	v_cvt_pk_bf16_f32 v44, v54, v55
	v_cvt_pk_bf16_f32 v45, v42, v43
	v_mov_b32_e32 v196, v44
	v_mov_b32_e32 v197, v45
	v_lshl_add_u64 v[198:199], v[200:201], 0, v[40:41]
	s_nop 0
	v_permlane16_swap_b32 v194, v196
	v_permlane16_swap_b32 v195, v197
	global_store_dwordx4 v[198:199], v[194:197], off
.LBB0_764:
	s_andn2_b64 vcc, exec, s[58:59]
	s_cbranch_vccnz .LBB0_766
	v_ashrrev_i32_e32 v121, 31, v120
	v_lshl_add_u64 v[40:41], v[50:51], 0, v[120:121]
	v_lshlrev_b64 v[40:41], 1, v[40:41]
	v_lshl_add_u64 v[42:43], s[38:39], 0, v[40:41]
	global_load_dwordx2 v[44:45], v[42:43], off
	s_nop 0
	global_load_dwordx2 v[42:43], v[42:43], off offset:32
	v_lshl_add_u64 v[40:41], s[36:37], 0, v[40:41]
	s_waitcnt vmcnt(0)
	v_lshlrev_b32_e32 v46, 16, v44
	v_and_b32_e32 v47, 0xffff0000, v44
	v_lshlrev_b32_e32 v44, 16, v45
	v_and_b32_e32 v45, 0xffff0000, v45
	v_pk_mul_f32 v[46:47], v[36:37], v[46:47]
	v_lshlrev_b32_e32 v50, 16, v42
	v_and_b32_e32 v51, 0xffff0000, v42
	v_lshlrev_b32_e32 v42, 16, v43
	v_and_b32_e32 v43, 0xffff0000, v43
	v_pk_mul_f32 v[44:45], v[38:39], v[44:45]
	v_cvt_pk_bf16_f32 v46, v46, v47
	v_pk_mul_f32 v[42:43], v[34:35], v[42:43]
	v_cvt_pk_bf16_f32 v47, v44, v45
	v_pk_mul_f32 v[50:51], v[32:33], v[50:51]
	v_cvt_pk_bf16_f32 v45, v42, v43
	s_nop 0
	v_cvt_pk_bf16_f32 v44, v50, v51
	v_mov_b32_e32 v194, v46
	v_mov_b32_e32 v195, v47
	v_mov_b32_e32 v196, v44
	v_mov_b32_e32 v197, v45
	v_lshl_add_u64 v[198:199], v[200:201], 0, v[40:41]
	s_nop 0
	v_permlane16_swap_b32 v194, v196
	v_permlane16_swap_b32 v195, v197
	global_store_dwordx4 v[198:199], v[194:197], off

.LBB0_774:
	s_ashr_i32 s33, s67, 2
	s_add_i32 s33, s33, 2
	v_mad_i64_i32 v[50:51], s[56:57], s33, v154, v[48:49]
	v_mov_b32_e32 v123, v153
	v_lshl_add_u64 v[50:51], v[50:51], 0, v[122:123]
	v_cvt_pk_bf16_f32 v46, v46, v47
	v_cvt_pk_bf16_f32 v47, v42, v43
	v_mov_b32_e32 v194, v46
	v_mov_b32_e32 v195, v47
	v_cvt_pk_bf16_f32 v42, v44, v45
	v_cvt_pk_bf16_f32 v43, v40, v41
	v_mov_b32_e32 v196, v42
	v_mov_b32_e32 v197, v43
	v_lshl_add_u64 v[198:199], v[200:201], 0, v[50:51]
	s_nop 0
	v_permlane16_swap_b32 v194, v196
	v_permlane16_swap_b32 v195, v197
	global_store_dwordx4 v[198:199], v[194:197], off

.LBB0_787:
	s_or_b64 exec, exec, s[56:57]
	s_add_i32 s33, s33, 1
	v_mad_i64_i32 v[50:51], s[10:11], s33, v154, v[48:49]
	v_mov_b32_e32 v123, v153
	v_lshl_add_u64 v[50:51], v[50:51], 0, v[122:123]
	v_cvt_pk_bf16_f32 v42, v42, v43
	v_cvt_pk_bf16_f32 v43, v40, v41
	v_mov_b32_e32 v194, v42
	v_mov_b32_e32 v195, v43
	v_cvt_pk_bf16_f32 v40, v46, v47
	v_cvt_pk_bf16_f32 v41, v44, v45
	v_mov_b32_e32 v196, v40
	v_mov_b32_e32 v197, v41
	v_lshl_add_u64 v[198:199], v[200:201], 0, v[50:51]
	s_nop 0
	v_permlane16_swap_b32 v194, v196
	v_permlane16_swap_b32 v195, v197
	global_store_dwordx4 v[198:199], v[194:197], off

.LBB0_799:
	s_andn2_b64 vcc, exec, s[56:57]
	s_cbranch_vccnz .LBB0_801
	s_ashr_i32 s2, s67, 2
	s_add_i32 s2, s2, 1
	v_mad_i64_i32 v[40:41], s[2:3], s2, v154, v[48:49]
	v_mov_b32_e32 v123, v153
	v_lshl_add_u64 v[40:41], v[40:41], 0, v[122:123]
	v_cvt_pk_f16_f32 v39, v38, v39
	v_cvt_pk_f16_f32 v38, v36, v37
	v_cvt_pk_f16_f32 v35, v34, v35
	v_cvt_pk_f16_f32 v34, v32, v33
	v_mov_b32_e32 v194, v38
	v_mov_b32_e32 v195, v39
	v_mov_b32_e32 v196, v34
	v_mov_b32_e32 v197, v35
	v_lshl_add_u64 v[198:199], v[200:201], 0, v[40:41]
	s_nop 0
	v_permlane16_swap_b32 v194, v196
	v_permlane16_swap_b32 v195, v197
	global_store_dwordx4 v[198:199], v[194:197], off
.LBB0_801:
	v_or_b32_e32 v44, s63, v176
	v_ashrrev_i32_e32 v45, 31, v44
	v_lshlrev_b64 v[32:33], 13, v[44:45]
	v_add_u32_e32 v42, 0xffffc000, v44
	v_mov_b32_e32 v43, v153
	v_lshl_add_u64 v[40:41], s[52:53], 0, v[32:33]
	v_cmp_gt_i32_e64 s[10:11], s92, v44
	v_cmp_lt_i32_e64 s[8:9], s80, v44
	v_lshlrev_b64 v[38:39], 10, v[42:43]
	v_lshlrev_b64 v[34:35], 10, v[44:45]
	s_mov_b64 s[58:59], -1
	s_mov_b64 s[56:57], 0
	s_cmp_lt_i32 s79, 22
	s_mov_b64 s[2:3], 0
	s_cbranch_scc1 .LBB0_826
	s_cmp_gt_i32 s79, 23
	s_cbranch_scc0 .LBB0_820
	s_cmp_gt_i32 s79, 24
	s_cbranch_scc0 .LBB0_817
	s_cmp_gt_i32 s79, 25
	s_cbranch_scc0 .LBB0_808
	s_cmp_eq_u32 s79, 26
	s_mov_b64 s[2:3], -1
	s_cbranch_scc0 .LBB0_807
	v_max_f32_e32 v32, v28, v28
	v_max_f32_e32 v33, v24, v24
	v_max_f32_e32 v32, 0, v32
	v_max_f32_e32 v33, 0, v33
	v_mul_f32_e32 v36, v32, v32
	v_mul_f32_e32 v46, v33, v33
	v_max_f32_e32 v32, v29, v29
	v_max_f32_e32 v33, v25, v25
	v_max_f32_e32 v32, 0, v32
	v_max_f32_e32 v33, 0, v33
	v_mul_f32_e32 v37, v32, v32
	v_mul_f32_e32 v47, v33, v33
	v_max_f32_e32 v32, v30, v30
	v_max_f32_e32 v33, v26, v26
	v_max_f32_e32 v32, 0, v32
	v_max_f32_e32 v33, 0, v33
	v_mul_f32_e32 v48, v32, v32
	v_mul_f32_e32 v49, v33, v33
	v_max_f32_e32 v32, v31, v31
	v_max_f32_e32 v33, v27, v27
	v_max_f32_e32 v32, 0, v32
	v_max_f32_e32 v33, 0, v33
	v_ashrrev_i32_e32 v137, 31, v136
	v_mul_f32_e32 v50, v32, v32
	v_mul_f32_e32 v51, v33, v33
	v_lshl_add_u64 v[32:33], v[136:137], 1, v[40:41]
	v_cvt_pk_bf16_f32 v36, v36, v37
	v_cvt_pk_bf16_f32 v37, v48, v50
	s_mov_b64 s[2:3], 0
	v_mov_b32_e32 v194, v36
	v_mov_b32_e32 v195, v37
	v_cvt_pk_bf16_f32 v36, v46, v47
	v_cvt_pk_bf16_f32 v37, v49, v51
	v_mov_b32_e32 v196, v36
	v_mov_b32_e32 v197, v37
	v_lshl_add_u64 v[198:199], v[200:201], 0, v[32:33]
	s_nop 0
	v_permlane16_swap_b32 v194, v196
	v_permlane16_swap_b32 v195, v197
	global_store_dwordx4 v[198:199], v[194:197], off

.LBB0_817:
	s_and_b64 vcc, exec, s[58:59]
	s_cbranch_vccz .LBB0_819
	v_ashrrev_i32_e32 v137, 31, v136
	v_lshl_add_u64 v[32:33], v[34:35], 0, v[136:137]
	v_lshlrev_b64 v[32:33], 1, v[32:33]
	v_lshl_add_u64 v[36:37], s[40:41], 0, v[32:33]
	v_lshl_add_u64 v[32:33], s[36:37], 0, v[32:33]
	global_load_dwordx2 v[46:47], v[36:37], off
	global_load_dwordx2 v[52:53], v[32:33], off
	s_waitcnt vmcnt(0)
	v_lshlrev_b32_e32 v48, 16, v46
	v_and_b32_e32 v49, 0xffff0000, v46
	v_lshlrev_b32_e32 v46, 16, v47
	v_and_b32_e32 v47, 0xffff0000, v47
	v_lshlrev_b32_e32 v54, 16, v52
	v_and_b32_e32 v55, 0xffff0000, v52
	v_lshlrev_b32_e32 v52, 16, v53
	v_and_b32_e32 v53, 0xffff0000, v53
	global_load_dwordx2 v[36:37], v[36:37], off offset:32
	v_pk_fma_f32 v[46:47], v[30:31], v[46:47], v[52:53]
	global_load_dwordx2 v[52:53], v[32:33], off offset:32
	v_pk_fma_f32 v[48:49], v[28:29], v[48:49], v[54:55]
	s_waitcnt vmcnt(1)
	v_lshlrev_b32_e32 v50, 16, v36
	v_and_b32_e32 v51, 0xffff0000, v36
	v_lshlrev_b32_e32 v36, 16, v37
	v_and_b32_e32 v37, 0xffff0000, v37
	s_waitcnt vmcnt(0)
	v_lshlrev_b32_e32 v54, 16, v52
	v_and_b32_e32 v55, 0xffff0000, v52
	v_lshlrev_b32_e32 v52, 16, v53
	v_and_b32_e32 v53, 0xffff0000, v53
	v_pk_fma_f32 v[36:37], v[26:27], v[36:37], v[52:53]
	v_pk_fma_f32 v[50:51], v[24:25], v[50:51], v[54:55]
	v_cvt_pk_bf16_f32 v48, v48, v49
	v_cvt_pk_bf16_f32 v49, v46, v47
	v_mov_b32_e32 v194, v48
	v_mov_b32_e32 v195, v49
	v_cvt_pk_bf16_f32 v46, v50, v51
	v_cvt_pk_bf16_f32 v47, v36, v37
	v_mov_b32_e32 v196, v46
	v_mov_b32_e32 v197, v47
	v_lshl_add_u64 v[198:199], v[200:201], 0, v[32:33]
	s_nop 0
	v_permlane16_swap_b32 v194, v196
	v_permlane16_swap_b32 v195, v197
	global_store_dwordx4 v[198:199], v[194:197], off

.LBB0_820:
	s_and_b64 vcc, exec, s[58:59]
	s_cbranch_vccz .LBB0_825
	s_cmp_gt_i32 s79, 22
	s_mov_b64 s[58:59], -1
	s_cbranch_scc0 .LBB0_823
	v_ashrrev_i32_e32 v137, 31, v136
	v_lshl_add_u64 v[32:33], v[34:35], 0, v[136:137]
	v_lshlrev_b64 v[32:33], 1, v[32:33]
	v_lshl_add_u64 v[36:37], s[34:35], 0, v[32:33]
	v_lshl_add_u64 v[32:33], s[36:37], 0, v[32:33]
	global_load_dwordx2 v[46:47], v[36:37], off
	global_load_dwordx2 v[52:53], v[32:33], off
	s_mov_b64 s[58:59], 0
	global_load_dwordx2 v[36:37], v[36:37], off offset:32
	s_waitcnt vmcnt(0)
	v_lshlrev_b32_e32 v48, 16, v46
	v_and_b32_e32 v49, 0xffff0000, v46
	v_lshlrev_b32_e32 v46, 16, v47
	v_and_b32_e32 v47, 0xffff0000, v47
	v_lshlrev_b32_e32 v54, 16, v52
	v_and_b32_e32 v55, 0xffff0000, v52
	v_lshlrev_b32_e32 v52, 16, v53
	v_and_b32_e32 v53, 0xffff0000, v53
	v_pk_fma_f32 v[46:47], v[30:31], v[46:47], v[52:53]
	global_load_dwordx2 v[52:53], v[32:33], off offset:32
	v_lshlrev_b32_e32 v50, 16, v36
	v_and_b32_e32 v51, 0xffff0000, v36
	v_lshlrev_b32_e32 v36, 16, v37
	v_and_b32_e32 v37, 0xffff0000, v37
	v_pk_fma_f32 v[48:49], v[28:29], v[48:49], v[54:55]
	s_waitcnt vmcnt(0)
	v_lshlrev_b32_e32 v54, 16, v52
	v_and_b32_e32 v55, 0xffff0000, v52
	v_lshlrev_b32_e32 v52, 16, v53
	v_and_b32_e32 v53, 0xffff0000, v53
	v_pk_fma_f32 v[36:37], v[26:27], v[36:37], v[52:53]
	v_pk_fma_f32 v[50:51], v[24:25], v[50:51], v[54:55]
	v_cvt_pk_bf16_f32 v48, v48, v49
	v_cvt_pk_bf16_f32 v49, v46, v47
	v_mov_b32_e32 v194, v48
	v_mov_b32_e32 v195, v49
	v_cvt_pk_bf16_f32 v46, v50, v51
	v_cvt_pk_bf16_f32 v47, v36, v37
	v_mov_b32_e32 v196, v46
	v_mov_b32_e32 v197, v47
	v_lshl_add_u64 v[198:199], v[200:201], 0, v[32:33]
	s_nop 0
	v_permlane16_swap_b32 v194, v196
	v_permlane16_swap_b32 v195, v197
	global_store_dwordx4 v[198:199], v[194:197], off
.LBB0_823:
	s_andn2_b64 vcc, exec, s[58:59]
	s_cbranch_vccnz .LBB0_825
	v_ashrrev_i32_e32 v137, 31, v136
	v_lshl_add_u64 v[32:33], v[34:35], 0, v[136:137]
	v_lshlrev_b64 v[32:33], 1, v[32:33]
	v_lshl_add_u64 v[36:37], s[38:39], 0, v[32:33]
	global_load_dwordx2 v[46:47], v[36:37], off
	s_nop 0
	global_load_dwordx2 v[36:37], v[36:37], off offset:32
	v_lshl_add_u64 v[32:33], s[36:37], 0, v[32:33]
	s_waitcnt vmcnt(0)
	v_lshlrev_b32_e32 v48, 16, v46
	v_and_b32_e32 v49, 0xffff0000, v46
	v_lshlrev_b32_e32 v46, 16, v47
	v_and_b32_e32 v47, 0xffff0000, v47
	v_pk_mul_f32 v[48:49], v[28:29], v[48:49]
	v_lshlrev_b32_e32 v50, 16, v36
	v_and_b32_e32 v51, 0xffff0000, v36
	v_lshlrev_b32_e32 v36, 16, v37
	v_and_b32_e32 v37, 0xffff0000, v37
	v_pk_mul_f32 v[46:47], v[30:31], v[46:47]
	v_cvt_pk_bf16_f32 v48, v48, v49
	v_pk_mul_f32 v[36:37], v[26:27], v[36:37]
	v_cvt_pk_bf16_f32 v49, v46, v47
	v_pk_mul_f32 v[50:51], v[24:25], v[50:51]
	v_cvt_pk_bf16_f32 v47, v36, v37
	s_nop 0
	v_cvt_pk_bf16_f32 v46, v50, v51
	v_mov_b32_e32 v194, v48
	v_mov_b32_e32 v195, v49
	v_mov_b32_e32 v196, v46
	v_mov_b32_e32 v197, v47
	v_lshl_add_u64 v[198:199], v[200:201], 0, v[32:33]
	s_nop 0
	v_permlane16_swap_b32 v194, v196
	v_permlane16_swap_b32 v195, v197
	global_store_dwordx4 v[198:199], v[194:197], off

.LBB0_833:
	s_ashr_i32 s33, s67, 2
	s_add_i32 s33, s33, 2
	v_mad_i64_i32 v[56:57], s[56:57], s33, v154, v[32:33]
	v_mov_b32_e32 v139, v153
	v_lshl_add_u64 v[56:57], v[56:57], 0, v[138:139]
	v_cvt_pk_bf16_f32 v52, v52, v53
	v_cvt_pk_bf16_f32 v53, v48, v49
	v_mov_b32_e32 v194, v52
	v_mov_b32_e32 v195, v53
	v_cvt_pk_bf16_f32 v48, v50, v51
	v_cvt_pk_bf16_f32 v49, v46, v47
	v_mov_b32_e32 v196, v48
	v_mov_b32_e32 v197, v49
	v_lshl_add_u64 v[198:199], v[200:201], 0, v[56:57]
	s_nop 0
	v_permlane16_swap_b32 v194, v196
	v_permlane16_swap_b32 v195, v197
	global_store_dwordx4 v[198:199], v[194:197], off

.LBB0_846:
	s_or_b64 exec, exec, s[56:57]
	s_add_i32 s33, s33, 1
	v_mad_i64_i32 v[56:57], s[56:57], s33, v154, v[32:33]
	v_mov_b32_e32 v139, v153
	v_lshl_add_u64 v[56:57], v[56:57], 0, v[138:139]
	v_cvt_pk_bf16_f32 v48, v48, v49
	v_cvt_pk_bf16_f32 v49, v46, v47
	v_mov_b32_e32 v194, v48
	v_mov_b32_e32 v195, v49
	v_cvt_pk_bf16_f32 v46, v52, v53
	v_cvt_pk_bf16_f32 v47, v50, v51
	v_mov_b32_e32 v196, v46
	v_mov_b32_e32 v197, v47
	v_lshl_add_u64 v[198:199], v[200:201], 0, v[56:57]
	s_nop 0
	v_permlane16_swap_b32 v194, v196
	v_permlane16_swap_b32 v195, v197
	global_store_dwordx4 v[198:199], v[194:197], off

.LBB0_858:
	s_andn2_b64 vcc, exec, s[56:57]
	s_cbranch_vccnz .LBB0_860
	s_ashr_i32 s2, s67, 2
	s_add_i32 s2, s2, 1
	v_mad_i64_i32 v[46:47], s[2:3], s2, v154, v[32:33]
	v_mov_b32_e32 v139, v153
	v_lshl_add_u64 v[46:47], v[46:47], 0, v[138:139]
	v_cvt_pk_f16_f32 v31, v30, v31
	v_cvt_pk_f16_f32 v30, v28, v29
	v_cvt_pk_f16_f32 v27, v26, v27
	v_cvt_pk_f16_f32 v26, v24, v25
	v_mov_b32_e32 v194, v30
	v_mov_b32_e32 v195, v31
	v_mov_b32_e32 v196, v26
	v_mov_b32_e32 v197, v27
	v_lshl_add_u64 v[198:199], v[200:201], 0, v[46:47]
	s_nop 0
	v_permlane16_swap_b32 v194, v196
	v_permlane16_swap_b32 v195, v197
	global_store_dwordx4 v[198:199], v[194:197], off
.LBB0_860:
	s_mov_b64 s[58:59], -1
	s_mov_b64 s[56:57], 0
	s_cmp_lt_i32 s79, 22
	s_mov_b64 s[2:3], 0
	s_cbranch_scc1 .LBB0_885
	s_cmp_gt_i32 s79, 23
	s_cbranch_scc0 .LBB0_879
	s_cmp_gt_i32 s79, 24
	s_cbranch_scc0 .LBB0_876
	s_cmp_gt_i32 s79, 25
	s_cbranch_scc0 .LBB0_867
	s_cmp_eq_u32 s79, 26
	s_mov_b64 s[2:3], -1
	s_cbranch_scc0 .LBB0_866
	v_max_f32_e32 v24, v20, v20
	v_max_f32_e32 v25, v16, v16
	v_max_f32_e32 v24, 0, v24
	v_max_f32_e32 v25, 0, v25
	v_mul_f32_e32 v26, v24, v24
	v_mul_f32_e32 v28, v25, v25
	v_max_f32_e32 v24, v21, v21
	v_max_f32_e32 v25, v17, v17
	v_max_f32_e32 v24, 0, v24
	v_max_f32_e32 v25, 0, v25
	v_mul_f32_e32 v27, v24, v24
	v_mul_f32_e32 v29, v25, v25
	v_max_f32_e32 v24, v22, v22
	v_max_f32_e32 v25, v18, v18
	v_max_f32_e32 v24, 0, v24
	v_max_f32_e32 v25, 0, v25
	v_mul_f32_e32 v30, v24, v24
	v_mul_f32_e32 v31, v25, v25
	v_max_f32_e32 v24, v23, v23
	v_max_f32_e32 v25, v19, v19
	v_max_f32_e32 v24, 0, v24
	v_max_f32_e32 v25, 0, v25
	v_ashrrev_i32_e32 v137, 31, v136
	v_mul_f32_e32 v46, v24, v24
	v_mul_f32_e32 v47, v25, v25
	v_lshl_add_u64 v[24:25], v[136:137], 1, v[40:41]
	v_cvt_pk_bf16_f32 v26, v26, v27
	v_cvt_pk_bf16_f32 v27, v30, v46
	s_mov_b64 s[2:3], 0
	v_mov_b32_e32 v194, v26
	v_mov_b32_e32 v195, v27
	v_cvt_pk_bf16_f32 v26, v28, v29
	v_cvt_pk_bf16_f32 v27, v31, v47
	v_mov_b32_e32 v196, v26
	v_mov_b32_e32 v197, v27
	v_lshl_add_u64 v[198:199], v[200:201], 0, v[24:25]
	s_nop 0
	v_permlane16_swap_b32 v194, v196
	v_permlane16_swap_b32 v195, v197
	global_store_dwordx4 v[198:199], v[194:197], off offset:256

.LBB0_876:
	s_and_b64 vcc, exec, s[58:59]
	s_cbranch_vccz .LBB0_878
	v_ashrrev_i32_e32 v121, 31, v120
	v_lshl_add_u64 v[24:25], v[34:35], 0, v[120:121]
	v_lshlrev_b64 v[24:25], 1, v[24:25]
	v_lshl_add_u64 v[26:27], s[40:41], 0, v[24:25]
	v_lshl_add_u64 v[24:25], s[36:37], 0, v[24:25]
	global_load_dwordx2 v[28:29], v[26:27], off
	global_load_dwordx2 v[40:41], v[24:25], off
	s_waitcnt vmcnt(0)
	v_lshlrev_b32_e32 v30, 16, v28
	v_and_b32_e32 v31, 0xffff0000, v28
	v_lshlrev_b32_e32 v28, 16, v29
	v_and_b32_e32 v29, 0xffff0000, v29
	v_lshlrev_b32_e32 v46, 16, v40
	v_and_b32_e32 v47, 0xffff0000, v40
	v_lshlrev_b32_e32 v40, 16, v41
	v_and_b32_e32 v41, 0xffff0000, v41
	global_load_dwordx2 v[26:27], v[26:27], off offset:32
	v_pk_fma_f32 v[28:29], v[22:23], v[28:29], v[40:41]
	global_load_dwordx2 v[40:41], v[24:25], off offset:32
	v_pk_fma_f32 v[30:31], v[20:21], v[30:31], v[46:47]
	s_waitcnt vmcnt(1)
	v_lshlrev_b32_e32 v38, 16, v26
	v_and_b32_e32 v39, 0xffff0000, v26
	v_lshlrev_b32_e32 v26, 16, v27
	v_and_b32_e32 v27, 0xffff0000, v27
	s_waitcnt vmcnt(0)
	v_lshlrev_b32_e32 v46, 16, v40
	v_and_b32_e32 v47, 0xffff0000, v40
	v_lshlrev_b32_e32 v40, 16, v41
	v_and_b32_e32 v41, 0xffff0000, v41
	v_pk_fma_f32 v[26:27], v[18:19], v[26:27], v[40:41]
	v_pk_fma_f32 v[38:39], v[16:17], v[38:39], v[46:47]
	v_cvt_pk_bf16_f32 v30, v30, v31
	v_cvt_pk_bf16_f32 v31, v28, v29
	v_mov_b32_e32 v194, v30
	v_mov_b32_e32 v195, v31
	v_cvt_pk_bf16_f32 v28, v38, v39
	v_cvt_pk_bf16_f32 v29, v26, v27
	v_mov_b32_e32 v196, v28
	v_mov_b32_e32 v197, v29
	v_lshl_add_u64 v[198:199], v[200:201], 0, v[24:25]
	s_nop 0
	v_permlane16_swap_b32 v194, v196
	v_permlane16_swap_b32 v195, v197
	global_store_dwordx4 v[198:199], v[194:197], off

.LBB0_879:
	s_and_b64 vcc, exec, s[58:59]
	s_cbranch_vccz .LBB0_884
	s_cmp_gt_i32 s79, 22
	s_mov_b64 s[58:59], -1
	s_cbranch_scc0 .LBB0_882
	v_ashrrev_i32_e32 v121, 31, v120
	v_lshl_add_u64 v[24:25], v[34:35], 0, v[120:121]
	v_lshlrev_b64 v[24:25], 1, v[24:25]
	v_lshl_add_u64 v[26:27], s[34:35], 0, v[24:25]
	v_lshl_add_u64 v[24:25], s[36:37], 0, v[24:25]
	global_load_dwordx2 v[28:29], v[26:27], off
	global_load_dwordx2 v[40:41], v[24:25], off
	s_mov_b64 s[58:59], 0
	global_load_dwordx2 v[26:27], v[26:27], off offset:32
	s_waitcnt vmcnt(0)
	v_lshlrev_b32_e32 v30, 16, v28
	v_and_b32_e32 v31, 0xffff0000, v28
	v_lshlrev_b32_e32 v28, 16, v29
	v_and_b32_e32 v29, 0xffff0000, v29
	v_lshlrev_b32_e32 v46, 16, v40
	v_and_b32_e32 v47, 0xffff0000, v40
	v_lshlrev_b32_e32 v40, 16, v41
	v_and_b32_e32 v41, 0xffff0000, v41
	v_pk_fma_f32 v[28:29], v[22:23], v[28:29], v[40:41]
	global_load_dwordx2 v[40:41], v[24:25], off offset:32
	v_lshlrev_b32_e32 v38, 16, v26
	v_and_b32_e32 v39, 0xffff0000, v26
	v_lshlrev_b32_e32 v26, 16, v27
	v_and_b32_e32 v27, 0xffff0000, v27
	v_pk_fma_f32 v[30:31], v[20:21], v[30:31], v[46:47]
	s_waitcnt vmcnt(0)
	v_lshlrev_b32_e32 v46, 16, v40
	v_and_b32_e32 v47, 0xffff0000, v40
	v_lshlrev_b32_e32 v40, 16, v41
	v_and_b32_e32 v41, 0xffff0000, v41
	v_pk_fma_f32 v[26:27], v[18:19], v[26:27], v[40:41]
	v_pk_fma_f32 v[38:39], v[16:17], v[38:39], v[46:47]
	v_cvt_pk_bf16_f32 v30, v30, v31
	v_cvt_pk_bf16_f32 v31, v28, v29
	v_mov_b32_e32 v194, v30
	v_mov_b32_e32 v195, v31
	v_cvt_pk_bf16_f32 v28, v38, v39
	v_cvt_pk_bf16_f32 v29, v26, v27
	v_mov_b32_e32 v196, v28
	v_mov_b32_e32 v197, v29
	v_lshl_add_u64 v[198:199], v[200:201], 0, v[24:25]
	s_nop 0
	v_permlane16_swap_b32 v194, v196
	v_permlane16_swap_b32 v195, v197
	global_store_dwordx4 v[198:199], v[194:197], off
.LBB0_882:
	s_andn2_b64 vcc, exec, s[58:59]
	s_cbranch_vccnz .LBB0_884
	v_ashrrev_i32_e32 v121, 31, v120
	v_lshl_add_u64 v[24:25], v[34:35], 0, v[120:121]
	v_lshlrev_b64 v[24:25], 1, v[24:25]
	v_lshl_add_u64 v[26:27], s[38:39], 0, v[24:25]
	global_load_dwordx2 v[28:29], v[26:27], off
	s_nop 0
	global_load_dwordx2 v[26:27], v[26:27], off offset:32
	v_lshl_add_u64 v[24:25], s[36:37], 0, v[24:25]
	s_waitcnt vmcnt(0)
	v_lshlrev_b32_e32 v30, 16, v28
	v_and_b32_e32 v31, 0xffff0000, v28
	v_lshlrev_b32_e32 v28, 16, v29
	v_and_b32_e32 v29, 0xffff0000, v29
	v_pk_mul_f32 v[30:31], v[20:21], v[30:31]
	v_lshlrev_b32_e32 v34, 16, v26
	v_and_b32_e32 v35, 0xffff0000, v26
	v_lshlrev_b32_e32 v26, 16, v27
	v_and_b32_e32 v27, 0xffff0000, v27
	v_pk_mul_f32 v[28:29], v[22:23], v[28:29]
	v_cvt_pk_bf16_f32 v30, v30, v31
	v_pk_mul_f32 v[26:27], v[18:19], v[26:27]
	v_cvt_pk_bf16_f32 v31, v28, v29
	v_pk_mul_f32 v[34:35], v[16:17], v[34:35]
	v_cvt_pk_bf16_f32 v29, v26, v27
	s_nop 0
	v_cvt_pk_bf16_f32 v28, v34, v35
	v_mov_b32_e32 v194, v30
	v_mov_b32_e32 v195, v31
	v_mov_b32_e32 v196, v28
	v_mov_b32_e32 v197, v29
	v_lshl_add_u64 v[198:199], v[200:201], 0, v[24:25]
	s_nop 0
	v_permlane16_swap_b32 v194, v196
	v_permlane16_swap_b32 v195, v197
	global_store_dwordx4 v[198:199], v[194:197], off

.LBB0_892:
	s_ashr_i32 s33, s67, 2
	s_add_i32 s33, s33, 2
	v_mad_i64_i32 v[34:35], s[56:57], s33, v154, v[32:33]
	v_mov_b32_e32 v123, v153
	v_lshl_add_u64 v[34:35], v[34:35], 0, v[122:123]
	v_cvt_pk_bf16_f32 v30, v30, v31
	v_cvt_pk_bf16_f32 v31, v26, v27
	v_mov_b32_e32 v194, v30
	v_mov_b32_e32 v195, v31
	v_cvt_pk_bf16_f32 v26, v28, v29
	v_cvt_pk_bf16_f32 v27, v24, v25
	v_mov_b32_e32 v196, v26
	v_mov_b32_e32 v197, v27
	v_lshl_add_u64 v[198:199], v[200:201], 0, v[34:35]
	s_nop 0
	v_permlane16_swap_b32 v194, v196
	v_permlane16_swap_b32 v195, v197
	global_store_dwordx4 v[198:199], v[194:197], off

.LBB0_905:
	s_or_b64 exec, exec, s[56:57]
	s_add_i32 s33, s33, 1
	v_mad_i64_i32 v[34:35], s[10:11], s33, v154, v[32:33]
	v_mov_b32_e32 v123, v153
	v_lshl_add_u64 v[34:35], v[34:35], 0, v[122:123]
	v_cvt_pk_bf16_f32 v26, v26, v27
	v_cvt_pk_bf16_f32 v27, v24, v25
	v_mov_b32_e32 v194, v26
	v_mov_b32_e32 v195, v27
	v_cvt_pk_bf16_f32 v24, v30, v31
	v_cvt_pk_bf16_f32 v25, v28, v29
	v_mov_b32_e32 v196, v24
	v_mov_b32_e32 v197, v25
	v_lshl_add_u64 v[198:199], v[200:201], 0, v[34:35]
	s_nop 0
	v_permlane16_swap_b32 v194, v196
	v_permlane16_swap_b32 v195, v197
	global_store_dwordx4 v[198:199], v[194:197], off

.LBB0_917:
	s_andn2_b64 vcc, exec, s[56:57]
	s_cbranch_vccnz .LBB0_919
	s_ashr_i32 s2, s67, 2
	s_add_i32 s2, s2, 1
	v_mad_i64_i32 v[24:25], s[2:3], s2, v154, v[32:33]
	v_mov_b32_e32 v123, v153
	v_lshl_add_u64 v[24:25], v[24:25], 0, v[122:123]
	v_cvt_pk_f16_f32 v23, v22, v23
	v_cvt_pk_f16_f32 v22, v20, v21
	v_cvt_pk_f16_f32 v19, v18, v19
	v_cvt_pk_f16_f32 v18, v16, v17
	v_mov_b32_e32 v194, v22
	v_mov_b32_e32 v195, v23
	v_mov_b32_e32 v196, v18
	v_mov_b32_e32 v197, v19
	v_lshl_add_u64 v[198:199], v[200:201], 0, v[24:25]
	s_nop 0
	v_permlane16_swap_b32 v194, v196
	v_permlane16_swap_b32 v195, v197
	global_store_dwordx4 v[198:199], v[194:197], off
.LBB0_919:
	v_or_b32_e32 v28, s63, v177
	v_ashrrev_i32_e32 v29, 31, v28
	v_lshlrev_b64 v[16:17], 13, v[28:29]
	v_add_u32_e32 v26, 0xffffc000, v28
	v_mov_b32_e32 v27, v153
	v_lshl_add_u64 v[24:25], s[52:53], 0, v[16:17]
	v_cmp_gt_i32_e64 s[10:11], s92, v28
	v_cmp_lt_i32_e64 s[8:9], s80, v28
	v_lshlrev_b64 v[22:23], 10, v[26:27]
	v_lshlrev_b64 v[18:19], 10, v[28:29]
	s_mov_b64 s[56:57], -1
	s_mov_b64 s[52:53], 0
	s_cmp_lt_i32 s79, 22
	s_mov_b64 s[2:3], 0
	s_cbranch_scc1 .LBB0_944
	s_cmp_gt_i32 s79, 23
	s_cbranch_scc0 .LBB0_938
	s_cmp_gt_i32 s79, 24
	s_cbranch_scc0 .LBB0_935
	s_cmp_gt_i32 s79, 25
	s_cbranch_scc0 .LBB0_926
	s_cmp_eq_u32 s79, 26
	s_mov_b64 s[2:3], -1
	s_cbranch_scc0 .LBB0_925
	v_max_f32_e32 v16, v12, v12
	v_max_f32_e32 v17, v8, v8
	v_max_f32_e32 v16, 0, v16
	v_max_f32_e32 v17, 0, v17
	v_mul_f32_e32 v20, v16, v16
	v_mul_f32_e32 v30, v17, v17
	v_max_f32_e32 v16, v13, v13
	v_max_f32_e32 v17, v9, v9
	v_max_f32_e32 v16, 0, v16
	v_max_f32_e32 v17, 0, v17
	v_mul_f32_e32 v21, v16, v16
	v_mul_f32_e32 v31, v17, v17
	v_max_f32_e32 v16, v14, v14
	v_max_f32_e32 v17, v10, v10
	v_max_f32_e32 v16, 0, v16
	v_max_f32_e32 v17, 0, v17
	v_mul_f32_e32 v32, v16, v16
	v_mul_f32_e32 v33, v17, v17
	v_max_f32_e32 v16, v15, v15
	v_max_f32_e32 v17, v11, v11
	v_max_f32_e32 v16, 0, v16
	v_max_f32_e32 v17, 0, v17
	v_ashrrev_i32_e32 v137, 31, v136
	v_mul_f32_e32 v34, v16, v16
	v_mul_f32_e32 v35, v17, v17
	v_lshl_add_u64 v[16:17], v[136:137], 1, v[24:25]
	v_cvt_pk_bf16_f32 v20, v20, v21
	v_cvt_pk_bf16_f32 v21, v32, v34
	s_mov_b64 s[2:3], 0
	v_mov_b32_e32 v194, v20
	v_mov_b32_e32 v195, v21
	v_cvt_pk_bf16_f32 v20, v30, v31
	v_cvt_pk_bf16_f32 v21, v33, v35
	v_mov_b32_e32 v196, v20
	v_mov_b32_e32 v197, v21
	v_lshl_add_u64 v[198:199], v[200:201], 0, v[16:17]
	s_nop 0
	v_permlane16_swap_b32 v194, v196
	v_permlane16_swap_b32 v195, v197
	global_store_dwordx4 v[198:199], v[194:197], off

.LBB0_935:
	s_and_b64 vcc, exec, s[56:57]
	s_cbranch_vccz .LBB0_937
	v_ashrrev_i32_e32 v137, 31, v136
	v_lshl_add_u64 v[16:17], v[18:19], 0, v[136:137]
	v_lshlrev_b64 v[16:17], 1, v[16:17]
	v_lshl_add_u64 v[20:21], s[40:41], 0, v[16:17]
	v_lshl_add_u64 v[16:17], s[36:37], 0, v[16:17]
	global_load_dwordx2 v[30:31], v[20:21], off
	global_load_dwordx2 v[36:37], v[16:17], off
	s_waitcnt vmcnt(0)
	v_lshlrev_b32_e32 v32, 16, v30
	v_and_b32_e32 v33, 0xffff0000, v30
	v_lshlrev_b32_e32 v30, 16, v31
	v_and_b32_e32 v31, 0xffff0000, v31
	v_lshlrev_b32_e32 v38, 16, v36
	v_and_b32_e32 v39, 0xffff0000, v36
	v_lshlrev_b32_e32 v36, 16, v37
	v_and_b32_e32 v37, 0xffff0000, v37
	global_load_dwordx2 v[20:21], v[20:21], off offset:32
	v_pk_fma_f32 v[30:31], v[14:15], v[30:31], v[36:37]
	global_load_dwordx2 v[36:37], v[16:17], off offset:32
	v_pk_fma_f32 v[32:33], v[12:13], v[32:33], v[38:39]
	s_waitcnt vmcnt(1)
	v_lshlrev_b32_e32 v34, 16, v20
	v_and_b32_e32 v35, 0xffff0000, v20
	v_lshlrev_b32_e32 v20, 16, v21
	v_and_b32_e32 v21, 0xffff0000, v21
	s_waitcnt vmcnt(0)
	v_lshlrev_b32_e32 v38, 16, v36
	v_and_b32_e32 v39, 0xffff0000, v36
	v_lshlrev_b32_e32 v36, 16, v37
	v_and_b32_e32 v37, 0xffff0000, v37
	v_pk_fma_f32 v[20:21], v[10:11], v[20:21], v[36:37]
	v_pk_fma_f32 v[34:35], v[8:9], v[34:35], v[38:39]
	v_cvt_pk_bf16_f32 v32, v32, v33
	v_cvt_pk_bf16_f32 v33, v30, v31
	v_mov_b32_e32 v194, v32
	v_mov_b32_e32 v195, v33
	v_cvt_pk_bf16_f32 v30, v34, v35
	v_cvt_pk_bf16_f32 v31, v20, v21
	v_mov_b32_e32 v196, v30
	v_mov_b32_e32 v197, v31
	v_lshl_add_u64 v[198:199], v[200:201], 0, v[16:17]
	s_nop 0
	v_permlane16_swap_b32 v194, v196
	v_permlane16_swap_b32 v195, v197
	global_store_dwordx4 v[198:199], v[194:197], off

.LBB0_938:
	s_and_b64 vcc, exec, s[56:57]
	s_cbranch_vccz .LBB0_943
	s_cmp_gt_i32 s79, 22
	s_mov_b64 s[56:57], -1
	s_cbranch_scc0 .LBB0_941
	v_ashrrev_i32_e32 v137, 31, v136
	v_lshl_add_u64 v[16:17], v[18:19], 0, v[136:137]
	v_lshlrev_b64 v[16:17], 1, v[16:17]
	v_lshl_add_u64 v[20:21], s[34:35], 0, v[16:17]
	v_lshl_add_u64 v[16:17], s[36:37], 0, v[16:17]
	global_load_dwordx2 v[30:31], v[20:21], off
	global_load_dwordx2 v[36:37], v[16:17], off
	s_mov_b64 s[56:57], 0
	global_load_dwordx2 v[20:21], v[20:21], off offset:32
	s_waitcnt vmcnt(0)
	v_lshlrev_b32_e32 v32, 16, v30
	v_and_b32_e32 v33, 0xffff0000, v30
	v_lshlrev_b32_e32 v30, 16, v31
	v_and_b32_e32 v31, 0xffff0000, v31
	v_lshlrev_b32_e32 v38, 16, v36
	v_and_b32_e32 v39, 0xffff0000, v36
	v_lshlrev_b32_e32 v36, 16, v37
	v_and_b32_e32 v37, 0xffff0000, v37
	v_pk_fma_f32 v[30:31], v[14:15], v[30:31], v[36:37]
	global_load_dwordx2 v[36:37], v[16:17], off offset:32
	v_lshlrev_b32_e32 v34, 16, v20
	v_and_b32_e32 v35, 0xffff0000, v20
	v_lshlrev_b32_e32 v20, 16, v21
	v_and_b32_e32 v21, 0xffff0000, v21
	v_pk_fma_f32 v[32:33], v[12:13], v[32:33], v[38:39]
	s_waitcnt vmcnt(0)
	v_lshlrev_b32_e32 v38, 16, v36
	v_and_b32_e32 v39, 0xffff0000, v36
	v_lshlrev_b32_e32 v36, 16, v37
	v_and_b32_e32 v37, 0xffff0000, v37
	v_pk_fma_f32 v[20:21], v[10:11], v[20:21], v[36:37]
	v_pk_fma_f32 v[34:35], v[8:9], v[34:35], v[38:39]
	v_cvt_pk_bf16_f32 v32, v32, v33
	v_cvt_pk_bf16_f32 v33, v30, v31
	v_mov_b32_e32 v194, v32
	v_mov_b32_e32 v195, v33
	v_cvt_pk_bf16_f32 v30, v34, v35
	v_cvt_pk_bf16_f32 v31, v20, v21
	v_mov_b32_e32 v196, v30
	v_mov_b32_e32 v197, v31
	v_lshl_add_u64 v[198:199], v[200:201], 0, v[16:17]
	s_nop 0
	v_permlane16_swap_b32 v194, v196
	v_permlane16_swap_b32 v195, v197
	global_store_dwordx4 v[198:199], v[194:197], off
.LBB0_941:
	s_andn2_b64 vcc, exec, s[56:57]
	s_cbranch_vccnz .LBB0_943
	v_ashrrev_i32_e32 v137, 31, v136
	v_lshl_add_u64 v[16:17], v[18:19], 0, v[136:137]
	v_lshlrev_b64 v[16:17], 1, v[16:17]
	v_lshl_add_u64 v[20:21], s[38:39], 0, v[16:17]
	global_load_dwordx2 v[30:31], v[20:21], off
	s_nop 0
	global_load_dwordx2 v[20:21], v[20:21], off offset:32
	v_lshl_add_u64 v[16:17], s[36:37], 0, v[16:17]
	s_waitcnt vmcnt(0)
	v_lshlrev_b32_e32 v32, 16, v30
	v_and_b32_e32 v33, 0xffff0000, v30
	v_lshlrev_b32_e32 v30, 16, v31
	v_and_b32_e32 v31, 0xffff0000, v31
	v_pk_mul_f32 v[32:33], v[12:13], v[32:33]
	v_lshlrev_b32_e32 v34, 16, v20
	v_and_b32_e32 v35, 0xffff0000, v20
	v_lshlrev_b32_e32 v20, 16, v21
	v_and_b32_e32 v21, 0xffff0000, v21
	v_pk_mul_f32 v[30:31], v[14:15], v[30:31]
	v_cvt_pk_bf16_f32 v32, v32, v33
	v_pk_mul_f32 v[20:21], v[10:11], v[20:21]
	v_cvt_pk_bf16_f32 v33, v30, v31
	v_pk_mul_f32 v[34:35], v[8:9], v[34:35]
	v_cvt_pk_bf16_f32 v31, v20, v21
	s_nop 0
	v_cvt_pk_bf16_f32 v30, v34, v35
	v_mov_b32_e32 v194, v32
	v_mov_b32_e32 v195, v33
	v_mov_b32_e32 v196, v30
	v_mov_b32_e32 v197, v31
	v_lshl_add_u64 v[198:199], v[200:201], 0, v[16:17]
	s_nop 0
	v_permlane16_swap_b32 v194, v196
	v_permlane16_swap_b32 v195, v197
	global_store_dwordx4 v[198:199], v[194:197], off

.LBB0_951:
	s_ashr_i32 s33, s67, 2
	s_add_i32 s33, s33, 2
	v_mad_i64_i32 v[40:41], s[48:49], s33, v154, v[16:17]
	v_mov_b32_e32 v139, v153
	v_lshl_add_u64 v[40:41], v[40:41], 0, v[138:139]
	v_cvt_pk_bf16_f32 v36, v36, v37
	v_cvt_pk_bf16_f32 v37, v32, v33
	v_mov_b32_e32 v194, v36
	v_mov_b32_e32 v195, v37
	v_cvt_pk_bf16_f32 v32, v34, v35
	v_cvt_pk_bf16_f32 v33, v30, v31
	v_mov_b32_e32 v196, v32
	v_mov_b32_e32 v197, v33
	v_lshl_add_u64 v[198:199], v[200:201], 0, v[40:41]
	s_nop 0
	v_permlane16_swap_b32 v194, v196
	v_permlane16_swap_b32 v195, v197
	global_store_dwordx4 v[198:199], v[194:197], off

.LBB0_964:
	s_or_b64 exec, exec, s[48:49]
	s_add_i32 s33, s33, 1
	v_mad_i64_i32 v[40:41], s[48:49], s33, v154, v[16:17]
	v_mov_b32_e32 v139, v153
	v_lshl_add_u64 v[40:41], v[40:41], 0, v[138:139]
	v_cvt_pk_bf16_f32 v32, v32, v33
	v_cvt_pk_bf16_f32 v33, v30, v31
	v_mov_b32_e32 v194, v32
	v_mov_b32_e32 v195, v33
	v_cvt_pk_bf16_f32 v30, v36, v37
	v_cvt_pk_bf16_f32 v31, v34, v35
	v_mov_b32_e32 v196, v30
	v_mov_b32_e32 v197, v31
	v_lshl_add_u64 v[198:199], v[200:201], 0, v[40:41]
	s_nop 0
	v_permlane16_swap_b32 v194, v196
	v_permlane16_swap_b32 v195, v197
	global_store_dwordx4 v[198:199], v[194:197], off

.LBB0_976:
	s_andn2_b64 vcc, exec, s[52:53]
	s_cbranch_vccnz .LBB0_978
	s_ashr_i32 s2, s67, 2
	s_add_i32 s2, s2, 1
	v_mad_i64_i32 v[30:31], s[2:3], s2, v154, v[16:17]
	v_mov_b32_e32 v139, v153
	v_lshl_add_u64 v[30:31], v[30:31], 0, v[138:139]
	v_cvt_pk_f16_f32 v15, v14, v15
	v_cvt_pk_f16_f32 v14, v12, v13
	v_cvt_pk_f16_f32 v11, v10, v11
	v_cvt_pk_f16_f32 v10, v8, v9
	v_mov_b32_e32 v194, v14
	v_mov_b32_e32 v195, v15
	v_mov_b32_e32 v196, v10
	v_mov_b32_e32 v197, v11
	v_lshl_add_u64 v[198:199], v[200:201], 0, v[30:31]
	s_nop 0
	v_permlane16_swap_b32 v194, v196
	v_permlane16_swap_b32 v195, v197
	global_store_dwordx4 v[198:199], v[194:197], off
.LBB0_978:
	s_mov_b64 s[50:51], -1
	s_mov_b64 s[48:49], 0
	s_cmp_lt_i32 s79, 22
	s_mov_b64 s[2:3], 0
	s_cbranch_scc1 .LBB0_1031
	s_cmp_gt_i32 s79, 23
	s_cbranch_scc0 .LBB0_1022
	s_cmp_gt_i32 s79, 24
	s_cbranch_scc0 .LBB0_1023
	s_cmp_gt_i32 s79, 25
	s_cbranch_scc0 .LBB0_985
	s_cmp_eq_u32 s79, 26
	s_mov_b64 s[2:3], -1
	s_cbranch_scc0 .LBB0_984
	v_max_f32_e32 v8, v4, v4
	v_max_f32_e32 v9, v0, v0
	v_max_f32_e32 v8, 0, v8
	v_max_f32_e32 v9, 0, v9
	v_mul_f32_e32 v10, v8, v8
	v_mul_f32_e32 v12, v9, v9
	v_max_f32_e32 v8, v5, v5
	v_max_f32_e32 v9, v1, v1
	v_max_f32_e32 v8, 0, v8
	v_max_f32_e32 v9, 0, v9
	v_mul_f32_e32 v11, v8, v8
	v_mul_f32_e32 v13, v9, v9
	v_max_f32_e32 v8, v6, v6
	v_max_f32_e32 v9, v2, v2
	v_max_f32_e32 v8, 0, v8
	v_max_f32_e32 v9, 0, v9
	v_mul_f32_e32 v14, v8, v8
	v_mul_f32_e32 v15, v9, v9
	v_max_f32_e32 v8, v7, v7
	v_max_f32_e32 v9, v3, v3
	v_max_f32_e32 v8, 0, v8
	v_max_f32_e32 v9, 0, v9
	v_ashrrev_i32_e32 v137, 31, v136
	v_mul_f32_e32 v30, v8, v8
	v_mul_f32_e32 v31, v9, v9
	v_lshl_add_u64 v[8:9], v[136:137], 1, v[24:25]
	v_cvt_pk_bf16_f32 v10, v10, v11
	v_cvt_pk_bf16_f32 v11, v14, v30
	s_mov_b64 s[2:3], 0
	v_mov_b32_e32 v194, v10
	v_mov_b32_e32 v195, v11
	v_cvt_pk_bf16_f32 v10, v12, v13
	v_cvt_pk_bf16_f32 v11, v15, v31
	v_mov_b32_e32 v196, v10
	v_mov_b32_e32 v197, v11
	v_lshl_add_u64 v[198:199], v[200:201], 0, v[8:9]
	s_nop 0
	v_permlane16_swap_b32 v194, v196
	v_permlane16_swap_b32 v195, v197
	global_store_dwordx4 v[198:199], v[194:197], off offset:256

.LBB0_1023:
	s_cbranch_execz .LBB0_1025
	v_ashrrev_i32_e32 v121, 31, v120
	v_lshl_add_u64 v[8:9], v[18:19], 0, v[120:121]
	v_lshlrev_b64 v[8:9], 1, v[8:9]
	v_lshl_add_u64 v[10:11], s[40:41], 0, v[8:9]
	v_lshl_add_u64 v[8:9], s[36:37], 0, v[8:9]
	global_load_dwordx2 v[12:13], v[10:11], off
	global_load_dwordx2 v[24:25], v[8:9], off
	s_waitcnt vmcnt(0)
	v_lshlrev_b32_e32 v14, 16, v12
	v_and_b32_e32 v15, 0xffff0000, v12
	v_lshlrev_b32_e32 v12, 16, v13
	v_and_b32_e32 v13, 0xffff0000, v13
	v_lshlrev_b32_e32 v30, 16, v24
	v_and_b32_e32 v31, 0xffff0000, v24
	v_lshlrev_b32_e32 v24, 16, v25
	v_and_b32_e32 v25, 0xffff0000, v25
	global_load_dwordx2 v[10:11], v[10:11], off offset:32
	v_pk_fma_f32 v[12:13], v[6:7], v[12:13], v[24:25]
	global_load_dwordx2 v[24:25], v[8:9], off offset:32
	v_pk_fma_f32 v[14:15], v[4:5], v[14:15], v[30:31]
	s_waitcnt vmcnt(1)
	v_lshlrev_b32_e32 v22, 16, v10
	v_and_b32_e32 v23, 0xffff0000, v10
	v_lshlrev_b32_e32 v10, 16, v11
	v_and_b32_e32 v11, 0xffff0000, v11
	s_waitcnt vmcnt(0)
	v_lshlrev_b32_e32 v30, 16, v24
	v_and_b32_e32 v31, 0xffff0000, v24
	v_lshlrev_b32_e32 v24, 16, v25
	v_and_b32_e32 v25, 0xffff0000, v25
	v_pk_fma_f32 v[10:11], v[2:3], v[10:11], v[24:25]
	v_pk_fma_f32 v[22:23], v[0:1], v[22:23], v[30:31]
	v_cvt_pk_bf16_f32 v14, v14, v15
	v_cvt_pk_bf16_f32 v15, v12, v13
	v_mov_b32_e32 v194, v14
	v_mov_b32_e32 v195, v15
	v_cvt_pk_bf16_f32 v12, v22, v23
	v_cvt_pk_bf16_f32 v13, v10, v11
	v_mov_b32_e32 v196, v12
	v_mov_b32_e32 v197, v13
	v_lshl_add_u64 v[198:199], v[200:201], 0, v[8:9]
	s_nop 0
	v_permlane16_swap_b32 v194, v196
	v_permlane16_swap_b32 v195, v197
	global_store_dwordx4 v[198:199], v[194:197], off

.LBB0_1026:
	s_cmp_gt_i32 s79, 22
	s_mov_b64 s[40:41], -1
	s_cbranch_scc0 .LBB0_1028
	v_ashrrev_i32_e32 v121, 31, v120
	v_lshl_add_u64 v[8:9], v[18:19], 0, v[120:121]
	v_lshlrev_b64 v[8:9], 1, v[8:9]
	v_lshl_add_u64 v[10:11], s[34:35], 0, v[8:9]
	v_lshl_add_u64 v[8:9], s[36:37], 0, v[8:9]
	global_load_dwordx2 v[12:13], v[10:11], off
	global_load_dwordx2 v[24:25], v[8:9], off
	s_mov_b64 s[40:41], 0
	global_load_dwordx2 v[10:11], v[10:11], off offset:32
	s_waitcnt vmcnt(0)
	v_lshlrev_b32_e32 v14, 16, v12
	v_and_b32_e32 v15, 0xffff0000, v12
	v_lshlrev_b32_e32 v12, 16, v13
	v_and_b32_e32 v13, 0xffff0000, v13
	v_lshlrev_b32_e32 v30, 16, v24
	v_and_b32_e32 v31, 0xffff0000, v24
	v_lshlrev_b32_e32 v24, 16, v25
	v_and_b32_e32 v25, 0xffff0000, v25
	v_pk_fma_f32 v[12:13], v[6:7], v[12:13], v[24:25]
	global_load_dwordx2 v[24:25], v[8:9], off offset:32
	v_lshlrev_b32_e32 v22, 16, v10
	v_and_b32_e32 v23, 0xffff0000, v10
	v_lshlrev_b32_e32 v10, 16, v11
	v_and_b32_e32 v11, 0xffff0000, v11
	v_pk_fma_f32 v[14:15], v[4:5], v[14:15], v[30:31]
	s_waitcnt vmcnt(0)
	v_lshlrev_b32_e32 v30, 16, v24
	v_and_b32_e32 v31, 0xffff0000, v24
	v_lshlrev_b32_e32 v24, 16, v25
	v_and_b32_e32 v25, 0xffff0000, v25
	v_pk_fma_f32 v[10:11], v[2:3], v[10:11], v[24:25]
	v_pk_fma_f32 v[22:23], v[0:1], v[22:23], v[30:31]
	v_cvt_pk_bf16_f32 v14, v14, v15
	v_cvt_pk_bf16_f32 v15, v12, v13
	v_mov_b32_e32 v194, v14
	v_mov_b32_e32 v195, v15
	v_cvt_pk_bf16_f32 v12, v22, v23
	v_cvt_pk_bf16_f32 v13, v10, v11
	v_mov_b32_e32 v196, v12
	v_mov_b32_e32 v197, v13
	v_lshl_add_u64 v[198:199], v[200:201], 0, v[8:9]
	s_nop 0
	v_permlane16_swap_b32 v194, v196
	v_permlane16_swap_b32 v195, v197
	global_store_dwordx4 v[198:199], v[194:197], off
.LBB0_1028:
	s_andn2_b64 vcc, exec, s[40:41]
	s_cbranch_vccnz .LBB0_1030
	v_ashrrev_i32_e32 v121, 31, v120
	v_lshl_add_u64 v[8:9], v[18:19], 0, v[120:121]
	v_lshlrev_b64 v[8:9], 1, v[8:9]
	v_lshl_add_u64 v[10:11], s[38:39], 0, v[8:9]
	global_load_dwordx2 v[12:13], v[10:11], off
	s_nop 0
	global_load_dwordx2 v[10:11], v[10:11], off offset:32
	v_lshl_add_u64 v[8:9], s[36:37], 0, v[8:9]
	s_waitcnt vmcnt(0)
	v_lshlrev_b32_e32 v14, 16, v12
	v_and_b32_e32 v15, 0xffff0000, v12
	v_lshlrev_b32_e32 v12, 16, v13
	v_and_b32_e32 v13, 0xffff0000, v13
	v_pk_mul_f32 v[14:15], v[4:5], v[14:15]
	v_lshlrev_b32_e32 v18, 16, v10
	v_and_b32_e32 v19, 0xffff0000, v10
	v_lshlrev_b32_e32 v10, 16, v11
	v_and_b32_e32 v11, 0xffff0000, v11
	v_pk_mul_f32 v[12:13], v[6:7], v[12:13]
	v_cvt_pk_bf16_f32 v14, v14, v15
	v_pk_mul_f32 v[10:11], v[2:3], v[10:11]
	v_cvt_pk_bf16_f32 v15, v12, v13
	v_pk_mul_f32 v[18:19], v[0:1], v[18:19]
	v_cvt_pk_bf16_f32 v13, v10, v11
	s_nop 0
	v_cvt_pk_bf16_f32 v12, v18, v19
	v_mov_b32_e32 v194, v14
	v_mov_b32_e32 v195, v15
	v_mov_b32_e32 v196, v12
	v_mov_b32_e32 v197, v13
	v_lshl_add_u64 v[198:199], v[200:201], 0, v[8:9]
	s_nop 0
	v_permlane16_swap_b32 v194, v196
	v_permlane16_swap_b32 v195, v197
	global_store_dwordx4 v[198:199], v[194:197], off

.LBB0_1038:
	s_ashr_i32 s27, s67, 2
	s_add_i32 s27, s27, 2
	v_mad_i64_i32 v[18:19], s[36:37], s27, v154, v[16:17]
	v_mov_b32_e32 v123, v153
	v_lshl_add_u64 v[18:19], v[18:19], 0, v[122:123]
	v_cvt_pk_bf16_f32 v14, v14, v15
	v_cvt_pk_bf16_f32 v15, v10, v11
	v_mov_b32_e32 v194, v14
	v_mov_b32_e32 v195, v15
	v_cvt_pk_bf16_f32 v10, v12, v13
	v_cvt_pk_bf16_f32 v11, v8, v9
	v_mov_b32_e32 v196, v10
	v_mov_b32_e32 v197, v11
	v_lshl_add_u64 v[198:199], v[200:201], 0, v[18:19]
	s_nop 0
	v_permlane16_swap_b32 v194, v196
	v_permlane16_swap_b32 v195, v197
	global_store_dwordx4 v[198:199], v[194:197], off

.LBB0_1051:
	s_or_b64 exec, exec, s[34:35]
	s_add_i32 s27, s27, 1
	v_mad_i64_i32 v[18:19], s[10:11], s27, v154, v[16:17]
	v_mov_b32_e32 v123, v153
	v_lshl_add_u64 v[18:19], v[18:19], 0, v[122:123]
	v_cvt_pk_bf16_f32 v10, v10, v11
	v_cvt_pk_bf16_f32 v11, v8, v9
	v_mov_b32_e32 v194, v10
	v_mov_b32_e32 v195, v11
	v_cvt_pk_bf16_f32 v8, v14, v15
	v_cvt_pk_bf16_f32 v9, v12, v13
	v_mov_b32_e32 v196, v8
	v_mov_b32_e32 v197, v9
	v_lshl_add_u64 v[198:199], v[200:201], 0, v[18:19]
	s_nop 0
	v_permlane16_swap_b32 v194, v196
	v_permlane16_swap_b32 v195, v197
	global_store_dwordx4 v[198:199], v[194:197], off

.LBB0_1063:
	s_andn2_b64 vcc, exec, s[48:49]
	s_cbranch_vccnz .LBB0_1065
	s_ashr_i32 s2, s67, 2
	s_add_i32 s2, s2, 1
	v_mad_i64_i32 v[8:9], s[2:3], s2, v154, v[16:17]
	v_mov_b32_e32 v123, v153
	v_lshl_add_u64 v[8:9], v[8:9], 0, v[122:123]
	v_cvt_pk_f16_f32 v7, v6, v7
	v_cvt_pk_f16_f32 v6, v4, v5
	v_cvt_pk_f16_f32 v3, v2, v3
	v_cvt_pk_f16_f32 v2, v0, v1
	v_mov_b32_e32 v194, v6
	v_mov_b32_e32 v195, v7
	v_mov_b32_e32 v196, v2
	v_mov_b32_e32 v197, v3
	v_lshl_add_u64 v[198:199], v[200:201], 0, v[8:9]
	s_nop 0
	v_permlane16_swap_b32 v194, v196
	v_permlane16_swap_b32 v195, v197
	global_store_dwordx4 v[198:199], v[194:197], off
